# HGRN prep: hoist all 96 token loads (software pipelined 48 deep) with re-derived vmcnt; chain DMA moved to idle waves 4-7; early GEMM barriers
# speedup vs baseline: 1.0072x; 1.0055x over previous
; __device__ __forceinline__ void hgrn_prep_item(const bf16_t* Z, const float* lbl, unsigned char* REC, int cidx, int h, LAS unsigned char* wl, int lane) {
;     ...
;     for (int e = 0; e < 2; ++e) { const float l0 = lbl[h * 128 + k0 + e], l1 = lbl[1024 + h * 128 + k0 + e]; lb[e] = __builtin_amdgcn_rcpf(1.f + __expf(l1 - l0)); omlb[e] = 1.f - lb[e]; }
;     float cv[32][2]; unsigned omp[32], qraw[32], itp[2][16];
;     const bf16_t* zr = Z + (size_t)m0 * DIN + h * 128 + k0;
; #pragma unroll
;     for (int t = 0; t < 32; ++t) {
;         const unsigned ff = *(const unsigned*)(zr + (size_t)t * DIN + ZHF), ii = *(const unsigned*)(zr + (size_t)t * DIN + ZHI);
;         qraw[t] = *(const unsigned*)(zr + (size_t)t * DIN + ZHQ); float omv[2];
.LBB0_434:
	v_mov_b32_e32 v217, v128
	v_mov_b32_e32 v1, v33
	v_lshlrev_b32_e32 v0, 1, v217
	v_or_b32_e32 v32, s2, v0
	v_or_b32_e32 v0, s3, v0
	s_waitcnt lgkmcnt(0)
	v_lshl_add_u64 v[2:3], v[32:33], 2, s[12:13]
	v_lshl_add_u64 v[0:1], v[0:1], 2, s[12:13]
	global_load_dwordx2 v[2:3], v[2:3], off
	s_mul_i32 s6, s14, 0x2c00
	global_load_dwordx2 v[0:1], v[0:1], off
	s_mul_hi_i32 s7, s14, 0x2c00
	s_add_u32 s6, s4, s6
	s_addc_u32 s7, s5, s7
	v_lshlrev_b32_e32 v32, 2, v217
	v_lshl_add_u64 v[36:37], s[6:7], 0, v[32:33]
	s_mov_b64 s[100:101], s[6:7]
	s_waitcnt vmcnt(8)
	v_add_u32_e32 v4, 0x1400, v32
	global_load_dword v4, v4, s[100:101]
	v_add_u32_e32 v122, 0xc00, v32
	global_load_dword v122, v122, s[100:101]
	v_add_u32_e32 v18, 0x1c00, v32
	global_load_dword v18, v18, s[100:101]
	v_add_u32_e32 v6, 0x4800, v32
	global_load_dword v6, v6, s[100:101]
	v_add_u32_e32 v130, 0x3800, v32
	global_load_dword v130, v130, s[100:101]
	v_add_u32_e32 v22, 0x4000, v32
	global_load_dword v22, v22, s[100:101]
	v_add_u32_e32 v24, 0x7400, v32
	global_load_dword v24, v24, s[100:101]
	v_add_u32_e32 v140, 0x6400, v32
	global_load_dword v140, v140, s[100:101]
	v_add_u32_e32 v26, 0x6c00, v32
	global_load_dword v26, v26, s[100:101]
	v_add_u32_e32 v28, 0xa000, v32
	global_load_dword v28, v28, s[100:101]
	v_add_u32_e32 v146, 0x9000, v32
	global_load_dword v146, v146, s[100:101]
	v_add_u32_e32 v30, 0x9800, v32
	global_load_dword v30, v30, s[100:101]
	v_add_u32_e32 v8, 0xcc00, v32
	global_load_dword v8, v8, s[100:101]
	v_add_u32_e32 v156, 0xbc00, v32
	global_load_dword v156, v156, s[100:101]
	v_add_u32_e32 v42, 0xc400, v32
	global_load_dword v42, v42, s[100:101]
	v_add_u32_e32 v10, 0xf800, v32
	global_load_dword v10, v10, s[100:101]
	v_add_u32_e32 v162, 0xe800, v32
	global_load_dword v162, v162, s[100:101]
	v_add_u32_e32 v46, 0xf000, v32
	global_load_dword v46, v46, s[100:101]
	v_add_u32_e32 v53, 0x12400, v32
	global_load_dword v53, v53, s[100:101]
	v_add_u32_e32 v164, 0x11400, v32
	global_load_dword v164, v164, s[100:101]
	v_add_u32_e32 v50, 0x11c00, v32
	global_load_dword v50, v50, s[100:101]
	v_add_u32_e32 v52, 0x15000, v32
	global_load_dword v52, v52, s[100:101]
	v_add_u32_e32 v166, 0x14000, v32
	global_load_dword v166, v166, s[100:101]
	v_add_u32_e32 v54, 0x14800, v32
	global_load_dword v54, v54, s[100:101]
	v_add_u32_e32 v12, 0x17c00, v32
	global_load_dword v12, v12, s[100:101]
	v_add_u32_e32 v168, 0x16c00, v32
	global_load_dword v168, v168, s[100:101]
	v_add_u32_e32 v62, 0x17400, v32
	global_load_dword v62, v62, s[100:101]
	v_add_u32_e32 v15, 0x1a800, v32
	global_load_dword v15, v15, s[100:101]
	v_add_u32_e32 v170, 0x19800, v32
	global_load_dword v170, v170, s[100:101]
	v_add_u32_e32 v70, 0x1a000, v32
	global_load_dword v70, v70, s[100:101]
	v_add_u32_e32 v72, 0x1d400, v32
	global_load_dword v72, v72, s[100:101]
	v_add_u32_e32 v172, 0x1c400, v32
	global_load_dword v172, v172, s[100:101]
	v_add_u32_e32 v76, 0x1cc00, v32
	global_load_dword v76, v76, s[100:101]
	v_add_u32_e32 v80, 0x20000, v32
	global_load_dword v80, v80, s[100:101]
	v_add_u32_e32 v174, 0x1f000, v32
	global_load_dword v174, v174, s[100:101]
	v_add_u32_e32 v82, 0x1f800, v32
	global_load_dword v82, v82, s[100:101]
	v_add_u32_e32 v38, 0x22c00, v32
	global_load_dword v38, v38, s[100:101]
	v_add_u32_e32 v176, 0x21c00, v32
	global_load_dword v176, v176, s[100:101]
	v_add_u32_e32 v86, 0x22400, v32
	global_load_dword v86, v86, s[100:101]
	v_add_u32_e32 v56, 0x25800, v32
	global_load_dword v56, v56, s[100:101]
	v_add_u32_e32 v178, 0x24800, v32
	global_load_dword v178, v178, s[100:101]
	v_add_u32_e32 v78, 0x25000, v32
	global_load_dword v78, v78, s[100:101]
	v_add_u32_e32 v57, 0x28400, v32
	global_load_dword v57, v57, s[100:101]
	v_add_u32_e32 v180, 0x27400, v32
	global_load_dword v180, v180, s[100:101]
	v_add_u32_e32 v68, 0x27c00, v32
	global_load_dword v68, v68, s[100:101]
	v_add_u32_e32 v98, 0x2b000, v32
	global_load_dword v98, v98, s[100:101]
	v_add_u32_e32 v182, 0x2a000, v32
	global_load_dword v182, v182, s[100:101]
	v_add_u32_e32 v58, 0x2a800, v32
	global_load_dword v58, v58, s[100:101]
	v_add_u32_e32 v224, s1, v32
	v_add_u32_e32 v173, 0x2000, v224
	v_add_u32_e32 v225, 0x400, v224
	v_add_u32_e32 v226, 0x800, v224
	v_add_u32_e32 v227, 0xc00, v224
	v_add_u32_e32 v228, 0x1000, v224
	v_add_u32_e32 v229, 0x1400, v224
	v_add_u32_e32 v230, 0x1800, v224
	v_add_u32_e32 v231, 0x1c00, v224
	s_add_i32 s65, s65, s90
	s_add_i32 s14, s14, s15
	s_waitcnt vmcnt(48)
	v_sub_f32_e32 v0, v0, v2
	v_mul_f32_e32 v0, 0x3fb8aa3b, v0
	v_exp_f32_e32 v0, v0
	s_nop 0
	v_add_f32_e32 v0, 1.0, v0
	v_rcp_f32_e32 v34, v0
	v_sub_f32_e32 v0, v1, v3
	v_mul_f32_e32 v0, 0x3fb8aa3b, v0
	v_exp_f32_e32 v0, v0
	s_nop 0
	v_add_f32_e32 v0, 1.0, v0
	v_rcp_f32_e32 v35, v0
	v_add_co_u32_e32 v0, vcc, s33, v36
	s_nop 1
	v_addc_co_u32_e32 v1, vcc, 0, v37, vcc
	s_nop 0
	v_add_u32_e32 v195, 0x2d400, v32
	global_load_dword v195, v195, s[100:101]
	s_nop 0
	v_add_u32_e32 v126, 0x2cc00, v32
	global_load_dword v126, v126, s[100:101]
	s_movk_i32 s6, 0x4000
	s_nop 0
	v_add_u32_e32 v189, 0x2dc00, v32
	global_load_dword v189, v189, s[100:101]
	s_waitcnt vmcnt(50)
	v_and_b32_e32 v3, 0xffff0000, v4
	v_lshlrev_b32_e32 v2, 16, v4
	v_mul_f32_e32 v2, 0xbfb8aa3b, v2
	v_exp_f32_e32 v16, v2
	s_waitcnt vmcnt(48)
; __device__ __forceinline__ unsigned cvt_pk_bf16(float lo, float hi) { const f32x2_cv v = {lo, hi}; return __builtin_bit_cast(unsigned, __builtin_convertvector(v, bf16x2_cv)); }
; __device__ __forceinline__ float bf_lo(unsigned u) { return __uint_as_float(u << 16); }
; __device__ __forceinline__ float bf_hi(unsigned u) { return __uint_as_float(u & 0xffff0000u); }
; __device__ __forceinline__ void hgrn_prep_item(const bf16_t* Z, const float* lbl, unsigned char* REC, int cidx, int h, LAS unsigned char* wl, int lane) {
;     ...
;     for (int t = 0; t < 32; ++t) {
;         const unsigned ff = *(const unsigned*)(zr + (size_t)t * DIN + ZHF), ii = *(const unsigned*)(zr + (size_t)t * DIN + ZHI);
;         qraw[t] = *(const unsigned*)(zr + (size_t)t * DIN + ZHQ); float omv[2];
; #pragma unroll
;         for (int e = 0; e < 2; ++e) {
;             const float fl = e ? bf_hi(ff) : bf_lo(ff);
;             const float ex = __expf(-fl), sg = __builtin_amdgcn_rcpf(1.f + ex);
;             const float f = lb[e] + omlb[e] * sg;
;             omv[e] = omlb[e] * (ex * sg);
;             cum[e] += __logf(f); cv[t][e] = cum[e];
;         }
;         omp[t] = cvt_pk_bf16(omv[0], omv[1]);
;         if ((t & 1) == 0) { itp[0][t >> 1] = ii & 0xffffu; itp[1][t >> 1] = ii >> 16; }
;         else { itp[0][t >> 1] |= ii << 16; itp[1][t >> 1] |= ii & 0xffff0000u; }
	v_and_b32_e32 v4, 0xffff, v18
	v_lshrrev_b32_e32 v5, 16, v18
	v_add_co_u32_e32 v0, vcc, s6, v36
	v_add_f32_e32 v2, 1.0, v16
	v_rcp_f32_e32 v18, v2
	v_mul_f32_e32 v2, 0xbfb8aa3b, v3
	v_exp_f32_e32 v17, v2
	v_addc_co_u32_e32 v1, vcc, 0, v37, vcc
	s_movk_i32 s6, 0x3000
	v_add_f32_e32 v2, 1.0, v17
	v_rcp_f32_e32 v19, v2
	v_add_co_u32_e32 v2, vcc, s6, v36
	s_nop 0
	v_add_u32_e32 v186, 0x30800, v32
	global_load_dword v186, v186, s[100:101]
	s_nop 0
	v_addc_co_u32_e32 v3, vcc, 0, v37, vcc
	s_nop 0
	v_add_u32_e32 v133, 0x2f800, v32
	global_load_dword v133, v133, s[100:101]
	s_nop 0
	s_nop 0
	v_add_u32_e32 v187, 0x30000, v32
	global_load_dword v187, v187, s[100:101]
	s_movk_i32 s6, 0x7000
	v_add_co_u32_e32 v2, vcc, s6, v36
	s_movk_i32 s6, 0x6000
	s_nop 0
	v_addc_co_u32_e32 v3, vcc, 0, v37, vcc
	v_pk_mul_f32 v[16:17], v[16:17], v[18:19]
	v_lshlrev_b32_e32 v184, 16, v122
	v_and_b32_e32 v185, 0xffff0000, v122
	s_waitcnt vmcnt(50)
	v_lshl_or_b32 v4, v6, 16, v4
	s_waitcnt vmcnt(48)
	v_and_b32_e32 v1, 0xffff0000, v22
	v_lshlrev_b32_e32 v0, 16, v22
	v_mul_f32_e32 v0, 0xbfb8aa3b, v0
	v_exp_f32_e32 v20, v0
	s_nop 0
	v_add_f32_e32 v0, 1.0, v20
	v_rcp_f32_e32 v22, v0
	v_mul_f32_e32 v0, 0xbfb8aa3b, v1
	s_nop 0
	v_add_u32_e32 v192, 0x33400, v32
	global_load_dword v192, v192, s[100:101]
	v_add_co_u32_e32 v2, vcc, s6, v36
	v_exp_f32_e32 v21, v0
	s_nop 0
	v_addc_co_u32_e32 v3, vcc, 0, v37, vcc
	s_nop 0
	v_add_u32_e32 v136, 0x32400, v32
	global_load_dword v136, v136, s[100:101]
	s_nop 0
	s_nop 0
	v_add_u32_e32 v188, 0x32c00, v32
	global_load_dword v188, v188, s[100:101]
	s_mov_b32 s6, 0xa000
	v_add_f32_e32 v0, 1.0, v21
	v_rcp_f32_e32 v23, v0
	v_and_or_b32 v0, v6, s16, v5
	s_waitcnt vmcnt(50)
	v_and_b32_e32 v5, 0xffff, v24
	v_lshrrev_b32_e32 v1, 16, v24
	s_waitcnt vmcnt(48)
	v_and_b32_e32 v3, 0xffff0000, v26
	v_lshlrev_b32_e32 v2, 16, v26
	v_mul_f32_e32 v2, 0xbfb8aa3b, v2
	v_exp_f32_e32 v24, v2
	s_nop 0
	v_add_f32_e32 v2, 1.0, v24
	v_rcp_f32_e32 v26, v2
	v_mul_f32_e32 v2, 0xbfb8aa3b, v3
	v_exp_f32_e32 v25, v2
	s_nop 0
	v_add_f32_e32 v2, 1.0, v25
	v_rcp_f32_e32 v27, v2
	v_add_co_u32_e32 v2, vcc, s6, v36
	s_mov_b32 s6, 0x9000
	s_nop 0
	v_addc_co_u32_e32 v3, vcc, 0, v37, vcc
	s_nop 0
	v_add_u32_e32 v191, 0x36000, v32
	global_load_dword v191, v191, s[100:101]
	v_add_co_u32_e32 v2, vcc, s6, v36
	s_mov_b32 s6, 0xc000
	s_nop 0
	v_addc_co_u32_e32 v3, vcc, 0, v37, vcc
	s_nop 0
	v_add_u32_e32 v139, 0x35000, v32
	global_load_dword v139, v139, s[100:101]
	s_nop 0
	s_nop 0
	v_add_u32_e32 v190, 0x35800, v32
	global_load_dword v190, v190, s[100:101]
	s_waitcnt vmcnt(50)
	v_lshl_or_b32 v5, v28, 16, v5
	v_and_or_b32 v1, v28, s16, v1
	s_waitcnt vmcnt(48)
	v_and_b32_e32 v3, 0xffff0000, v30
	v_lshlrev_b32_e32 v2, 16, v30
	v_mul_f32_e32 v2, 0xbfb8aa3b, v2
	v_exp_f32_e32 v28, v2
	s_nop 0
	v_add_f32_e32 v2, 1.0, v28
	v_rcp_f32_e32 v30, v2
	v_mul_f32_e32 v2, 0xbfb8aa3b, v3
	v_exp_f32_e32 v29, v2
	s_nop 0
	v_add_f32_e32 v2, 1.0, v29
	v_rcp_f32_e32 v31, v2
	v_add_co_u32_e32 v2, vcc, s6, v36
	s_mov_b32 s6, 0xb000
	s_nop 0
	v_addc_co_u32_e32 v3, vcc, 0, v37, vcc
	v_add_co_u32_e32 v6, vcc, s6, v36
	s_nop 0
	v_add_u32_e32 v99, 0x38c00, v32
	global_load_dword v99, v99, s[100:101]
	s_nop 0
	v_addc_co_u32_e32 v7, vcc, 0, v37, vcc
	s_nop 0
	v_add_u32_e32 v144, 0x37c00, v32
	global_load_dword v144, v144, s[100:101]
	s_nop 0
	s_nop 0
	v_add_u32_e32 v193, 0x38400, v32
	global_load_dword v193, v193, s[100:101]
	s_mov_b32 s6, 0xf000
	s_waitcnt vmcnt(50)
	v_and_b32_e32 v9, 0xffff, v8
	v_lshrrev_b32_e32 v8, 16, v8
	s_waitcnt vmcnt(48)
	v_and_b32_e32 v3, 0xffff0000, v42
	v_lshlrev_b32_e32 v2, 16, v42
	v_mul_f32_e32 v2, 0xbfb8aa3b, v2
	v_exp_f32_e32 v40, v2
	s_nop 0
	v_add_f32_e32 v2, 1.0, v40
	v_rcp_f32_e32 v42, v2
	v_mul_f32_e32 v2, 0xbfb8aa3b, v3
	v_exp_f32_e32 v41, v2
	s_nop 0
	v_add_f32_e32 v2, 1.0, v41
	v_rcp_f32_e32 v43, v2
	v_add_co_u32_e32 v2, vcc, s6, v36
	s_mov_b32 s6, 0xe000
	s_nop 0
	v_addc_co_u32_e32 v3, vcc, 0, v37, vcc
	v_add_co_u32_e32 v6, vcc, s6, v36
	s_nop 0
	v_add_u32_e32 v197, 0x3b800, v32
	global_load_dword v197, v197, s[100:101]
	s_nop 0
	v_addc_co_u32_e32 v7, vcc, 0, v37, vcc
	s_nop 0
	v_add_u32_e32 v194, 0x3a800, v32
	global_load_dword v194, v194, s[100:101]
	s_nop 0
	s_nop 0
	v_add_u32_e32 v100, 0x3b000, v32
	global_load_dword v100, v100, s[100:101]
	s_mov_b32 s6, 0x12000
	s_waitcnt vmcnt(50)
	v_lshl_or_b32 v6, v10, 16, v9
	s_waitcnt vmcnt(48)
	v_and_b32_e32 v3, 0xffff0000, v46
	v_lshlrev_b32_e32 v2, 16, v46
	v_mul_f32_e32 v2, 0xbfb8aa3b, v2
	v_exp_f32_e32 v44, v2
	s_nop 0
	v_add_f32_e32 v2, 1.0, v44
	v_rcp_f32_e32 v46, v2
	v_mul_f32_e32 v2, 0xbfb8aa3b, v3
	v_exp_f32_e32 v45, v2
	s_nop 0
	v_add_f32_e32 v2, 1.0, v45
	v_rcp_f32_e32 v47, v2
	v_and_or_b32 v2, v10, s16, v8
	v_add_co_u32_e32 v8, vcc, s6, v36
	s_mov_b32 s6, 0x11000
	s_nop 0
	v_addc_co_u32_e32 v9, vcc, 0, v37, vcc
	s_nop 0
	v_add_u32_e32 v105, 0x3e400, v32
	global_load_dword v105, v105, s[100:101]
	v_add_co_u32_e32 v8, vcc, s6, v36
	s_mov_b32 s6, 0x15000
	s_nop 0
	v_addc_co_u32_e32 v9, vcc, 0, v37, vcc
	s_nop 0
	v_add_u32_e32 v196, 0x3d400, v32
	global_load_dword v196, v196, s[100:101]
	s_nop 0
	v_add_u32_e32 v102, 0x3dc00, v32
	global_load_dword v102, v102, s[100:101]
	s_waitcnt vmcnt(48)
	v_and_b32_e32 v8, 0xffff0000, v50
	v_lshlrev_b32_e32 v7, 16, v50
	v_mul_f32_e32 v7, 0xbfb8aa3b, v7
	v_exp_f32_e32 v48, v7
	s_nop 0
	v_add_f32_e32 v7, 1.0, v48
	v_rcp_f32_e32 v50, v7
	v_mul_f32_e32 v7, 0xbfb8aa3b, v8
	v_add_co_u32_e32 v8, vcc, s6, v36
	s_mov_b32 s6, 0x14000
	s_nop 0
	v_addc_co_u32_e32 v9, vcc, 0, v37, vcc
	s_nop 0
	v_add_u32_e32 v199, 0x41000, v32
	global_load_dword v199, v199, s[100:101]
	v_add_co_u32_e32 v8, vcc, s6, v36
	v_exp_f32_e32 v49, v7
	s_nop 0
	v_addc_co_u32_e32 v9, vcc, 0, v37, vcc
	s_nop 0
	v_add_u32_e32 v198, 0x40000, v32
	global_load_dword v198, v198, s[100:101]
	s_nop 0
	s_nop 0
	v_add_u32_e32 v104, 0x40800, v32
	global_load_dword v104, v104, s[100:101]
	s_mov_b32 s6, 0x17000
	v_add_f32_e32 v7, 1.0, v49
	v_rcp_f32_e32 v51, v7
	v_and_b32_e32 v7, 0xffff, v53
	v_lshrrev_b32_e32 v3, 16, v53
	s_waitcnt vmcnt(50)
; __device__ __forceinline__ unsigned cvt_pk_bf16(float lo, float hi) { const f32x2_cv v = {lo, hi}; return __builtin_bit_cast(unsigned, __builtin_convertvector(v, bf16x2_cv)); }
; __device__ __forceinline__ float bf_lo(unsigned u) { return __uint_as_float(u << 16); }
; __device__ __forceinline__ float bf_hi(unsigned u) { return __uint_as_float(u & 0xffff0000u); }
; __device__ __forceinline__ void hgrn_prep_item(const bf16_t* Z, const float* lbl, unsigned char* REC, int cidx, int h, LAS unsigned char* wl, int lane) {
;     ...
;     for (int t = 0; t < 32; ++t) {
;         const unsigned ff = *(const unsigned*)(zr + (size_t)t * DIN + ZHF), ii = *(const unsigned*)(zr + (size_t)t * DIN + ZHI);
;         qraw[t] = *(const unsigned*)(zr + (size_t)t * DIN + ZHQ); float omv[2];
; #pragma unroll
;         for (int e = 0; e < 2; ++e) {
;             const float fl = e ? bf_hi(ff) : bf_lo(ff);
;             const float ex = __expf(-fl), sg = __builtin_amdgcn_rcpf(1.f + ex);
;             const float f = lb[e] + omlb[e] * sg;
;             omv[e] = omlb[e] * (ex * sg);
;             cum[e] += __logf(f); cv[t][e] = cum[e];
;         }
;         omp[t] = cvt_pk_bf16(omv[0], omv[1]);
;         if ((t & 1) == 0) { itp[0][t >> 1] = ii & 0xffffu; itp[1][t >> 1] = ii >> 16; }
;         else { itp[0][t >> 1] |= ii << 16; itp[1][t >> 1] |= ii & 0xffff0000u; }
	v_lshl_or_b32 v7, v52, 16, v7
	v_and_or_b32 v3, v52, s16, v3
	s_waitcnt vmcnt(48)
	v_and_b32_e32 v9, 0xffff0000, v54
	v_lshlrev_b32_e32 v8, 16, v54
	v_mul_f32_e32 v8, 0xbfb8aa3b, v8
	v_exp_f32_e32 v52, v8
	s_nop 0
	v_add_f32_e32 v8, 1.0, v52
	v_rcp_f32_e32 v54, v8
	v_mul_f32_e32 v8, 0xbfb8aa3b, v9
	v_exp_f32_e32 v53, v8
	s_nop 0
	v_add_f32_e32 v8, 1.0, v53
	v_rcp_f32_e32 v55, v8
	v_add_co_u32_e32 v8, vcc, s6, v36
	s_mov_b32 s6, 0x16000
	s_nop 0
	v_addc_co_u32_e32 v9, vcc, 0, v37, vcc
	v_add_co_u32_e32 v10, vcc, s6, v36
	s_nop 0
	v_add_u32_e32 v202, 0x43c00, v32
	global_load_dword v202, v202, s[100:101]
	s_nop 0
	v_addc_co_u32_e32 v11, vcc, 0, v37, vcc
	s_nop 0
	v_add_u32_e32 v200, 0x42c00, v32
	global_load_dword v200, v200, s[100:101]
	s_nop 0
	s_nop 0
	v_add_u32_e32 v106, 0x43400, v32
	global_load_dword v106, v106, s[100:101]
	s_mov_b32 s6, 0x1a000
	s_waitcnt vmcnt(50)
	v_lshrrev_b32_e32 v14, 16, v12
	v_and_b32_e32 v13, 0xffff, v12
	s_waitcnt vmcnt(48)
	v_and_b32_e32 v9, 0xffff0000, v62
	v_lshlrev_b32_e32 v8, 16, v62
	v_mul_f32_e32 v8, 0xbfb8aa3b, v8
	v_exp_f32_e32 v60, v8
	s_nop 0
	v_add_f32_e32 v8, 1.0, v60
	v_rcp_f32_e32 v62, v8
	v_mul_f32_e32 v8, 0xbfb8aa3b, v9
	v_exp_f32_e32 v61, v8
	s_nop 0
	v_add_f32_e32 v8, 1.0, v61
	v_rcp_f32_e32 v63, v8
	v_add_co_u32_e32 v8, vcc, s6, v36
	s_mov_b32 s6, 0x19000
	s_nop 0
	v_addc_co_u32_e32 v9, vcc, 0, v37, vcc
	v_add_co_u32_e32 v10, vcc, s6, v36
	s_nop 0
	v_add_u32_e32 v109, 0x46800, v32
	global_load_dword v109, v109, s[100:101]
	s_nop 0
	v_addc_co_u32_e32 v11, vcc, 0, v37, vcc
	s_nop 0
	v_add_u32_e32 v204, 0x45800, v32
	global_load_dword v204, v204, s[100:101]
	s_nop 0
	s_nop 0
	v_add_u32_e32 v108, 0x46000, v32
	global_load_dword v108, v108, s[100:101]
	s_mov_b32 s6, 0x1d000
	v_add_co_u32_e32 v10, vcc, s6, v36
	s_mov_b32 s6, 0x1c000
	s_nop 0
	v_addc_co_u32_e32 v11, vcc, 0, v37, vcc
	s_waitcnt vmcnt(50)
	v_lshl_or_b32 v12, v15, 16, v13
	s_waitcnt vmcnt(48)
	v_and_b32_e32 v9, 0xffff0000, v70
	v_lshlrev_b32_e32 v8, 16, v70
	v_mul_f32_e32 v8, 0xbfb8aa3b, v8
	v_exp_f32_e32 v66, v8
	s_nop 0
	v_add_f32_e32 v8, 1.0, v66
	v_rcp_f32_e32 v70, v8
	v_mul_f32_e32 v8, 0xbfb8aa3b, v9
	s_nop 0
	v_add_u32_e32 v113, 0x49400, v32
	global_load_dword v113, v113, s[100:101]
	v_add_co_u32_e32 v10, vcc, s6, v36
	v_exp_f32_e32 v67, v8
	s_nop 0
	v_addc_co_u32_e32 v11, vcc, 0, v37, vcc
	s_nop 0
	v_add_u32_e32 v208, 0x48400, v32
	global_load_dword v208, v208, s[100:101]
	s_nop 0
	s_nop 0
	v_add_u32_e32 v110, 0x48c00, v32
	global_load_dword v110, v110, s[100:101]
	s_mov_b32 s6, 0x20000
	v_add_f32_e32 v8, 1.0, v67
	v_rcp_f32_e32 v71, v8
	v_and_or_b32 v8, v15, s16, v14
	s_waitcnt vmcnt(50)
	v_and_b32_e32 v13, 0xffff, v72
	v_lshrrev_b32_e32 v9, 16, v72
	s_waitcnt vmcnt(48)
	v_and_b32_e32 v11, 0xffff0000, v76
	v_lshlrev_b32_e32 v10, 16, v76
	v_mul_f32_e32 v10, 0xbfb8aa3b, v10
	v_exp_f32_e32 v72, v10
	s_nop 0
	v_add_f32_e32 v10, 1.0, v72
	v_rcp_f32_e32 v76, v10
	v_mul_f32_e32 v10, 0xbfb8aa3b, v11
	v_exp_f32_e32 v73, v10
	s_nop 0
	v_add_f32_e32 v10, 1.0, v73
	v_rcp_f32_e32 v77, v10
	v_add_co_u32_e32 v10, vcc, s6, v36
	s_mov_b32 s6, 0x1f000
	s_nop 0
	v_addc_co_u32_e32 v11, vcc, 0, v37, vcc
	s_nop 0
	v_add_u32_e32 v211, 0x4c000, v32
	global_load_dword v211, v211, s[100:101]
	v_add_co_u32_e32 v10, vcc, s6, v36
	s_mov_b32 s6, 0x22000
	s_nop 0
	v_addc_co_u32_e32 v11, vcc, 0, v37, vcc
	s_nop 0
	v_add_u32_e32 v210, 0x4b000, v32
	global_load_dword v210, v210, s[100:101]
	s_nop 0
	s_nop 0
	v_add_u32_e32 v112, 0x4b800, v32
	global_load_dword v112, v112, s[100:101]
	s_waitcnt vmcnt(50)
	v_lshl_or_b32 v13, v80, 16, v13
	v_and_or_b32 v9, v80, s16, v9
	s_waitcnt vmcnt(48)
	v_and_b32_e32 v11, 0xffff0000, v82
	v_lshlrev_b32_e32 v10, 16, v82
	v_mul_f32_e32 v10, 0xbfb8aa3b, v10
	v_exp_f32_e32 v80, v10
	s_nop 0
	v_add_f32_e32 v10, 1.0, v80
	v_rcp_f32_e32 v82, v10
	v_mul_f32_e32 v10, 0xbfb8aa3b, v11
	v_exp_f32_e32 v81, v10
	s_nop 0
	v_add_f32_e32 v10, 1.0, v81
	v_rcp_f32_e32 v83, v10
	v_add_co_u32_e32 v10, vcc, s6, v36
	s_nop 1
	v_addc_co_u32_e32 v11, vcc, 0, v37, vcc
	v_add_co_u32_e32 v14, vcc, s17, v36
	s_nop 0
	v_add_u32_e32 v115, 0x4ec00, v32
	global_load_dword v115, v115, s[100:101]
	s_nop 0
	v_addc_co_u32_e32 v15, vcc, 0, v37, vcc
	s_nop 0
	v_add_u32_e32 v212, 0x4dc00, v32
	global_load_dword v212, v212, s[100:101]
	s_nop 0
	s_nop 0
	v_add_u32_e32 v114, 0x4e400, v32
	global_load_dword v114, v114, s[100:101]
	s_waitcnt vmcnt(50)
	v_and_b32_e32 v39, 0xffff, v38
	v_lshrrev_b32_e32 v38, 16, v38
	s_waitcnt vmcnt(48)
	v_and_b32_e32 v11, 0xffff0000, v86
	v_lshlrev_b32_e32 v10, 16, v86
	v_mul_f32_e32 v10, 0xbfb8aa3b, v10
	v_exp_f32_e32 v84, v10
	s_nop 0
	v_add_f32_e32 v10, 1.0, v84
	v_rcp_f32_e32 v86, v10
	v_mul_f32_e32 v10, 0xbfb8aa3b, v11
	v_exp_f32_e32 v85, v10
	s_nop 0
	v_add_f32_e32 v10, 1.0, v85
	v_rcp_f32_e32 v87, v10
	v_add_co_u32_e32 v10, vcc, s18, v36
	s_nop 1
	v_addc_co_u32_e32 v11, vcc, 0, v37, vcc
	v_add_co_u32_e32 v14, vcc, s19, v36
	s_nop 0
	v_add_u32_e32 v118, 0x51800, v32
	global_load_dword v118, v118, s[100:101]
	s_nop 0
	v_addc_co_u32_e32 v15, vcc, 0, v37, vcc
	s_nop 0
	v_add_u32_e32 v214, 0x50800, v32
	global_load_dword v214, v214, s[100:101]
	s_nop 0
	s_nop 0
	v_add_u32_e32 v116, 0x51000, v32
	global_load_dword v116, v116, s[100:101]
	s_waitcnt vmcnt(50)
	v_lshl_or_b32 v14, v56, 16, v39
	s_waitcnt vmcnt(48)
	v_and_b32_e32 v11, 0xffff0000, v78
	v_lshlrev_b32_e32 v10, 16, v78
	v_mul_f32_e32 v10, 0xbfb8aa3b, v10
	v_exp_f32_e32 v74, v10
	s_nop 0
	v_add_f32_e32 v10, 1.0, v74
	v_rcp_f32_e32 v78, v10
	v_mul_f32_e32 v10, 0xbfb8aa3b, v11
	v_exp_f32_e32 v75, v10
	s_nop 0
	v_add_f32_e32 v10, 1.0, v75
	v_rcp_f32_e32 v79, v10
	v_and_or_b32 v10, v56, s16, v38
	v_add_co_u32_e32 v38, vcc, s20, v36
	s_nop 1
	v_addc_co_u32_e32 v39, vcc, 0, v37, vcc
	s_nop 0
	v_add_u32_e32 v219, 0x54400, v32
	global_load_dword v219, v219, s[100:101]
	v_add_co_u32_e32 v38, vcc, s21, v36
	s_waitcnt vmcnt(48)
; __device__ __forceinline__ unsigned cvt_pk_bf16(float lo, float hi) { const f32x2_cv v = {lo, hi}; return __builtin_bit_cast(unsigned, __builtin_convertvector(v, bf16x2_cv)); }
; __device__ __forceinline__ float bf_lo(unsigned u) { return __uint_as_float(u << 16); }
; __device__ __forceinline__ float bf_hi(unsigned u) { return __uint_as_float(u & 0xffff0000u); }
; __device__ __forceinline__ void hgrn_prep_item(const bf16_t* Z, const float* lbl, unsigned char* REC, int cidx, int h, LAS unsigned char* wl, int lane) {
;     ...
;     for (int t = 0; t < 32; ++t) {
;         const unsigned ff = *(const unsigned*)(zr + (size_t)t * DIN + ZHF), ii = *(const unsigned*)(zr + (size_t)t * DIN + ZHI);
;         qraw[t] = *(const unsigned*)(zr + (size_t)t * DIN + ZHQ); float omv[2];
; #pragma unroll
;         for (int e = 0; e < 2; ++e) {
;             const float fl = e ? bf_hi(ff) : bf_lo(ff);
;             const float ex = __expf(-fl), sg = __builtin_amdgcn_rcpf(1.f + ex);
;             const float f = lb[e] + omlb[e] * sg;
;             omv[e] = omlb[e] * (ex * sg);
;             cum[e] += __logf(f); cv[t][e] = cum[e];
;         }
;         omp[t] = cvt_pk_bf16(omv[0], omv[1]);
	v_lshrrev_b32_e32 v97, 16, v57
	v_addc_co_u32_e32 v39, vcc, 0, v37, vcc
	s_nop 0
	v_add_u32_e32 v220, 0x53400, v32
	global_load_dword v220, v220, s[100:101]
	s_nop 0
	v_add_u32_e32 v120, 0x53c00, v32
	global_load_dword v120, v120, s[100:101]
	s_waitcnt vmcnt(48)
	v_and_b32_e32 v38, 0xffff0000, v68
	v_lshlrev_b32_e32 v11, 16, v68
	v_mul_f32_e32 v11, 0xbfb8aa3b, v11
	v_exp_f32_e32 v64, v11
	s_nop 0
	v_add_f32_e32 v11, 1.0, v64
	v_rcp_f32_e32 v68, v11
	v_mul_f32_e32 v11, 0xbfb8aa3b, v38
	v_exp_f32_e32 v65, v11
	v_add_co_u32_e32 v38, vcc, s22, v36
	v_add_f32_e32 v11, 1.0, v65
	s_nop 0
	v_addc_co_u32_e32 v39, vcc, 0, v37, vcc
	s_nop 0
	v_add_u32_e32 v223, 0x57000, v32
	global_load_dword v223, v223, s[100:101]
	v_add_co_u32_e32 v38, vcc, s23, v36
	v_rcp_f32_e32 v69, v11
	s_nop 0
	v_addc_co_u32_e32 v39, vcc, 0, v37, vcc
	v_and_b32_e32 v11, 0xffff, v57
	s_nop 0
	v_add_u32_e32 v222, 0x56000, v32
	global_load_dword v222, v222, s[100:101]
	s_nop 0
	v_add_u32_e32 v218, 0x56800, v32
	global_load_dword v218, v218, s[100:101]
	s_waitcnt vmcnt(48)
	v_and_b32_e32 v38, 0xffff0000, v58
	v_lshlrev_b32_e32 v15, 16, v58
	v_mul_f32_e32 v15, 0xbfb8aa3b, v15
	v_exp_f32_e32 v56, v15
	s_nop 0
	v_add_f32_e32 v15, 1.0, v56
	v_rcp_f32_e32 v58, v15
	v_mul_f32_e32 v15, 0xbfb8aa3b, v38
	v_exp_f32_e32 v57, v15
	v_pk_add_f32 v[38:39], v[34:35], 1.0 op_sel_hi:[1,0] neg_lo:[1,0] neg_hi:[1,0]
	v_add_f32_e32 v15, 1.0, v57
	v_rcp_f32_e32 v59, v15
	v_fma_f32 v15, v38, v18, v34
	v_cmp_gt_f32_e32 vcc, s24, v15
	v_pk_mul_f32 v[16:17], v[38:39], v[16:17]
	s_nop 0
	v_cndmask_b32_e64 v88, 0, 32, vcc
	v_ldexp_f32 v15, v15, v88
	v_log_f32_e32 v15, v15
	v_cvt_pk_bf16_f32 v123, v16, v17
	v_lshlrev_b32_e32 v122, 16, v123
	v_and_b32_e32 v123, 0xffff0000, v123
	v_mul_f32_e32 v88, 0x3f317217, v15
	v_fma_f32 v88, v15, s25, -v88
	v_fmac_f32_e32 v88, 0x3377d1cf, v15
	v_fmac_f32_e32 v88, 0x3f317217, v15
	v_cmp_lt_f32_e64 s[6:7], |v15|, s26
	s_nop 1
	v_cndmask_b32_e64 v15, v15, v88, s[6:7]
	v_cndmask_b32_e32 v88, 0, v216, vcc
	v_sub_f32_e32 v15, v15, v88
	v_add_f32_e32 v88, 0, v15
	v_fma_f32 v15, v39, v19, v35
	v_cmp_gt_f32_e32 vcc, s24, v15
	s_nop 1
	v_cndmask_b32_e64 v18, 0, 32, vcc
	v_ldexp_f32 v15, v15, v18
	v_log_f32_e32 v15, v15
	s_nop 0
	v_mul_f32_e32 v18, 0x3f317217, v15
	v_fma_f32 v18, v15, s25, -v18
	v_fmac_f32_e32 v18, 0x3377d1cf, v15
	v_fmac_f32_e32 v18, 0x3f317217, v15
	v_cmp_lt_f32_e64 s[6:7], |v15|, s26
	s_nop 1
	v_cndmask_b32_e64 v15, v15, v18, s[6:7]
	v_cndmask_b32_e32 v18, 0, v216, vcc
	v_sub_f32_e32 v15, v15, v18
	v_add_f32_e32 v89, 0, v15
	v_fma_f32 v15, v38, v22, v34
	v_cmp_gt_f32_e32 vcc, s24, v15
	s_nop 1
	v_cndmask_b32_e64 v16, 0, 32, vcc
	v_ldexp_f32 v15, v15, v16
	v_log_f32_e32 v15, v15
	s_nop 0
	v_mul_f32_e32 v16, 0x3f317217, v15
	v_fma_f32 v16, v15, s25, -v16
	v_fmac_f32_e32 v16, 0x3377d1cf, v15
	v_fmac_f32_e32 v16, 0x3f317217, v15
	v_cmp_lt_f32_e64 s[6:7], |v15|, s26
	s_nop 1
	v_cndmask_b32_e64 v15, v15, v16, s[6:7]
	v_cndmask_b32_e32 v16, 0, v216, vcc
	v_sub_f32_e32 v15, v15, v16
	v_add_f32_e32 v90, v88, v15
	v_fma_f32 v15, v39, v23, v35
	v_cmp_gt_f32_e32 vcc, s24, v15
	v_pk_mul_f32 v[16:17], v[20:21], v[22:23]
	s_nop 0
	v_cndmask_b32_e64 v18, 0, 32, vcc
	v_ldexp_f32 v15, v15, v18
	v_log_f32_e32 v15, v15
	v_pk_mul_f32 v[16:17], v[38:39], v[16:17]
	v_mul_f32_e32 v18, 0x3f317217, v15
	v_fma_f32 v18, v15, s25, -v18
	v_fmac_f32_e32 v18, 0x3377d1cf, v15
	v_fmac_f32_e32 v18, 0x3f317217, v15
	v_cmp_lt_f32_e64 s[6:7], |v15|, s26
	v_cvt_pk_bf16_f32 v131, v16, v17
	s_nop 0
	v_cndmask_b32_e64 v15, v15, v18, s[6:7]
	v_cndmask_b32_e32 v18, 0, v216, vcc
	v_sub_f32_e32 v15, v15, v18
	v_add_f32_e32 v91, v89, v15
	v_fma_f32 v15, v38, v26, v34
	v_cmp_gt_f32_e32 vcc, s24, v15
	s_nop 1
	v_cndmask_b32_e64 v16, 0, 32, vcc
	v_ldexp_f32 v15, v15, v16
	v_log_f32_e32 v15, v15
	s_nop 0
	v_mul_f32_e32 v16, 0x3f317217, v15
	v_fma_f32 v16, v15, s25, -v16
	v_fmac_f32_e32 v16, 0x3377d1cf, v15
	v_fmac_f32_e32 v16, 0x3f317217, v15
	v_cmp_lt_f32_e64 s[6:7], |v15|, s26
	s_nop 1
	v_cndmask_b32_e64 v15, v15, v16, s[6:7]
	v_cndmask_b32_e32 v16, 0, v216, vcc
	v_sub_f32_e32 v15, v15, v16
	v_add_f32_e32 v92, v90, v15
	v_fma_f32 v15, v39, v27, v35
	v_cmp_gt_f32_e32 vcc, s24, v15
	v_pk_mul_f32 v[16:17], v[24:25], v[26:27]
	s_nop 0
	v_cndmask_b32_e64 v18, 0, 32, vcc
	v_ldexp_f32 v15, v15, v18
	v_log_f32_e32 v15, v15
	v_pk_mul_f32 v[16:17], v[38:39], v[16:17]
	v_mul_f32_e32 v18, 0x3f317217, v15
	v_fma_f32 v18, v15, s25, -v18
	v_fmac_f32_e32 v18, 0x3377d1cf, v15
	v_fmac_f32_e32 v18, 0x3f317217, v15
	v_cmp_lt_f32_e64 s[6:7], |v15|, s26
	v_cvt_pk_bf16_f32 v141, v16, v17
	s_nop 0
	v_cndmask_b32_e64 v15, v15, v18, s[6:7]
	v_cndmask_b32_e32 v18, 0, v216, vcc
	v_sub_f32_e32 v15, v15, v18
	v_add_f32_e32 v93, v91, v15
	v_fma_f32 v15, v38, v30, v34
	v_cmp_gt_f32_e32 vcc, s24, v15
	s_nop 1
	v_cndmask_b32_e64 v16, 0, 32, vcc
	v_ldexp_f32 v15, v15, v16
	v_log_f32_e32 v15, v15
	s_nop 0
	v_mul_f32_e32 v16, 0x3f317217, v15
	v_fma_f32 v16, v15, s25, -v16
	v_fmac_f32_e32 v16, 0x3377d1cf, v15
	v_fmac_f32_e32 v16, 0x3f317217, v15
	v_cmp_lt_f32_e64 s[6:7], |v15|, s26
	s_nop 1
	v_cndmask_b32_e64 v15, v15, v16, s[6:7]
	v_cndmask_b32_e32 v16, 0, v216, vcc
	v_sub_f32_e32 v15, v15, v16
	v_add_f32_e32 v94, v92, v15
	v_fma_f32 v15, v39, v31, v35
	v_cmp_gt_f32_e32 vcc, s24, v15
	v_pk_mul_f32 v[16:17], v[28:29], v[30:31]
	s_nop 0
	v_cndmask_b32_e64 v18, 0, 32, vcc
	v_ldexp_f32 v15, v15, v18
	v_log_f32_e32 v15, v15
	v_pk_mul_f32 v[16:17], v[38:39], v[16:17]
	v_mul_f32_e32 v18, 0x3f317217, v15
	v_fma_f32 v18, v15, s25, -v18
	v_fmac_f32_e32 v18, 0x3377d1cf, v15
	v_fmac_f32_e32 v18, 0x3f317217, v15
	v_cmp_lt_f32_e64 s[6:7], |v15|, s26
; __device__ __forceinline__ unsigned cvt_pk_bf16(float lo, float hi) { const f32x2_cv v = {lo, hi}; return __builtin_bit_cast(unsigned, __builtin_convertvector(v, bf16x2_cv)); }
; __device__ __forceinline__ float bf_lo(unsigned u) { return __uint_as_float(u << 16); }
; __device__ __forceinline__ float bf_hi(unsigned u) { return __uint_as_float(u & 0xffff0000u); }
; __device__ __forceinline__ void hgrn_prep_item(const bf16_t* Z, const float* lbl, unsigned char* REC, int cidx, int h, LAS unsigned char* wl, int lane) {
;     ...
;         for (int e = 0; e < 2; ++e) {
;             const float fl = e ? bf_hi(ff) : bf_lo(ff);
;             const float ex = __expf(-fl), sg = __builtin_amdgcn_rcpf(1.f + ex);
;             const float f = lb[e] + omlb[e] * sg;
;             omv[e] = omlb[e] * (ex * sg);
;             cum[e] += __logf(f); cv[t][e] = cum[e];
;         }
;         omp[t] = cvt_pk_bf16(omv[0], omv[1]);
	v_cvt_pk_bf16_f32 v147, v16, v17
	s_nop 0
	v_cndmask_b32_e64 v15, v15, v18, s[6:7]
	v_cndmask_b32_e32 v18, 0, v216, vcc
	v_sub_f32_e32 v15, v15, v18
	v_add_f32_e32 v95, v93, v15
	v_fma_f32 v15, v38, v42, v34
	v_cmp_gt_f32_e32 vcc, s24, v15
	s_nop 1
	v_cndmask_b32_e64 v16, 0, 32, vcc
	v_ldexp_f32 v15, v15, v16
	v_log_f32_e32 v15, v15
	s_nop 0
	v_mul_f32_e32 v16, 0x3f317217, v15
	v_fma_f32 v16, v15, s25, -v16
	v_fmac_f32_e32 v16, 0x3377d1cf, v15
	v_fmac_f32_e32 v16, 0x3f317217, v15
	v_cmp_lt_f32_e64 s[6:7], |v15|, s26
	s_nop 1
	v_cndmask_b32_e64 v15, v15, v16, s[6:7]
	v_cndmask_b32_e32 v16, 0, v216, vcc
	v_sub_f32_e32 v15, v15, v16
	v_add_f32_e32 v96, v94, v15
	v_fma_f32 v15, v39, v43, v35
	v_cmp_gt_f32_e32 vcc, s24, v15
	v_pk_mul_f32 v[16:17], v[40:41], v[42:43]
	s_nop 0
	v_cndmask_b32_e64 v18, 0, 32, vcc
	v_ldexp_f32 v15, v15, v18
	v_log_f32_e32 v15, v15
	v_pk_mul_f32 v[16:17], v[38:39], v[16:17]
	v_mul_f32_e32 v18, 0x3f317217, v15
	v_fma_f32 v18, v15, s25, -v18
	v_fmac_f32_e32 v18, 0x3377d1cf, v15
	v_fmac_f32_e32 v18, 0x3f317217, v15
	v_cmp_lt_f32_e64 s[6:7], |v15|, s26
	v_cvt_pk_bf16_f32 v157, v16, v17
	s_nop 0
	v_cndmask_b32_e64 v15, v15, v18, s[6:7]
	v_cndmask_b32_e32 v18, 0, v216, vcc
	v_sub_f32_e32 v15, v15, v18
	v_add_f32_e32 v40, v95, v15
	v_fma_f32 v15, v38, v46, v34
	v_cmp_gt_f32_e32 vcc, s24, v15
	s_nop 1
	v_cndmask_b32_e64 v16, 0, 32, vcc
	v_ldexp_f32 v15, v15, v16
	v_log_f32_e32 v15, v15
	s_nop 0
	v_mul_f32_e32 v16, 0x3f317217, v15
	v_fma_f32 v16, v15, s25, -v16
	v_fmac_f32_e32 v16, 0x3377d1cf, v15
	v_fmac_f32_e32 v16, 0x3f317217, v15
	v_cmp_lt_f32_e64 s[6:7], |v15|, s26
	s_nop 1
	v_cndmask_b32_e64 v15, v15, v16, s[6:7]
	v_cndmask_b32_e32 v16, 0, v216, vcc
	v_sub_f32_e32 v15, v15, v16
	v_add_f32_e32 v41, v96, v15
	v_fma_f32 v15, v39, v47, v35
	v_cmp_gt_f32_e32 vcc, s24, v15
	v_pk_mul_f32 v[16:17], v[44:45], v[46:47]
	s_nop 0
	v_cndmask_b32_e64 v18, 0, 32, vcc
	v_ldexp_f32 v15, v15, v18
	v_log_f32_e32 v15, v15
	v_pk_mul_f32 v[16:17], v[38:39], v[16:17]
	v_mul_f32_e32 v18, 0x3f317217, v15
	v_fma_f32 v18, v15, s25, -v18
	v_fmac_f32_e32 v18, 0x3377d1cf, v15
	v_fmac_f32_e32 v18, 0x3f317217, v15
	v_cmp_lt_f32_e64 s[6:7], |v15|, s26
	v_cvt_pk_bf16_f32 v163, v16, v17
	s_nop 0
	v_cndmask_b32_e64 v15, v15, v18, s[6:7]
	v_cndmask_b32_e32 v18, 0, v216, vcc
	v_sub_f32_e32 v15, v15, v18
	v_add_f32_e32 v42, v40, v15
	v_fma_f32 v15, v38, v50, v34
	v_cmp_gt_f32_e32 vcc, s24, v15
	s_nop 1
	v_cndmask_b32_e64 v16, 0, 32, vcc
	v_ldexp_f32 v15, v15, v16
	v_log_f32_e32 v15, v15
	s_nop 0
	v_mul_f32_e32 v16, 0x3f317217, v15
	v_fma_f32 v16, v15, s25, -v16
	v_fmac_f32_e32 v16, 0x3377d1cf, v15
	v_fmac_f32_e32 v16, 0x3f317217, v15
	v_cmp_lt_f32_e64 s[6:7], |v15|, s26
	s_nop 1
	v_cndmask_b32_e64 v15, v15, v16, s[6:7]
	v_cndmask_b32_e32 v16, 0, v216, vcc
	v_sub_f32_e32 v15, v15, v16
	v_add_f32_e32 v43, v41, v15
	v_fma_f32 v15, v39, v51, v35
	v_cmp_gt_f32_e32 vcc, s24, v15
	v_pk_mul_f32 v[16:17], v[48:49], v[50:51]
	s_nop 0
	v_cndmask_b32_e64 v18, 0, 32, vcc
	v_ldexp_f32 v15, v15, v18
	v_log_f32_e32 v15, v15
	v_pk_mul_f32 v[16:17], v[38:39], v[16:17]
	v_mul_f32_e32 v18, 0x3f317217, v15
	v_fma_f32 v18, v15, s25, -v18
	v_fmac_f32_e32 v18, 0x3377d1cf, v15
	v_fmac_f32_e32 v18, 0x3f317217, v15
	v_cmp_lt_f32_e64 s[6:7], |v15|, s26
	v_cvt_pk_bf16_f32 v165, v16, v17
	s_nop 0
	v_cndmask_b32_e64 v15, v15, v18, s[6:7]
	v_cndmask_b32_e32 v18, 0, v216, vcc
	v_sub_f32_e32 v15, v15, v18
	v_add_f32_e32 v44, v42, v15
	v_fma_f32 v15, v38, v54, v34
	v_cmp_gt_f32_e32 vcc, s24, v15
	s_nop 1
	v_cndmask_b32_e64 v16, 0, 32, vcc
	v_ldexp_f32 v15, v15, v16
	v_log_f32_e32 v15, v15
	s_nop 0
	v_mul_f32_e32 v16, 0x3f317217, v15
	v_fma_f32 v16, v15, s25, -v16
	v_fmac_f32_e32 v16, 0x3377d1cf, v15
	v_fmac_f32_e32 v16, 0x3f317217, v15
	v_cmp_lt_f32_e64 s[6:7], |v15|, s26
	s_nop 1
	v_cndmask_b32_e64 v15, v15, v16, s[6:7]
	v_cndmask_b32_e32 v16, 0, v216, vcc
	v_sub_f32_e32 v15, v15, v16
	v_add_f32_e32 v45, v43, v15
	v_fma_f32 v15, v39, v55, v35
	v_cmp_gt_f32_e32 vcc, s24, v15
	v_pk_mul_f32 v[16:17], v[52:53], v[54:55]
	s_nop 0
	v_cndmask_b32_e64 v18, 0, 32, vcc
	v_ldexp_f32 v15, v15, v18
	v_log_f32_e32 v15, v15
	v_pk_mul_f32 v[16:17], v[38:39], v[16:17]
	v_mul_f32_e32 v18, 0x3f317217, v15
	v_fma_f32 v18, v15, s25, -v18
	v_fmac_f32_e32 v18, 0x3377d1cf, v15
	v_fmac_f32_e32 v18, 0x3f317217, v15
	v_cmp_lt_f32_e64 s[6:7], |v15|, s26
	v_cvt_pk_bf16_f32 v167, v16, v17
	s_nop 0
	v_cndmask_b32_e64 v15, v15, v18, s[6:7]
	v_cndmask_b32_e32 v18, 0, v216, vcc
	v_sub_f32_e32 v15, v15, v18
	v_add_f32_e32 v46, v44, v15
	v_fma_f32 v15, v38, v62, v34
	v_cmp_gt_f32_e32 vcc, s24, v15
	s_nop 1
	v_cndmask_b32_e64 v16, 0, 32, vcc
	v_ldexp_f32 v15, v15, v16
	v_log_f32_e32 v15, v15
	s_nop 0
	v_mul_f32_e32 v16, 0x3f317217, v15
	v_fma_f32 v16, v15, s25, -v16
	v_fmac_f32_e32 v16, 0x3377d1cf, v15
	v_fmac_f32_e32 v16, 0x3f317217, v15
	v_cmp_lt_f32_e64 s[6:7], |v15|, s26
	s_nop 1
	v_cndmask_b32_e64 v15, v15, v16, s[6:7]
	v_cndmask_b32_e32 v16, 0, v216, vcc
	v_sub_f32_e32 v15, v15, v16
	v_add_f32_e32 v47, v45, v15
	v_fma_f32 v15, v39, v63, v35
	v_cmp_gt_f32_e32 vcc, s24, v15
	v_pk_mul_f32 v[16:17], v[60:61], v[62:63]
	s_nop 0
	v_cndmask_b32_e64 v18, 0, 32, vcc
	v_ldexp_f32 v15, v15, v18
	v_log_f32_e32 v15, v15
	v_pk_mul_f32 v[16:17], v[38:39], v[16:17]
	v_mul_f32_e32 v18, 0x3f317217, v15
	v_fma_f32 v18, v15, s25, -v18
	v_fmac_f32_e32 v18, 0x3377d1cf, v15
	v_fmac_f32_e32 v18, 0x3f317217, v15
	v_cmp_lt_f32_e64 s[6:7], |v15|, s26
	v_cvt_pk_bf16_f32 v169, v16, v17
	s_nop 0
	v_cndmask_b32_e64 v15, v15, v18, s[6:7]
	v_cndmask_b32_e32 v18, 0, v216, vcc
	v_sub_f32_e32 v15, v15, v18
	v_add_f32_e32 v48, v46, v15
	v_fma_f32 v15, v38, v70, v34
; __device__ __forceinline__ unsigned cvt_pk_bf16(float lo, float hi) { const f32x2_cv v = {lo, hi}; return __builtin_bit_cast(unsigned, __builtin_convertvector(v, bf16x2_cv)); }
; __device__ __forceinline__ float bf_lo(unsigned u) { return __uint_as_float(u << 16); }
; __device__ __forceinline__ float bf_hi(unsigned u) { return __uint_as_float(u & 0xffff0000u); }
; __device__ __forceinline__ void hgrn_prep_item(const bf16_t* Z, const float* lbl, unsigned char* REC, int cidx, int h, LAS unsigned char* wl, int lane) {
;     ...
;         for (int e = 0; e < 2; ++e) {
;             const float fl = e ? bf_hi(ff) : bf_lo(ff);
;             const float ex = __expf(-fl), sg = __builtin_amdgcn_rcpf(1.f + ex);
;             const float f = lb[e] + omlb[e] * sg;
;             omv[e] = omlb[e] * (ex * sg);
;             cum[e] += __logf(f); cv[t][e] = cum[e];
;         }
;         omp[t] = cvt_pk_bf16(omv[0], omv[1]);
	v_cmp_gt_f32_e32 vcc, s24, v15
	s_nop 1
	v_cndmask_b32_e64 v16, 0, 32, vcc
	v_ldexp_f32 v15, v15, v16
	v_log_f32_e32 v15, v15
	s_nop 0
	v_mul_f32_e32 v16, 0x3f317217, v15
	v_fma_f32 v16, v15, s25, -v16
	v_fmac_f32_e32 v16, 0x3377d1cf, v15
	v_fmac_f32_e32 v16, 0x3f317217, v15
	v_cmp_lt_f32_e64 s[6:7], |v15|, s26
	s_nop 1
	v_cndmask_b32_e64 v15, v15, v16, s[6:7]
	v_cndmask_b32_e32 v16, 0, v216, vcc
	v_sub_f32_e32 v15, v15, v16
	v_add_f32_e32 v49, v47, v15
	v_fma_f32 v15, v39, v71, v35
	v_cmp_gt_f32_e32 vcc, s24, v15
	v_pk_mul_f32 v[16:17], v[66:67], v[70:71]
	s_nop 0
	v_cndmask_b32_e64 v18, 0, 32, vcc
	v_ldexp_f32 v15, v15, v18
	v_log_f32_e32 v15, v15
	v_pk_mul_f32 v[16:17], v[38:39], v[16:17]
	v_mul_f32_e32 v18, 0x3f317217, v15
	v_fma_f32 v18, v15, s25, -v18
	v_fmac_f32_e32 v18, 0x3377d1cf, v15
	v_fmac_f32_e32 v18, 0x3f317217, v15
	v_cmp_lt_f32_e64 s[6:7], |v15|, s26
	v_cvt_pk_bf16_f32 v66, v16, v17
	s_nop 0
	v_cndmask_b32_e64 v15, v15, v18, s[6:7]
	v_cndmask_b32_e32 v18, 0, v216, vcc
	v_sub_f32_e32 v15, v15, v18
	v_add_f32_e32 v50, v48, v15
	v_fma_f32 v15, v38, v76, v34
	v_cmp_gt_f32_e32 vcc, s24, v15
	s_nop 1
	v_cndmask_b32_e64 v16, 0, 32, vcc
	v_ldexp_f32 v15, v15, v16
	v_log_f32_e32 v15, v15
	s_nop 0
	v_mul_f32_e32 v16, 0x3f317217, v15
	v_fma_f32 v16, v15, s25, -v16
	v_fmac_f32_e32 v16, 0x3377d1cf, v15
	v_fmac_f32_e32 v16, 0x3f317217, v15
	v_cmp_lt_f32_e64 s[6:7], |v15|, s26
	s_nop 1
	v_cndmask_b32_e64 v15, v15, v16, s[6:7]
	v_cndmask_b32_e32 v16, 0, v216, vcc
	v_sub_f32_e32 v15, v15, v16
	v_add_f32_e32 v51, v49, v15
	v_fma_f32 v15, v39, v77, v35
	v_cmp_gt_f32_e32 vcc, s24, v15
	v_pk_mul_f32 v[16:17], v[72:73], v[76:77]
	s_nop 0
	v_cndmask_b32_e64 v18, 0, 32, vcc
	v_ldexp_f32 v15, v15, v18
	v_log_f32_e32 v15, v15
	v_pk_mul_f32 v[16:17], v[38:39], v[16:17]
	v_mul_f32_e32 v18, 0x3f317217, v15
	v_fma_f32 v18, v15, s25, -v18
	v_fmac_f32_e32 v18, 0x3377d1cf, v15
	v_fmac_f32_e32 v18, 0x3f317217, v15
	v_cmp_lt_f32_e64 s[6:7], |v15|, s26
	v_cvt_pk_bf16_f32 v67, v16, v17
	s_nop 0
	v_cndmask_b32_e64 v15, v15, v18, s[6:7]
	v_cndmask_b32_e32 v18, 0, v216, vcc
	v_sub_f32_e32 v15, v15, v18
	v_add_f32_e32 v52, v50, v15
	v_fma_f32 v15, v38, v82, v34
	v_cmp_gt_f32_e32 vcc, s24, v15
	s_nop 1
	v_cndmask_b32_e64 v16, 0, 32, vcc
	v_ldexp_f32 v15, v15, v16
	v_log_f32_e32 v15, v15
	s_nop 0
	v_mul_f32_e32 v16, 0x3f317217, v15
	v_fma_f32 v16, v15, s25, -v16
	v_fmac_f32_e32 v16, 0x3377d1cf, v15
	v_fmac_f32_e32 v16, 0x3f317217, v15
	v_cmp_lt_f32_e64 s[6:7], |v15|, s26
	s_nop 1
	v_cndmask_b32_e64 v15, v15, v16, s[6:7]
	v_cndmask_b32_e32 v16, 0, v216, vcc
	v_sub_f32_e32 v15, v15, v16
	v_add_f32_e32 v53, v51, v15
	v_fma_f32 v15, v39, v83, v35
	v_cmp_gt_f32_e32 vcc, s24, v15
	v_pk_mul_f32 v[16:17], v[80:81], v[82:83]
	s_nop 0
	v_cndmask_b32_e64 v18, 0, 32, vcc
	v_ldexp_f32 v15, v15, v18
	v_log_f32_e32 v15, v15
	v_pk_mul_f32 v[16:17], v[38:39], v[16:17]
	v_mul_f32_e32 v18, 0x3f317217, v15
	v_fma_f32 v18, v15, s25, -v18
	v_fmac_f32_e32 v18, 0x3377d1cf, v15
	v_fmac_f32_e32 v18, 0x3f317217, v15
	v_cmp_lt_f32_e64 s[6:7], |v15|, s26
	v_cvt_pk_bf16_f32 v70, v16, v17
	v_and_b32_e32 v175, 0xffff0000, v70
	v_cndmask_b32_e64 v15, v15, v18, s[6:7]
	v_cndmask_b32_e32 v18, 0, v216, vcc
	v_sub_f32_e32 v15, v15, v18
	v_add_f32_e32 v54, v52, v15
	v_fma_f32 v15, v38, v86, v34
	v_cmp_gt_f32_e32 vcc, s24, v15
	s_nop 1
	v_cndmask_b32_e64 v16, 0, 32, vcc
	v_ldexp_f32 v15, v15, v16
	v_log_f32_e32 v15, v15
	s_nop 0
	v_mul_f32_e32 v16, 0x3f317217, v15
	v_fma_f32 v16, v15, s25, -v16
	v_fmac_f32_e32 v16, 0x3377d1cf, v15
	v_fmac_f32_e32 v16, 0x3f317217, v15
	v_cmp_lt_f32_e64 s[6:7], |v15|, s26
	s_nop 1
	v_cndmask_b32_e64 v15, v15, v16, s[6:7]
	v_cndmask_b32_e32 v16, 0, v216, vcc
	v_sub_f32_e32 v15, v15, v16
	v_add_f32_e32 v55, v53, v15
	v_fma_f32 v15, v39, v87, v35
	v_cmp_gt_f32_e32 vcc, s24, v15
	v_pk_mul_f32 v[16:17], v[84:85], v[86:87]
	s_nop 0
	v_cndmask_b32_e64 v18, 0, 32, vcc
	v_ldexp_f32 v15, v15, v18
	v_log_f32_e32 v15, v15
	v_pk_mul_f32 v[16:17], v[38:39], v[16:17]
	v_mul_f32_e32 v18, 0x3f317217, v15
	v_fma_f32 v18, v15, s25, -v18
	v_fmac_f32_e32 v18, 0x3377d1cf, v15
	v_fmac_f32_e32 v18, 0x3f317217, v15
	v_cmp_lt_f32_e64 s[6:7], |v15|, s26
	v_cvt_pk_bf16_f32 v71, v16, v17
	s_nop 0
	v_cndmask_b32_e64 v15, v15, v18, s[6:7]
	v_cndmask_b32_e32 v18, 0, v216, vcc
	v_sub_f32_e32 v15, v15, v18
	v_add_f32_e32 v60, v54, v15
	v_fma_f32 v15, v38, v78, v34
	v_cmp_gt_f32_e32 vcc, s24, v15
	s_nop 1
	v_cndmask_b32_e64 v16, 0, 32, vcc
	v_ldexp_f32 v15, v15, v16
	v_log_f32_e32 v15, v15
	s_nop 0
	v_mul_f32_e32 v16, 0x3f317217, v15
	v_fma_f32 v16, v15, s25, -v16
	v_fmac_f32_e32 v16, 0x3377d1cf, v15
	v_fmac_f32_e32 v16, 0x3f317217, v15
	v_cmp_lt_f32_e64 s[6:7], |v15|, s26
	s_nop 1
	v_cndmask_b32_e64 v15, v15, v16, s[6:7]
	v_cndmask_b32_e32 v16, 0, v216, vcc
	v_sub_f32_e32 v15, v15, v16
	v_add_f32_e32 v61, v55, v15
	v_fma_f32 v15, v39, v79, v35
	v_cmp_gt_f32_e32 vcc, s24, v15
	v_pk_mul_f32 v[16:17], v[74:75], v[78:79]
	s_nop 0
	v_cndmask_b32_e64 v18, 0, 32, vcc
	v_ldexp_f32 v15, v15, v18
	v_log_f32_e32 v15, v15
	v_pk_mul_f32 v[16:17], v[38:39], v[16:17]
	v_mul_f32_e32 v18, 0x3f317217, v15
	v_fma_f32 v18, v15, s25, -v18
	v_fmac_f32_e32 v18, 0x3377d1cf, v15
	v_fmac_f32_e32 v18, 0x3f317217, v15
	v_cmp_lt_f32_e64 s[6:7], |v15|, s26
	v_cvt_pk_bf16_f32 v72, v16, v17
	v_and_b32_e32 v179, 0xffff0000, v72
	v_cndmask_b32_e64 v15, v15, v18, s[6:7]
	v_cndmask_b32_e32 v18, 0, v216, vcc
	v_sub_f32_e32 v15, v15, v18
	v_add_f32_e32 v62, v60, v15
	v_fma_f32 v15, v38, v68, v34
	v_cmp_gt_f32_e32 vcc, s24, v15
	s_nop 1
	v_cndmask_b32_e64 v16, 0, 32, vcc
	v_ldexp_f32 v15, v15, v16
	v_log_f32_e32 v15, v15
	s_nop 0
; __device__ __forceinline__ unsigned cvt_pk_bf16(float lo, float hi) { const f32x2_cv v = {lo, hi}; return __builtin_bit_cast(unsigned, __builtin_convertvector(v, bf16x2_cv)); }
; __device__ __forceinline__ float bf_lo(unsigned u) { return __uint_as_float(u << 16); }
; __device__ __forceinline__ float bf_hi(unsigned u) { return __uint_as_float(u & 0xffff0000u); }
; __device__ __forceinline__ void hgrn_prep_item(const bf16_t* Z, const float* lbl, unsigned char* REC, int cidx, int h, LAS unsigned char* wl, int lane) {
;     ...
;     for (int t = 0; t < 32; ++t) {
;         const unsigned ff = *(const unsigned*)(zr + (size_t)t * DIN + ZHF), ii = *(const unsigned*)(zr + (size_t)t * DIN + ZHI);
;         qraw[t] = *(const unsigned*)(zr + (size_t)t * DIN + ZHQ); float omv[2];
; #pragma unroll
;         for (int e = 0; e < 2; ++e) {
;             const float fl = e ? bf_hi(ff) : bf_lo(ff);
;             const float ex = __expf(-fl), sg = __builtin_amdgcn_rcpf(1.f + ex);
;             const float f = lb[e] + omlb[e] * sg;
;             omv[e] = omlb[e] * (ex * sg);
;             cum[e] += __logf(f); cv[t][e] = cum[e];
;         }
;         omp[t] = cvt_pk_bf16(omv[0], omv[1]);
;         if ((t & 1) == 0) { itp[0][t >> 1] = ii & 0xffffu; itp[1][t >> 1] = ii >> 16; }
;         else { itp[0][t >> 1] |= ii << 16; itp[1][t >> 1] |= ii & 0xffff0000u; }
	v_mul_f32_e32 v16, 0x3f317217, v15
	v_fma_f32 v16, v15, s25, -v16
	v_fmac_f32_e32 v16, 0x3377d1cf, v15
	v_fmac_f32_e32 v16, 0x3f317217, v15
	v_cmp_lt_f32_e64 s[6:7], |v15|, s26
	s_nop 1
	v_cndmask_b32_e64 v15, v15, v16, s[6:7]
	v_cndmask_b32_e32 v16, 0, v216, vcc
	v_sub_f32_e32 v15, v15, v16
	v_add_f32_e32 v63, v61, v15
	v_fma_f32 v15, v39, v69, v35
	v_cmp_gt_f32_e32 vcc, s24, v15
	v_pk_mul_f32 v[16:17], v[64:65], v[68:69]
	s_nop 0
	v_cndmask_b32_e64 v18, 0, 32, vcc
	v_ldexp_f32 v15, v15, v18
	v_log_f32_e32 v15, v15
	v_pk_mul_f32 v[16:17], v[38:39], v[16:17]
	v_mul_f32_e32 v18, 0x3f317217, v15
	v_fma_f32 v18, v15, s25, -v18
	v_fmac_f32_e32 v18, 0x3377d1cf, v15
	v_fmac_f32_e32 v18, 0x3f317217, v15
	v_cmp_lt_f32_e64 s[6:7], |v15|, s26
	v_cvt_pk_bf16_f32 v68, v16, v17
	v_and_b32_e32 v181, 0xffff0000, v68
	v_cndmask_b32_e64 v15, v15, v18, s[6:7]
	v_cndmask_b32_e32 v18, 0, v216, vcc
	v_sub_f32_e32 v15, v15, v18
	v_add_f32_e32 v64, v62, v15
	v_fma_f32 v15, v38, v58, v34
	v_cmp_gt_f32_e32 vcc, s24, v15
	s_nop 1
	v_cndmask_b32_e64 v16, 0, 32, vcc
	v_ldexp_f32 v15, v15, v16
	v_log_f32_e32 v15, v15
	s_nop 0
	v_mul_f32_e32 v16, 0x3f317217, v15
	v_fma_f32 v16, v15, s25, -v16
	v_fmac_f32_e32 v16, 0x3377d1cf, v15
	v_fmac_f32_e32 v16, 0x3f317217, v15
	v_cmp_lt_f32_e64 s[6:7], |v15|, s26
	s_nop 1
	v_cndmask_b32_e64 v15, v15, v16, s[6:7]
	v_cndmask_b32_e32 v16, 0, v216, vcc
	v_sub_f32_e32 v15, v15, v16
	v_add_f32_e32 v84, v63, v15
	v_fma_f32 v15, v39, v59, v35
	v_cmp_gt_f32_e32 vcc, s24, v15
	v_pk_mul_f32 v[16:17], v[56:57], v[58:59]
	s_nop 0
	v_cndmask_b32_e64 v18, 0, 32, vcc
	v_ldexp_f32 v15, v15, v18
	v_log_f32_e32 v15, v15
	v_pk_mul_f32 v[16:17], v[38:39], v[16:17]
	v_mul_f32_e32 v18, 0x3f317217, v15
	v_fma_f32 v18, v15, s25, -v18
	v_fmac_f32_e32 v18, 0x3377d1cf, v15
	v_fmac_f32_e32 v18, 0x3f317217, v15
	v_cmp_lt_f32_e64 s[6:7], |v15|, s26
	v_cvt_pk_bf16_f32 v69, v16, v17
	v_and_b32_e32 v183, 0xffff0000, v69
	v_cndmask_b32_e64 v15, v15, v18, s[6:7]
	v_cndmask_b32_e32 v18, 0, v216, vcc
	v_add_co_u32_e32 v16, vcc, s27, v36
	v_sub_f32_e32 v15, v15, v18
	s_nop 0
	v_addc_co_u32_e32 v17, vcc, 0, v37, vcc
	s_nop 0
	v_add_co_u32_e32 v18, vcc, s28, v36
	v_add_f32_e32 v85, v64, v15
	s_nop 0
	v_addc_co_u32_e32 v19, vcc, 0, v37, vcc
	s_nop 0
	v_lshl_or_b32 v15, v98, 16, v11
	s_nop 0
	v_and_or_b32 v11, v98, s16, v97
	s_waitcnt vmcnt(47)
	v_lshlrev_b32_e32 v18, 16, v195
	v_mul_f32_e32 v18, 0xbfb8aa3b, v18
	v_exp_f32_e32 v18, v18
	v_and_b32_e32 v19, 0xffff0000, v195
	v_mul_f32_e32 v19, 0xbfb8aa3b, v19
	v_exp_f32_e32 v19, v19
	v_add_f32_e32 v20, 1.0, v18
	v_rcp_f32_e32 v20, v20
	s_nop 0
	v_fma_f32 v21, v38, v20, v34
	v_cmp_gt_f32_e32 vcc, s24, v21
	s_nop 1
	v_cndmask_b32_e64 v22, 0, 32, vcc
	v_ldexp_f32 v21, v21, v22
	v_log_f32_e32 v21, v21
	s_nop 0
	v_mul_f32_e32 v22, 0x3f317217, v21
	v_fma_f32 v22, v21, s25, -v22
	v_fmac_f32_e32 v22, 0x3377d1cf, v21
	v_fmac_f32_e32 v22, 0x3f317217, v21
	v_cmp_lt_f32_e64 s[6:7], |v21|, s26
	s_nop 1
	v_cndmask_b32_e64 v21, v21, v22, s[6:7]
	v_cndmask_b32_e32 v22, 0, v216, vcc
	v_sub_f32_e32 v21, v21, v22
	v_add_f32_e32 v56, v84, v21
	v_add_f32_e32 v21, 1.0, v19
	v_rcp_f32_e32 v21, v21
	s_nop 0
	v_fma_f32 v22, v39, v21, v35
	v_cmp_gt_f32_e32 vcc, s24, v22
	v_pk_mul_f32 v[18:19], v[18:19], v[20:21]
	s_nop 0
	v_cndmask_b32_e64 v20, 0, 32, vcc
	v_ldexp_f32 v20, v22, v20
	v_log_f32_e32 v20, v20
	v_pk_mul_f32 v[18:19], v[38:39], v[18:19]
	v_mul_f32_e32 v21, 0x3f317217, v20
	v_fma_f32 v21, v20, s25, -v21
	v_fmac_f32_e32 v21, 0x3377d1cf, v20
	v_fmac_f32_e32 v21, 0x3f317217, v20
	v_cmp_lt_f32_e64 s[6:7], |v20|, s26
	v_cvt_pk_bf16_f32 v74, v18, v19
	s_nop 0
	v_cndmask_b32_e64 v20, v20, v21, s[6:7]
	v_cndmask_b32_e32 v21, 0, v216, vcc
	v_sub_f32_e32 v20, v20, v21
	v_add_f32_e32 v57, v85, v20
	s_waitcnt vmcnt(45)
	v_and_b32_e32 v20, 0xffff, v189
	v_lshrrev_b32_e32 v21, 16, v189
	v_add_co_u32_e32 v16, vcc, s29, v36
	s_nop 1
	v_addc_co_u32_e32 v17, vcc, 0, v37, vcc
	v_add_co_u32_e32 v18, vcc, s30, v36
	s_nop 0
	s_nop 0
	v_addc_co_u32_e32 v19, vcc, 0, v37, vcc
	s_nop 0
	s_nop 0
	s_nop 0
	s_waitcnt vmcnt(44)
	v_lshl_or_b32 v20, v186, 16, v20
	s_waitcnt vmcnt(42)
	v_and_b32_e32 v17, 0xffff0000, v187
	v_lshlrev_b32_e32 v16, 16, v187
	v_mul_f32_e32 v16, 0xbfb8aa3b, v16
	v_exp_f32_e32 v16, v16
	v_mul_f32_e32 v17, 0xbfb8aa3b, v17
	v_exp_f32_e32 v17, v17
	v_add_f32_e32 v18, 1.0, v16
	v_rcp_f32_e32 v18, v18
	s_nop 0
	v_fma_f32 v19, v38, v18, v34
	v_cmp_gt_f32_e32 vcc, s24, v19
	s_nop 1
	v_cndmask_b32_e64 v23, 0, 32, vcc
	v_ldexp_f32 v19, v19, v23
	v_log_f32_e32 v19, v19
	s_nop 0
	v_mul_f32_e32 v23, 0x3f317217, v19
	v_fma_f32 v23, v19, s25, -v23
	v_fmac_f32_e32 v23, 0x3377d1cf, v19
	v_fmac_f32_e32 v23, 0x3f317217, v19
	v_cmp_lt_f32_e64 s[6:7], |v19|, s26
	s_nop 1
	v_cndmask_b32_e64 v19, v19, v23, s[6:7]
	v_cndmask_b32_e32 v23, 0, v216, vcc
	v_sub_f32_e32 v19, v19, v23
	v_add_f32_e32 v58, v56, v19
	v_add_f32_e32 v19, 1.0, v17
	v_rcp_f32_e32 v19, v19
	s_nop 0
	v_fma_f32 v23, v39, v19, v35
	v_cmp_gt_f32_e32 vcc, s24, v23
	v_pk_mul_f32 v[16:17], v[16:17], v[18:19]
	s_nop 0
	v_cndmask_b32_e64 v18, 0, 32, vcc
	v_ldexp_f32 v18, v23, v18
	v_log_f32_e32 v18, v18
	v_pk_mul_f32 v[16:17], v[38:39], v[16:17]
	v_mul_f32_e32 v19, 0x3f317217, v18
	v_fma_f32 v19, v18, s25, -v19
	v_fmac_f32_e32 v19, 0x3377d1cf, v18
	v_fmac_f32_e32 v19, 0x3f317217, v18
	v_cmp_lt_f32_e64 s[6:7], |v18|, s26
	v_cvt_pk_bf16_f32 v76, v16, v17
	v_and_or_b32 v16, v186, s16, v21
	v_cndmask_b32_e64 v18, v18, v19, s[6:7]
	v_cndmask_b32_e32 v19, 0, v216, vcc
	v_sub_f32_e32 v18, v18, v19
	v_add_f32_e32 v59, v57, v18
	v_add_co_u32_e32 v18, vcc, s31, v36
	v_lshlrev_b32_e32 v186, 16, v76
	s_nop 0
	v_addc_co_u32_e32 v19, vcc, 0, v37, vcc
	s_nop 0
	v_add_co_u32_e32 v18, vcc, s34, v36
	v_and_b32_e32 v187, 0xffff0000, v76
	s_nop 0
	v_addc_co_u32_e32 v19, vcc, 0, v37, vcc
	s_nop 0
	s_nop 0
	s_nop 0
	s_waitcnt vmcnt(39)
; __device__ __forceinline__ unsigned cvt_pk_bf16(float lo, float hi) { const f32x2_cv v = {lo, hi}; return __builtin_bit_cast(unsigned, __builtin_convertvector(v, bf16x2_cv)); }
; __device__ __forceinline__ float bf_lo(unsigned u) { return __uint_as_float(u << 16); }
; __device__ __forceinline__ float bf_hi(unsigned u) { return __uint_as_float(u & 0xffff0000u); }
; __device__ __forceinline__ void hgrn_prep_item(const bf16_t* Z, const float* lbl, unsigned char* REC, int cidx, int h, LAS unsigned char* wl, int lane) {
;     ...
;     for (int t = 0; t < 32; ++t) {
;         const unsigned ff = *(const unsigned*)(zr + (size_t)t * DIN + ZHF), ii = *(const unsigned*)(zr + (size_t)t * DIN + ZHI);
;         qraw[t] = *(const unsigned*)(zr + (size_t)t * DIN + ZHQ); float omv[2];
; #pragma unroll
;         for (int e = 0; e < 2; ++e) {
;             const float fl = e ? bf_hi(ff) : bf_lo(ff);
;             const float ex = __expf(-fl), sg = __builtin_amdgcn_rcpf(1.f + ex);
;             const float f = lb[e] + omlb[e] * sg;
;             omv[e] = omlb[e] * (ex * sg);
;             cum[e] += __logf(f); cv[t][e] = cum[e];
;         }
;         omp[t] = cvt_pk_bf16(omv[0], omv[1]);
;         if ((t & 1) == 0) { itp[0][t >> 1] = ii & 0xffffu; itp[1][t >> 1] = ii >> 16; }
;         else { itp[0][t >> 1] |= ii << 16; itp[1][t >> 1] |= ii & 0xffff0000u; }
	v_and_b32_e32 v19, 0xffff0000, v188
	v_lshlrev_b32_e32 v18, 16, v188
	v_mul_f32_e32 v18, 0xbfb8aa3b, v18
	v_exp_f32_e32 v18, v18
	v_mul_f32_e32 v19, 0xbfb8aa3b, v19
	v_exp_f32_e32 v19, v19
	v_add_f32_e32 v21, 1.0, v18
	v_rcp_f32_e32 v22, v21
	s_nop 0
	v_fma_f32 v21, v38, v22, v34
	v_cmp_gt_f32_e32 vcc, s24, v21
	s_nop 1
	v_cndmask_b32_e64 v23, 0, 32, vcc
	v_ldexp_f32 v21, v21, v23
	v_log_f32_e32 v21, v21
	s_nop 0
	v_mul_f32_e32 v23, 0x3f317217, v21
	v_fma_f32 v23, v21, s25, -v23
	v_fmac_f32_e32 v23, 0x3377d1cf, v21
	v_fmac_f32_e32 v23, 0x3f317217, v21
	v_cmp_lt_f32_e64 s[6:7], |v21|, s26
	s_nop 1
	v_cndmask_b32_e64 v21, v21, v23, s[6:7]
	v_cndmask_b32_e32 v23, 0, v216, vcc
	v_sub_f32_e32 v21, v21, v23
	v_add_f32_e32 v65, v58, v21
	v_add_f32_e32 v21, 1.0, v19
	v_rcp_f32_e32 v23, v21
	s_nop 0
	v_fma_f32 v21, v39, v23, v35
	v_cmp_gt_f32_e32 vcc, s24, v21
	v_pk_mul_f32 v[18:19], v[18:19], v[22:23]
	s_nop 0
	v_cndmask_b32_e64 v22, 0, 32, vcc
	v_ldexp_f32 v21, v21, v22
	v_log_f32_e32 v21, v21
	v_pk_mul_f32 v[18:19], v[38:39], v[18:19]
	v_mul_f32_e32 v22, 0x3f317217, v21
	v_fma_f32 v22, v21, s25, -v22
	v_fmac_f32_e32 v22, 0x3377d1cf, v21
	v_fmac_f32_e32 v22, 0x3f317217, v21
	v_cmp_lt_f32_e64 s[6:7], |v21|, s26
	v_cvt_pk_bf16_f32 v78, v18, v19
	v_lshlrev_b32_e32 v188, 16, v78
	v_cndmask_b32_e64 v21, v21, v22, s[6:7]
	v_cndmask_b32_e32 v22, 0, v216, vcc
	v_add_co_u32_e32 v18, vcc, s35, v36
	s_mov_b32 s6, 0x35000
	s_nop 0
	v_addc_co_u32_e32 v19, vcc, 0, v37, vcc
	s_nop 0
	v_add_co_u32_e32 v18, vcc, s6, v36
	v_sub_f32_e32 v21, v21, v22
	s_nop 0
	v_addc_co_u32_e32 v19, vcc, 0, v37, vcc
	s_nop 0
	s_nop 0
	s_nop 0
	v_add_f32_e32 v86, v59, v21
	v_and_b32_e32 v21, 0xffff, v192
	v_lshrrev_b32_e32 v17, 16, v192
	v_and_b32_e32 v189, 0xffff0000, v78
	s_waitcnt vmcnt(38)
	v_lshl_or_b32 v21, v191, 16, v21
	v_and_or_b32 v17, v191, s16, v17
	s_waitcnt vmcnt(36)
	v_and_b32_e32 v19, 0xffff0000, v190
	v_lshlrev_b32_e32 v18, 16, v190
	v_mul_f32_e32 v18, 0xbfb8aa3b, v18
	v_exp_f32_e32 v18, v18
	v_mul_f32_e32 v19, 0xbfb8aa3b, v19
	v_exp_f32_e32 v19, v19
	v_add_f32_e32 v22, 1.0, v18
	v_rcp_f32_e32 v22, v22
	s_nop 0
	v_fma_f32 v23, v38, v22, v34
	v_cmp_gt_f32_e32 vcc, s24, v23
	s_nop 1
	v_cndmask_b32_e64 v25, 0, 32, vcc
	v_ldexp_f32 v23, v23, v25
	v_log_f32_e32 v23, v23
	s_nop 0
	v_mul_f32_e32 v25, 0x3f317217, v23
	v_fma_f32 v25, v23, s25, -v25
	v_fmac_f32_e32 v25, 0x3377d1cf, v23
	v_fmac_f32_e32 v25, 0x3f317217, v23
	v_cmp_lt_f32_e64 s[6:7], |v23|, s26
	s_nop 1
	v_cndmask_b32_e64 v23, v23, v25, s[6:7]
	v_cndmask_b32_e32 v25, 0, v216, vcc
	v_sub_f32_e32 v23, v23, v25
	v_add_f32_e32 v87, v65, v23
	v_add_f32_e32 v23, 1.0, v19
	v_rcp_f32_e32 v23, v23
	s_nop 0
	v_fma_f32 v25, v39, v23, v35
	v_cmp_gt_f32_e32 vcc, s24, v25
	v_pk_mul_f32 v[18:19], v[18:19], v[22:23]
	s_nop 0
	v_cndmask_b32_e64 v22, 0, 32, vcc
	v_ldexp_f32 v22, v25, v22
	v_log_f32_e32 v22, v22
	v_pk_mul_f32 v[18:19], v[38:39], v[18:19]
	v_mul_f32_e32 v23, 0x3f317217, v22
	v_fma_f32 v23, v22, s25, -v23
	v_fmac_f32_e32 v23, 0x3377d1cf, v22
	v_fmac_f32_e32 v23, 0x3f317217, v22
	v_cmp_lt_f32_e64 s[6:7], |v22|, s26
	v_cvt_pk_bf16_f32 v80, v18, v19
	v_lshlrev_b32_e32 v190, 16, v80
	v_cndmask_b32_e64 v22, v22, v23, s[6:7]
	v_cndmask_b32_e32 v23, 0, v216, vcc
	v_add_co_u32_e32 v18, vcc, s36, v36
	v_sub_f32_e32 v22, v22, v23
	s_nop 0
	v_addc_co_u32_e32 v19, vcc, 0, v37, vcc
	v_add_f32_e32 v97, v86, v22
	v_add_co_u32_e32 v22, vcc, s37, v36
	s_nop 0
	s_nop 0
	v_addc_co_u32_e32 v23, vcc, 0, v37, vcc
	s_nop 0
	s_nop 0
	s_nop 0
	v_and_b32_e32 v191, 0xffff0000, v80
	s_waitcnt vmcnt(33)
	v_and_b32_e32 v19, 0xffff0000, v193
	v_lshlrev_b32_e32 v18, 16, v193
	v_mul_f32_e32 v18, 0xbfb8aa3b, v18
	v_exp_f32_e32 v18, v18
	v_mul_f32_e32 v19, 0xbfb8aa3b, v19
	v_exp_f32_e32 v19, v19
	v_add_f32_e32 v22, 1.0, v18
	v_rcp_f32_e32 v22, v22
	s_nop 0
	v_fma_f32 v23, v38, v22, v34
	v_cmp_gt_f32_e32 vcc, s24, v23
	s_nop 1
	v_cndmask_b32_e64 v25, 0, 32, vcc
	v_ldexp_f32 v23, v23, v25
	v_log_f32_e32 v23, v23
	s_nop 0
	v_mul_f32_e32 v25, 0x3f317217, v23
	v_fma_f32 v25, v23, s25, -v25
	v_fmac_f32_e32 v25, 0x3377d1cf, v23
	v_fmac_f32_e32 v25, 0x3f317217, v23
	v_cmp_lt_f32_e64 s[6:7], |v23|, s26
	s_nop 1
	v_cndmask_b32_e64 v23, v23, v25, s[6:7]
	v_cndmask_b32_e32 v25, 0, v216, vcc
	v_sub_f32_e32 v23, v23, v25
	v_add_f32_e32 v98, v87, v23
	v_add_f32_e32 v23, 1.0, v19
	v_rcp_f32_e32 v23, v23
	s_nop 0
	v_fma_f32 v25, v39, v23, v35
	v_cmp_gt_f32_e32 vcc, s24, v25
	v_pk_mul_f32 v[18:19], v[18:19], v[22:23]
	s_nop 0
	v_cndmask_b32_e64 v22, 0, 32, vcc
	v_ldexp_f32 v22, v25, v22
	v_log_f32_e32 v22, v22
	v_pk_mul_f32 v[18:19], v[38:39], v[18:19]
	v_and_b32_e32 v25, 0xffff, v99
	v_cvt_pk_bf16_f32 v193, v18, v19
	v_mul_f32_e32 v23, 0x3f317217, v22
	v_fma_f32 v23, v22, s25, -v23
	v_fmac_f32_e32 v23, 0x3377d1cf, v22
	v_fmac_f32_e32 v23, 0x3f317217, v22
	v_cmp_lt_f32_e64 s[6:7], |v22|, s26
	v_lshrrev_b32_e32 v24, 16, v99
	v_lshlrev_b32_e32 v192, 16, v193
	v_cndmask_b32_e64 v22, v22, v23, s[6:7]
	v_cndmask_b32_e32 v23, 0, v216, vcc
	v_add_co_u32_e32 v18, vcc, s38, v36
	v_sub_f32_e32 v22, v22, v23
	s_nop 0
	v_addc_co_u32_e32 v19, vcc, 0, v37, vcc
	v_add_f32_e32 v99, v97, v22
	v_add_co_u32_e32 v22, vcc, s39, v36
	s_nop 0
	s_nop 0
	v_addc_co_u32_e32 v23, vcc, 0, v37, vcc
	s_nop 0
	s_nop 0
	s_nop 0
	v_and_b32_e32 v193, 0xffff0000, v193
	s_waitcnt vmcnt(30)
; __device__ __forceinline__ unsigned cvt_pk_bf16(float lo, float hi) { const f32x2_cv v = {lo, hi}; return __builtin_bit_cast(unsigned, __builtin_convertvector(v, bf16x2_cv)); }
; __device__ __forceinline__ float bf_lo(unsigned u) { return __uint_as_float(u << 16); }
; __device__ __forceinline__ float bf_hi(unsigned u) { return __uint_as_float(u & 0xffff0000u); }
; __device__ __forceinline__ void hgrn_prep_item(const bf16_t* Z, const float* lbl, unsigned char* REC, int cidx, int h, LAS unsigned char* wl, int lane) {
;     ...
;     for (int t = 0; t < 32; ++t) {
;         const unsigned ff = *(const unsigned*)(zr + (size_t)t * DIN + ZHF), ii = *(const unsigned*)(zr + (size_t)t * DIN + ZHI);
;         qraw[t] = *(const unsigned*)(zr + (size_t)t * DIN + ZHQ); float omv[2];
; #pragma unroll
;         for (int e = 0; e < 2; ++e) {
;             const float fl = e ? bf_hi(ff) : bf_lo(ff);
;             const float ex = __expf(-fl), sg = __builtin_amdgcn_rcpf(1.f + ex);
;             const float f = lb[e] + omlb[e] * sg;
;             omv[e] = omlb[e] * (ex * sg);
;             cum[e] += __logf(f); cv[t][e] = cum[e];
;         }
;         omp[t] = cvt_pk_bf16(omv[0], omv[1]);
;         if ((t & 1) == 0) { itp[0][t >> 1] = ii & 0xffffu; itp[1][t >> 1] = ii >> 16; }
;         else { itp[0][t >> 1] |= ii << 16; itp[1][t >> 1] |= ii & 0xffff0000u; }
	v_and_b32_e32 v19, 0xffff0000, v100
	v_lshlrev_b32_e32 v18, 16, v100
	v_mul_f32_e32 v18, 0xbfb8aa3b, v18
	v_exp_f32_e32 v18, v18
	v_mul_f32_e32 v19, 0xbfb8aa3b, v19
	v_exp_f32_e32 v19, v19
	v_add_f32_e32 v22, 1.0, v18
	v_rcp_f32_e32 v22, v22
	s_nop 0
	v_fma_f32 v23, v38, v22, v34
	v_cmp_gt_f32_e32 vcc, s24, v23
	s_nop 1
	v_cndmask_b32_e64 v27, 0, 32, vcc
	v_ldexp_f32 v23, v23, v27
	v_log_f32_e32 v23, v23
	s_nop 0
	v_mul_f32_e32 v27, 0x3f317217, v23
	v_fma_f32 v27, v23, s25, -v27
	v_fmac_f32_e32 v27, 0x3377d1cf, v23
	v_fmac_f32_e32 v27, 0x3f317217, v23
	v_cmp_lt_f32_e64 s[6:7], |v23|, s26
	s_nop 1
	v_cndmask_b32_e64 v23, v23, v27, s[6:7]
	v_cndmask_b32_e32 v27, 0, v216, vcc
	v_sub_f32_e32 v23, v23, v27
	v_add_f32_e32 v100, v98, v23
	v_add_f32_e32 v23, 1.0, v19
	v_rcp_f32_e32 v23, v23
	s_nop 0
	v_fma_f32 v27, v39, v23, v35
	v_cmp_gt_f32_e32 vcc, s24, v27
	v_pk_mul_f32 v[18:19], v[18:19], v[22:23]
	s_nop 0
	v_cndmask_b32_e64 v22, 0, 32, vcc
	v_ldexp_f32 v22, v27, v22
	v_log_f32_e32 v22, v22
	v_pk_mul_f32 v[18:19], v[38:39], v[18:19]
	v_mul_f32_e32 v23, 0x3f317217, v22
	v_fma_f32 v23, v22, s25, -v23
	v_fmac_f32_e32 v23, 0x3377d1cf, v22
	v_fmac_f32_e32 v23, 0x3f317217, v22
	v_cmp_lt_f32_e64 s[6:7], |v22|, s26
	v_cvt_pk_bf16_f32 v195, v18, v19
	v_and_or_b32 v18, v197, s16, v24
	v_cndmask_b32_e64 v22, v22, v23, s[6:7]
	v_cndmask_b32_e32 v23, 0, v216, vcc
	v_sub_f32_e32 v22, v22, v23
	v_add_co_u32_e32 v24, vcc, s40, v36
	v_add_f32_e32 v101, v99, v22
	v_lshl_or_b32 v22, v197, 16, v25
	v_addc_co_u32_e32 v25, vcc, 0, v37, vcc
	s_nop 0
	v_add_co_u32_e32 v24, vcc, s41, v36
	s_nop 1
	v_addc_co_u32_e32 v25, vcc, 0, v37, vcc
	s_nop 0
	s_nop 0
	s_waitcnt vmcnt(27)
	v_and_b32_e32 v25, 0xffff0000, v102
	v_lshlrev_b32_e32 v23, 16, v102
	v_mul_f32_e32 v23, 0xbfb8aa3b, v23
	v_exp_f32_e32 v24, v23
	s_nop 0
	v_add_f32_e32 v23, 1.0, v24
	v_rcp_f32_e32 v26, v23
	s_nop 0
	v_fma_f32 v23, v38, v26, v34
	v_cmp_gt_f32_e32 vcc, s24, v23
	s_nop 1
	v_cndmask_b32_e64 v27, 0, 32, vcc
	v_ldexp_f32 v23, v23, v27
	v_log_f32_e32 v23, v23
	s_nop 0
	v_mul_f32_e32 v27, 0x3f317217, v23
	v_fma_f32 v27, v23, s25, -v27
	v_fmac_f32_e32 v27, 0x3377d1cf, v23
	v_fmac_f32_e32 v27, 0x3f317217, v23
	v_cmp_lt_f32_e64 s[6:7], |v23|, s26
	s_nop 1
	v_cndmask_b32_e64 v23, v23, v27, s[6:7]
	v_cndmask_b32_e32 v27, 0, v216, vcc
	v_sub_f32_e32 v23, v23, v27
	v_add_f32_e32 v102, v100, v23
	v_mul_f32_e32 v23, 0xbfb8aa3b, v25
	v_exp_f32_e32 v25, v23
	s_nop 0
	v_add_f32_e32 v23, 1.0, v25
	v_rcp_f32_e32 v27, v23
	s_nop 0
	v_fma_f32 v23, v39, v27, v35
	v_cmp_gt_f32_e32 vcc, s24, v23
	v_pk_mul_f32 v[24:25], v[24:25], v[26:27]
	s_nop 0
	v_cndmask_b32_e64 v26, 0, 32, vcc
	v_ldexp_f32 v23, v23, v26
	v_log_f32_e32 v23, v23
	v_pk_mul_f32 v[24:25], v[38:39], v[24:25]
	v_mul_f32_e32 v26, 0x3f317217, v23
	v_fma_f32 v26, v23, s25, -v26
	v_fmac_f32_e32 v26, 0x3377d1cf, v23
	v_fmac_f32_e32 v26, 0x3f317217, v23
	v_cmp_lt_f32_e64 s[6:7], |v23|, s26
	v_cvt_pk_bf16_f32 v197, v24, v25
	s_nop 0
	v_cndmask_b32_e64 v23, v23, v26, s[6:7]
	v_cndmask_b32_e32 v26, 0, v216, vcc
	v_add_co_u32_e32 v24, vcc, s42, v36
	v_sub_f32_e32 v23, v23, v26
	s_nop 0
	v_addc_co_u32_e32 v25, vcc, 0, v37, vcc
	s_nop 0
	v_add_co_u32_e32 v24, vcc, s43, v36
	v_add_f32_e32 v103, v101, v23
	s_nop 0
	v_addc_co_u32_e32 v25, vcc, 0, v37, vcc
	s_nop 0
	s_nop 0
	s_nop 0
	v_and_b32_e32 v23, 0xffff, v105
	v_lshrrev_b32_e32 v19, 16, v105
	s_waitcnt vmcnt(26)
	v_lshl_or_b32 v23, v199, 16, v23
	v_and_or_b32 v19, v199, s16, v19
	s_waitcnt vmcnt(24)
	v_and_b32_e32 v25, 0xffff0000, v104
	v_lshlrev_b32_e32 v24, 16, v104
	v_mul_f32_e32 v24, 0xbfb8aa3b, v24
	v_exp_f32_e32 v24, v24
	v_mul_f32_e32 v25, 0xbfb8aa3b, v25
	v_exp_f32_e32 v25, v25
	v_add_f32_e32 v26, 1.0, v24
	v_rcp_f32_e32 v26, v26
	s_nop 0
	v_fma_f32 v27, v38, v26, v34
	v_cmp_gt_f32_e32 vcc, s24, v27
	s_nop 1
	v_cndmask_b32_e64 v29, 0, 32, vcc
	v_ldexp_f32 v27, v27, v29
	v_log_f32_e32 v27, v27
	s_nop 0
	v_mul_f32_e32 v29, 0x3f317217, v27
	v_fma_f32 v29, v27, s25, -v29
	v_fmac_f32_e32 v29, 0x3377d1cf, v27
	v_fmac_f32_e32 v29, 0x3f317217, v27
	v_cmp_lt_f32_e64 s[6:7], |v27|, s26
	s_nop 1
	v_cndmask_b32_e64 v27, v27, v29, s[6:7]
	v_cndmask_b32_e32 v29, 0, v216, vcc
	v_sub_f32_e32 v27, v27, v29
	v_add_f32_e32 v104, v102, v27
	v_add_f32_e32 v27, 1.0, v25
	v_rcp_f32_e32 v27, v27
	s_nop 0
	v_fma_f32 v29, v39, v27, v35
	v_cmp_gt_f32_e32 vcc, s24, v29
	v_pk_mul_f32 v[24:25], v[24:25], v[26:27]
	s_nop 0
	v_cndmask_b32_e64 v26, 0, 32, vcc
	v_ldexp_f32 v26, v29, v26
	v_log_f32_e32 v26, v26
	v_pk_mul_f32 v[24:25], v[38:39], v[24:25]
	v_mul_f32_e32 v27, 0x3f317217, v26
	v_fma_f32 v27, v26, s25, -v27
	v_fmac_f32_e32 v27, 0x3377d1cf, v26
	v_fmac_f32_e32 v27, 0x3f317217, v26
	v_cmp_lt_f32_e64 s[6:7], |v26|, s26
	v_cvt_pk_bf16_f32 v199, v24, v25
	s_nop 0
	v_cndmask_b32_e64 v26, v26, v27, s[6:7]
	v_cndmask_b32_e32 v27, 0, v216, vcc
	v_add_co_u32_e32 v24, vcc, s44, v36
	v_sub_f32_e32 v26, v26, v27
	s_nop 0
	v_addc_co_u32_e32 v25, vcc, 0, v37, vcc
	v_add_f32_e32 v105, v103, v26
	v_add_co_u32_e32 v26, vcc, s45, v36
	s_nop 0
	s_nop 0
	v_addc_co_u32_e32 v27, vcc, 0, v37, vcc
	s_nop 0
	s_nop 0
	s_nop 0
	s_waitcnt vmcnt(23)
	v_lshrrev_b32_e32 v30, 16, v202
	s_waitcnt vmcnt(21)
; __device__ __forceinline__ unsigned cvt_pk_bf16(float lo, float hi) { const f32x2_cv v = {lo, hi}; return __builtin_bit_cast(unsigned, __builtin_convertvector(v, bf16x2_cv)); }
; __device__ __forceinline__ float bf_lo(unsigned u) { return __uint_as_float(u << 16); }
; __device__ __forceinline__ float bf_hi(unsigned u) { return __uint_as_float(u & 0xffff0000u); }
; __device__ __forceinline__ void hgrn_prep_item(const bf16_t* Z, const float* lbl, unsigned char* REC, int cidx, int h, LAS unsigned char* wl, int lane) {
;     ...
;     for (int t = 0; t < 32; ++t) {
;         const unsigned ff = *(const unsigned*)(zr + (size_t)t * DIN + ZHF), ii = *(const unsigned*)(zr + (size_t)t * DIN + ZHI);
;         qraw[t] = *(const unsigned*)(zr + (size_t)t * DIN + ZHQ); float omv[2];
; #pragma unroll
;         for (int e = 0; e < 2; ++e) {
;             const float fl = e ? bf_hi(ff) : bf_lo(ff);
;             const float ex = __expf(-fl), sg = __builtin_amdgcn_rcpf(1.f + ex);
;             const float f = lb[e] + omlb[e] * sg;
;             omv[e] = omlb[e] * (ex * sg);
;             cum[e] += __logf(f); cv[t][e] = cum[e];
;         }
;         omp[t] = cvt_pk_bf16(omv[0], omv[1]);
;         if ((t & 1) == 0) { itp[0][t >> 1] = ii & 0xffffu; itp[1][t >> 1] = ii >> 16; }
;         else { itp[0][t >> 1] |= ii << 16; itp[1][t >> 1] |= ii & 0xffff0000u; }
	v_and_b32_e32 v25, 0xffff0000, v106
	v_lshlrev_b32_e32 v24, 16, v106
	v_mul_f32_e32 v24, 0xbfb8aa3b, v24
	v_exp_f32_e32 v24, v24
	v_mul_f32_e32 v25, 0xbfb8aa3b, v25
	v_exp_f32_e32 v25, v25
	v_add_f32_e32 v26, 1.0, v24
	v_rcp_f32_e32 v26, v26
	s_nop 0
	v_fma_f32 v27, v38, v26, v34
	v_cmp_gt_f32_e32 vcc, s24, v27
	s_nop 1
	v_cndmask_b32_e64 v29, 0, 32, vcc
	v_ldexp_f32 v27, v27, v29
	v_log_f32_e32 v27, v27
	s_nop 0
	v_mul_f32_e32 v29, 0x3f317217, v27
	v_fma_f32 v29, v27, s25, -v29
	v_fmac_f32_e32 v29, 0x3377d1cf, v27
	v_fmac_f32_e32 v29, 0x3f317217, v27
	v_cmp_lt_f32_e64 s[6:7], |v27|, s26
	s_nop 1
	v_cndmask_b32_e64 v27, v27, v29, s[6:7]
	v_cndmask_b32_e32 v29, 0, v216, vcc
	v_sub_f32_e32 v27, v27, v29
	v_add_f32_e32 v106, v104, v27
	v_add_f32_e32 v27, 1.0, v25
	v_rcp_f32_e32 v27, v27
	s_nop 0
	v_fma_f32 v29, v39, v27, v35
	v_cmp_gt_f32_e32 vcc, s24, v29
	v_pk_mul_f32 v[24:25], v[24:25], v[26:27]
	s_nop 0
	v_cndmask_b32_e64 v26, 0, 32, vcc
	v_ldexp_f32 v26, v29, v26
	v_log_f32_e32 v26, v26
	v_pk_mul_f32 v[24:25], v[38:39], v[24:25]
	v_and_b32_e32 v29, 0xffff, v202
	v_cvt_pk_bf16_f32 v201, v24, v25
	v_mul_f32_e32 v27, 0x3f317217, v26
	v_fma_f32 v27, v26, s25, -v27
	v_fmac_f32_e32 v27, 0x3377d1cf, v26
	v_fmac_f32_e32 v27, 0x3f317217, v26
	v_cmp_lt_f32_e64 s[6:7], |v26|, s26
	v_lshlrev_b32_e32 v202, 16, v201
	v_and_b32_e32 v203, 0xffff0000, v201
	v_cndmask_b32_e64 v26, v26, v27, s[6:7]
	v_cndmask_b32_e32 v27, 0, v216, vcc
	v_add_co_u32_e32 v24, vcc, s47, v36
	v_sub_f32_e32 v26, v26, v27
	s_nop 0
	v_addc_co_u32_e32 v25, vcc, 0, v37, vcc
	v_add_f32_e32 v107, v105, v26
	v_add_co_u32_e32 v26, vcc, s48, v36
	s_nop 0
	s_nop 0
	v_addc_co_u32_e32 v27, vcc, 0, v37, vcc
	s_nop 0
	s_nop 0
	s_nop 0
	s_waitcnt vmcnt(18)
	v_and_b32_e32 v25, 0xffff0000, v108
	v_lshlrev_b32_e32 v24, 16, v108
	v_mul_f32_e32 v24, 0xbfb8aa3b, v24
	v_exp_f32_e32 v24, v24
	v_mul_f32_e32 v25, 0xbfb8aa3b, v25
	v_exp_f32_e32 v25, v25
	v_add_f32_e32 v26, 1.0, v24
	v_rcp_f32_e32 v26, v26
	s_nop 0
	v_fma_f32 v27, v38, v26, v34
	v_cmp_gt_f32_e32 vcc, s24, v27
	s_nop 1
	v_cndmask_b32_e64 v28, 0, 32, vcc
	v_ldexp_f32 v27, v27, v28
	v_log_f32_e32 v27, v27
	s_nop 0
	v_mul_f32_e32 v28, 0x3f317217, v27
	v_fma_f32 v28, v27, s25, -v28
	v_fmac_f32_e32 v28, 0x3377d1cf, v27
	v_fmac_f32_e32 v28, 0x3f317217, v27
	v_cmp_lt_f32_e64 s[6:7], |v27|, s26
	s_nop 1
	v_cndmask_b32_e64 v27, v27, v28, s[6:7]
	v_cndmask_b32_e32 v28, 0, v216, vcc
	v_sub_f32_e32 v27, v27, v28
	v_add_f32_e32 v108, v106, v27
	v_add_f32_e32 v27, 1.0, v25
	v_rcp_f32_e32 v27, v27
	s_nop 0
	v_fma_f32 v28, v39, v27, v35
	v_cmp_gt_f32_e32 vcc, s24, v28
	v_pk_mul_f32 v[24:25], v[24:25], v[26:27]
	s_nop 0
	v_cndmask_b32_e64 v26, 0, 32, vcc
	v_ldexp_f32 v26, v28, v26
	v_log_f32_e32 v26, v26
	v_pk_mul_f32 v[24:25], v[38:39], v[24:25]
	v_lshl_or_b32 v28, v109, 16, v29
	v_cvt_pk_bf16_f32 v205, v24, v25
	v_mul_f32_e32 v27, 0x3f317217, v26
	v_fma_f32 v27, v26, s25, -v27
	v_fmac_f32_e32 v27, 0x3377d1cf, v26
	v_fmac_f32_e32 v27, 0x3f317217, v26
	v_cmp_lt_f32_e64 s[6:7], |v26|, s26
	v_and_or_b32 v24, v109, s16, v30
	v_lshlrev_b32_e32 v206, 16, v205
	v_cndmask_b32_e64 v26, v26, v27, s[6:7]
	v_cndmask_b32_e32 v27, 0, v216, vcc
	v_sub_f32_e32 v26, v26, v27
	v_add_f32_e32 v109, v107, v26
	v_add_co_u32_e32 v26, vcc, s49, v36
	v_and_b32_e32 v207, 0xffff0000, v205
	s_nop 0
	v_addc_co_u32_e32 v27, vcc, 0, v37, vcc
	s_nop 0
	v_add_co_u32_e32 v26, vcc, s50, v36
	s_nop 1
	v_addc_co_u32_e32 v27, vcc, 0, v37, vcc
	s_nop 0
	s_nop 0
	s_nop 0
	s_waitcnt vmcnt(15)
	v_and_b32_e32 v27, 0xffff0000, v110
	v_lshlrev_b32_e32 v26, 16, v110
	v_mul_f32_e32 v26, 0xbfb8aa3b, v26
	v_exp_f32_e32 v26, v26
	v_mul_f32_e32 v27, 0xbfb8aa3b, v27
	v_exp_f32_e32 v27, v27
	v_add_f32_e32 v29, 1.0, v26
	v_rcp_f32_e32 v30, v29
	s_nop 0
	v_fma_f32 v29, v38, v30, v34
	v_cmp_gt_f32_e32 vcc, s24, v29
	s_nop 1
	v_cndmask_b32_e64 v31, 0, 32, vcc
	v_ldexp_f32 v29, v29, v31
	v_log_f32_e32 v29, v29
	s_nop 0
	v_mul_f32_e32 v31, 0x3f317217, v29
	v_fma_f32 v31, v29, s25, -v31
	v_fmac_f32_e32 v31, 0x3377d1cf, v29
	v_fmac_f32_e32 v31, 0x3f317217, v29
	v_cmp_lt_f32_e64 s[6:7], |v29|, s26
	s_nop 1
	v_cndmask_b32_e64 v29, v29, v31, s[6:7]
	v_cndmask_b32_e32 v31, 0, v216, vcc
	v_sub_f32_e32 v29, v29, v31
	v_add_f32_e32 v110, v108, v29
	v_add_f32_e32 v29, 1.0, v27
	v_rcp_f32_e32 v31, v29
	s_nop 0
	v_fma_f32 v29, v39, v31, v35
	v_cmp_gt_f32_e32 vcc, s24, v29
	v_pk_mul_f32 v[26:27], v[26:27], v[30:31]
	s_nop 0
	v_cndmask_b32_e64 v30, 0, 32, vcc
	v_ldexp_f32 v29, v29, v30
	v_log_f32_e32 v29, v29
	v_pk_mul_f32 v[26:27], v[38:39], v[26:27]
	v_mul_f32_e32 v30, 0x3f317217, v29
	v_fma_f32 v30, v29, s25, -v30
	v_fmac_f32_e32 v30, 0x3377d1cf, v29
	v_fmac_f32_e32 v30, 0x3f317217, v29
	v_cmp_lt_f32_e64 s[6:7], |v29|, s26
	v_cvt_pk_bf16_f32 v209, v26, v27
	s_nop 0
	v_cndmask_b32_e64 v29, v29, v30, s[6:7]
	v_cndmask_b32_e32 v30, 0, v216, vcc
	v_add_co_u32_e32 v26, vcc, s51, v36
	v_sub_f32_e32 v29, v29, v30
	s_nop 0
	v_addc_co_u32_e32 v27, vcc, 0, v37, vcc
	s_nop 0
	v_add_co_u32_e32 v26, vcc, s52, v36
	v_add_f32_e32 v111, v109, v29
	s_nop 0
	v_addc_co_u32_e32 v27, vcc, 0, v37, vcc
	s_nop 0
	s_nop 0
	s_nop 0
	v_and_b32_e32 v29, 0xffff, v113
	v_lshrrev_b32_e32 v25, 16, v113
	s_waitcnt vmcnt(14)
	v_lshl_or_b32 v29, v211, 16, v29
	v_and_or_b32 v25, v211, s16, v25
	s_waitcnt vmcnt(12)
; __device__ __forceinline__ unsigned cvt_pk_bf16(float lo, float hi) { const f32x2_cv v = {lo, hi}; return __builtin_bit_cast(unsigned, __builtin_convertvector(v, bf16x2_cv)); }
; __device__ __forceinline__ float bf_lo(unsigned u) { return __uint_as_float(u << 16); }
; __device__ __forceinline__ float bf_hi(unsigned u) { return __uint_as_float(u & 0xffff0000u); }
; __device__ __forceinline__ void hgrn_prep_item(const bf16_t* Z, const float* lbl, unsigned char* REC, int cidx, int h, LAS unsigned char* wl, int lane) {
;     ...
;     for (int t = 0; t < 32; ++t) {
;         const unsigned ff = *(const unsigned*)(zr + (size_t)t * DIN + ZHF), ii = *(const unsigned*)(zr + (size_t)t * DIN + ZHI);
;         qraw[t] = *(const unsigned*)(zr + (size_t)t * DIN + ZHQ); float omv[2];
; #pragma unroll
;         for (int e = 0; e < 2; ++e) {
;             const float fl = e ? bf_hi(ff) : bf_lo(ff);
;             const float ex = __expf(-fl), sg = __builtin_amdgcn_rcpf(1.f + ex);
;             const float f = lb[e] + omlb[e] * sg;
;             omv[e] = omlb[e] * (ex * sg);
;             cum[e] += __logf(f); cv[t][e] = cum[e];
;         }
;         omp[t] = cvt_pk_bf16(omv[0], omv[1]);
;         if ((t & 1) == 0) { itp[0][t >> 1] = ii & 0xffffu; itp[1][t >> 1] = ii >> 16; }
;         else { itp[0][t >> 1] |= ii << 16; itp[1][t >> 1] |= ii & 0xffff0000u; }
	v_and_b32_e32 v27, 0xffff0000, v112
	v_lshlrev_b32_e32 v26, 16, v112
	v_mul_f32_e32 v26, 0xbfb8aa3b, v26
	v_exp_f32_e32 v26, v26
	v_mul_f32_e32 v27, 0xbfb8aa3b, v27
	v_exp_f32_e32 v27, v27
	v_add_f32_e32 v30, 1.0, v26
	v_rcp_f32_e32 v30, v30
	s_nop 0
	v_fma_f32 v31, v38, v30, v34
	v_cmp_gt_f32_e32 vcc, s24, v31
	s_nop 1
	v_cndmask_b32_e64 v83, 0, 32, vcc
	v_ldexp_f32 v31, v31, v83
	v_log_f32_e32 v31, v31
	s_nop 0
	v_mul_f32_e32 v83, 0x3f317217, v31
	v_fma_f32 v83, v31, s25, -v83
	v_fmac_f32_e32 v83, 0x3377d1cf, v31
	v_fmac_f32_e32 v83, 0x3f317217, v31
	v_cmp_lt_f32_e64 s[6:7], |v31|, s26
	s_nop 1
	v_cndmask_b32_e64 v31, v31, v83, s[6:7]
	v_cndmask_b32_e32 v83, 0, v216, vcc
	v_sub_f32_e32 v31, v31, v83
	v_add_f32_e32 v112, v110, v31
	v_add_f32_e32 v31, 1.0, v27
	v_rcp_f32_e32 v31, v31
	s_nop 0
	v_fma_f32 v83, v39, v31, v35
	v_cmp_gt_f32_e32 vcc, s24, v83
	v_pk_mul_f32 v[26:27], v[26:27], v[30:31]
	s_nop 0
	v_cndmask_b32_e64 v30, 0, 32, vcc
	v_ldexp_f32 v30, v83, v30
	v_log_f32_e32 v30, v30
	v_pk_mul_f32 v[26:27], v[38:39], v[26:27]
	v_mul_f32_e32 v31, 0x3f317217, v30
	v_fma_f32 v31, v30, s25, -v31
	v_fmac_f32_e32 v31, 0x3377d1cf, v30
	v_fmac_f32_e32 v31, 0x3f317217, v30
	v_cmp_lt_f32_e64 s[6:7], |v30|, s26
	v_cvt_pk_bf16_f32 v211, v26, v27
	s_nop 0
	v_cndmask_b32_e64 v30, v30, v31, s[6:7]
	v_cndmask_b32_e32 v31, 0, v216, vcc
	v_add_co_u32_e32 v26, vcc, s53, v36
	v_sub_f32_e32 v30, v30, v31
	s_nop 0
	v_addc_co_u32_e32 v27, vcc, 0, v37, vcc
	v_add_f32_e32 v113, v111, v30
	v_add_co_u32_e32 v30, vcc, s54, v36
	s_nop 0
	s_nop 0
	v_addc_co_u32_e32 v31, vcc, 0, v37, vcc
	s_nop 0
	s_nop 0
	s_nop 0
	s_waitcnt vmcnt(9)
	v_and_b32_e32 v27, 0xffff0000, v114
	v_lshlrev_b32_e32 v26, 16, v114
	v_mul_f32_e32 v26, 0xbfb8aa3b, v26
	v_exp_f32_e32 v26, v26
	v_mul_f32_e32 v27, 0xbfb8aa3b, v27
	v_exp_f32_e32 v27, v27
	v_add_f32_e32 v30, 1.0, v26
	v_rcp_f32_e32 v30, v30
	s_nop 0
	v_fma_f32 v31, v38, v30, v34
	v_cmp_gt_f32_e32 vcc, s24, v31
	s_nop 1
	v_cndmask_b32_e64 v83, 0, 32, vcc
	v_ldexp_f32 v31, v31, v83
	v_log_f32_e32 v31, v31
	s_nop 0
	v_mul_f32_e32 v83, 0x3f317217, v31
	v_fma_f32 v83, v31, s25, -v83
	v_fmac_f32_e32 v83, 0x3377d1cf, v31
	v_fmac_f32_e32 v83, 0x3f317217, v31
	v_cmp_lt_f32_e64 s[6:7], |v31|, s26
	s_nop 1
	v_cndmask_b32_e64 v31, v31, v83, s[6:7]
	v_cndmask_b32_e32 v83, 0, v216, vcc
	v_sub_f32_e32 v31, v31, v83
	v_add_f32_e32 v114, v112, v31
	v_add_f32_e32 v31, 1.0, v27
	v_rcp_f32_e32 v31, v31
	s_nop 0
	v_fma_f32 v83, v39, v31, v35
	v_cmp_gt_f32_e32 vcc, s24, v83
	v_pk_mul_f32 v[26:27], v[26:27], v[30:31]
	s_nop 0
	v_cndmask_b32_e64 v30, 0, 32, vcc
	v_ldexp_f32 v30, v83, v30
	v_log_f32_e32 v30, v30
	v_pk_mul_f32 v[26:27], v[38:39], v[26:27]
	v_and_b32_e32 v83, 0xffff, v115
	v_cvt_pk_bf16_f32 v213, v26, v27
	v_mul_f32_e32 v31, 0x3f317217, v30
	v_fma_f32 v31, v30, s25, -v31
	v_fmac_f32_e32 v31, 0x3377d1cf, v30
	v_fmac_f32_e32 v31, 0x3f317217, v30
	v_cmp_lt_f32_e64 s[6:7], |v30|, s26
	v_lshrrev_b32_e32 v82, 16, v115
	s_nop 0
	v_cndmask_b32_e64 v30, v30, v31, s[6:7]
	v_cndmask_b32_e32 v31, 0, v216, vcc
	v_add_co_u32_e32 v26, vcc, s55, v36
	v_sub_f32_e32 v30, v30, v31
	s_nop 0
	v_addc_co_u32_e32 v27, vcc, 0, v37, vcc
	v_add_f32_e32 v115, v113, v30
	v_add_co_u32_e32 v30, vcc, s56, v36
	s_nop 0
	s_nop 0
	v_addc_co_u32_e32 v31, vcc, 0, v37, vcc
	s_nop 0
	s_nop 0
	s_nop 0
	s_waitcnt vmcnt(6)
	v_and_b32_e32 v27, 0xffff0000, v116
	v_lshlrev_b32_e32 v26, 16, v116
	v_mul_f32_e32 v26, 0xbfb8aa3b, v26
	v_exp_f32_e32 v26, v26
	v_mul_f32_e32 v27, 0xbfb8aa3b, v27
	v_exp_f32_e32 v27, v27
	v_add_f32_e32 v30, 1.0, v26
	v_rcp_f32_e32 v30, v30
	s_nop 0
	v_fma_f32 v31, v38, v30, v34
	v_cmp_gt_f32_e32 vcc, s24, v31
	s_nop 1
	v_cndmask_b32_e64 v116, 0, 32, vcc
	v_ldexp_f32 v31, v31, v116
	v_log_f32_e32 v31, v31
	s_nop 0
	v_mul_f32_e32 v116, 0x3f317217, v31
	v_fma_f32 v116, v31, s25, -v116
	v_fmac_f32_e32 v116, 0x3377d1cf, v31
	v_fmac_f32_e32 v116, 0x3f317217, v31
	v_cmp_lt_f32_e64 s[6:7], |v31|, s26
	s_nop 1
	v_cndmask_b32_e64 v31, v31, v116, s[6:7]
	v_cndmask_b32_e32 v116, 0, v216, vcc
	v_sub_f32_e32 v31, v31, v116
	v_add_f32_e32 v116, v114, v31
	v_add_f32_e32 v31, 1.0, v27
	v_rcp_f32_e32 v31, v31
	s_nop 0
	v_fma_f32 v117, v39, v31, v35
	v_cmp_gt_f32_e32 vcc, s24, v117
	v_pk_mul_f32 v[26:27], v[26:27], v[30:31]
	s_nop 0
	v_cndmask_b32_e64 v30, 0, 32, vcc
	v_ldexp_f32 v30, v117, v30
	v_log_f32_e32 v30, v30
	v_pk_mul_f32 v[26:27], v[38:39], v[26:27]
	v_mul_f32_e32 v31, 0x3f317217, v30
	v_fma_f32 v31, v30, s25, -v31
	v_fmac_f32_e32 v31, 0x3377d1cf, v30
	v_fmac_f32_e32 v31, 0x3f317217, v30
	v_cmp_lt_f32_e64 s[6:7], |v30|, s26
	v_cvt_pk_bf16_f32 v215, v26, v27
	v_and_or_b32 v26, v118, s16, v82
	v_cndmask_b32_e64 v30, v30, v31, s[6:7]
	v_cndmask_b32_e32 v31, 0, v216, vcc
	v_sub_f32_e32 v30, v30, v31
	v_add_co_u32_e32 v82, vcc, s57, v36
	v_add_f32_e32 v117, v115, v30
	v_lshl_or_b32 v30, v118, 16, v83
	v_addc_co_u32_e32 v83, vcc, 0, v37, vcc
	s_nop 0
	v_add_co_u32_e32 v82, vcc, s58, v36
	s_nop 1
	v_addc_co_u32_e32 v83, vcc, 0, v37, vcc
	s_nop 0
	s_nop 0
	s_waitcnt vmcnt(3)
; __device__ __forceinline__ unsigned cvt_pk_bf16(float lo, float hi) { const f32x2_cv v = {lo, hi}; return __builtin_bit_cast(unsigned, __builtin_convertvector(v, bf16x2_cv)); }
; __device__ __forceinline__ float bf_lo(unsigned u) { return __uint_as_float(u << 16); }
; __device__ __forceinline__ float bf_hi(unsigned u) { return __uint_as_float(u & 0xffff0000u); }
; __device__ __forceinline__ void hgrn_prep_item(const bf16_t* Z, const float* lbl, unsigned char* REC, int cidx, int h, LAS unsigned char* wl, int lane) {
;     ...
;     for (int t = 0; t < 32; ++t) {
;         const unsigned ff = *(const unsigned*)(zr + (size_t)t * DIN + ZHF), ii = *(const unsigned*)(zr + (size_t)t * DIN + ZHI);
;         qraw[t] = *(const unsigned*)(zr + (size_t)t * DIN + ZHQ); float omv[2];
; #pragma unroll
;         for (int e = 0; e < 2; ++e) {
;             const float fl = e ? bf_hi(ff) : bf_lo(ff);
;             const float ex = __expf(-fl), sg = __builtin_amdgcn_rcpf(1.f + ex);
;             const float f = lb[e] + omlb[e] * sg;
;             omv[e] = omlb[e] * (ex * sg);
;             cum[e] += __logf(f); cv[t][e] = cum[e];
;         }
;         omp[t] = cvt_pk_bf16(omv[0], omv[1]);
;         if ((t & 1) == 0) { itp[0][t >> 1] = ii & 0xffffu; itp[1][t >> 1] = ii >> 16; }
;         else { itp[0][t >> 1] |= ii << 16; itp[1][t >> 1] |= ii & 0xffff0000u; }
;         if ((t & 15) == 15) asm volatile("" ::: "memory");
;     }
;     unsigned char* R = REC + ((size_t)cidx * 8 + h) * REC_STRIDE;
;     {   u32x4* it = (u32x4*)(R + R_IT + k0 * 64);
; #pragma unroll
;         for (int e = 0; e < 2; ++e)
; #pragma unroll
;             for (int q4 = 0; q4 < 4; ++q4) it[4 * e + q4] = (u32x4){itp[e][4 * q4], itp[e][4 * q4 + 1], itp[e][4 * q4 + 2], itp[e][4 * q4 + 3]}; }
;     const float ref0 = cv[15][0], ref1 = cv[15][1];
;     const float eref0 = __expf(ref0), eref1 = __expf(ref1), eL0 = __expf(cum[0] - ref0), eL1 = __expf(cum[1] - ref1);
; #pragma unroll
;     for (int t = 0; t < 32; ++t) { cv[t][0] = __expf(cv[t][0] - ref0); cv[t][1] = __expf(cv[t][1] - ref1); }
	v_and_b32_e32 v83, 0xffff0000, v120
	v_lshlrev_b32_e32 v31, 16, v120
	v_mul_f32_e32 v31, 0xbfb8aa3b, v31
	v_exp_f32_e32 v82, v31
	s_nop 0
	v_add_f32_e32 v31, 1.0, v82
	v_rcp_f32_e32 v120, v31
	s_nop 0
	v_fma_f32 v31, v38, v120, v34
	v_cmp_gt_f32_e32 vcc, s24, v31
	s_nop 1
	v_cndmask_b32_e64 v118, 0, 32, vcc
	v_ldexp_f32 v31, v31, v118
	v_log_f32_e32 v31, v31
	s_nop 0
	v_mul_f32_e32 v118, 0x3f317217, v31
	v_fma_f32 v118, v31, s25, -v118
	v_fmac_f32_e32 v118, 0x3377d1cf, v31
	v_fmac_f32_e32 v118, 0x3f317217, v31
	v_cmp_lt_f32_e64 s[6:7], |v31|, s26
	s_nop 1
	v_cndmask_b32_e64 v31, v31, v118, s[6:7]
	v_cndmask_b32_e32 v118, 0, v216, vcc
	v_sub_f32_e32 v31, v31, v118
	v_add_f32_e32 v118, v116, v31
	v_mul_f32_e32 v31, 0xbfb8aa3b, v83
	v_exp_f32_e32 v83, v31
	s_nop 0
	v_add_f32_e32 v31, 1.0, v83
	v_rcp_f32_e32 v121, v31
	s_nop 0
	v_fma_f32 v31, v39, v121, v35
	v_cmp_gt_f32_e32 vcc, s24, v31
	v_pk_mul_f32 v[82:83], v[82:83], v[120:121]
	s_nop 0
	v_cndmask_b32_e64 v119, 0, 32, vcc
	v_ldexp_f32 v31, v31, v119
	v_log_f32_e32 v31, v31
	v_pk_mul_f32 v[82:83], v[38:39], v[82:83]
	v_mul_f32_e32 v119, 0x3f317217, v31
	v_fma_f32 v119, v31, s25, -v119
	v_fmac_f32_e32 v119, 0x3377d1cf, v31
	v_fmac_f32_e32 v119, 0x3f317217, v31
	v_cmp_lt_f32_e64 s[6:7], |v31|, s26
	v_cvt_pk_bf16_f32 v221, v82, v83
	v_and_b32_e32 v201, 0xffff0000, v221
	v_cndmask_b32_e64 v31, v31, v119, s[6:7]
	v_cndmask_b32_e32 v119, 0, v216, vcc
	v_add_co_u32_e32 v82, vcc, s59, v36
	v_sub_f32_e32 v31, v31, v119
	s_nop 0
	v_addc_co_u32_e32 v83, vcc, 0, v37, vcc
	v_add_co_u32_e32 v36, vcc, s60, v36
	s_nop 0
	s_nop 0
	v_addc_co_u32_e32 v37, vcc, 0, v37, vcc
	s_nop 0
	s_nop 0
	s_nop 0
	v_add_f32_e32 v119, v117, v31
	v_and_b32_e32 v31, 0xffff, v219
	v_lshrrev_b32_e32 v27, 16, v219
	s_waitcnt vmcnt(2)
	v_lshl_or_b32 v31, v223, 16, v31
	v_and_or_b32 v27, v223, s16, v27
	s_waitcnt vmcnt(0)
	v_and_b32_e32 v37, 0xffff0000, v218
	v_lshlrev_b32_e32 v36, 16, v218
	v_mul_f32_e32 v36, 0xbfb8aa3b, v36
	v_exp_f32_e32 v36, v36
	s_nop 0
	v_add_f32_e32 v82, 1.0, v36
	v_rcp_f32_e32 v82, v82
	s_nop 0
	v_fmac_f32_e32 v34, v38, v82
	v_cmp_gt_f32_e32 vcc, s24, v34
	s_nop 1
	v_cndmask_b32_e64 v83, 0, 32, vcc
	v_ldexp_f32 v34, v34, v83
	v_log_f32_e32 v34, v34
	s_nop 0
	v_mul_f32_e32 v83, 0x3f317217, v34
	v_fma_f32 v83, v34, s25, -v83
	v_fmac_f32_e32 v83, 0x3377d1cf, v34
	v_fmac_f32_e32 v83, 0x3f317217, v34
	v_cmp_lt_f32_e64 s[6:7], |v34|, s26
	s_nop 1
	v_cndmask_b32_e64 v34, v34, v83, s[6:7]
	v_cndmask_b32_e32 v83, 0, v216, vcc
	v_sub_f32_e32 v34, v34, v83
	v_add_f32_e32 v218, v118, v34
	v_mul_f32_e32 v34, 0xbfb8aa3b, v37
	v_exp_f32_e32 v37, v34
	s_nop 0
	v_add_f32_e32 v34, 1.0, v37
	v_rcp_f32_e32 v83, v34
	s_nop 0
	v_fmac_f32_e32 v35, v39, v83
	v_cmp_gt_f32_e32 vcc, s24, v35
	v_pk_mul_f32 v[36:37], v[36:37], v[82:83]
	s_nop 0
	v_cndmask_b32_e64 v34, 0, 32, vcc
	v_ldexp_f32 v34, v35, v34
	v_log_f32_e32 v34, v34
	v_pk_mul_f32 v[36:37], v[38:39], v[36:37]
	v_mul_f32_e32 v35, 0x3f317217, v34
	v_fma_f32 v35, v34, s25, -v35
	v_fmac_f32_e32 v35, 0x3377d1cf, v34
	v_fmac_f32_e32 v35, 0x3f317217, v34
	v_cmp_lt_f32_e64 s[6:7], |v34|, s26
	v_cvt_pk_bf16_f32 v223, v36, v37
	v_and_b32_e32 v205, 0xffff0000, v223
	v_cndmask_b32_e64 v34, v34, v35, s[6:7]
	v_cndmask_b32_e32 v35, 0, v216, vcc
	v_sub_f32_e32 v34, v34, v35
	v_add_f32_e32 v219, v119, v34
	v_lshlrev_b32_e32 v34, 7, v217
	v_mov_b32_e32 v35, v33
	v_lshl_add_u64 v[82:83], s[10:11], 0, v[34:35]
	v_add_co_u32_e32 v34, vcc, s61, v82
	s_mul_i32 s6, s90, 0x35000
	s_nop 0
	v_addc_co_u32_e32 v35, vcc, -1, v83, vcc
	global_store_dwordx4 v[34:35], v[4:7], off offset:-2052
	global_store_dwordx4 v[34:35], v[12:15], off offset:-2036
	global_store_dwordx4 v[34:35], v[20:23], off offset:-2020
	global_store_dwordx4 v[34:35], v[28:31], off offset:-2004
	global_store_dwordx4 v[34:35], v[0:3], off offset:-1988
	global_store_dwordx4 v[34:35], v[8:11], off offset:-1972
	global_store_dwordx4 v[34:35], v[16:19], off offset:-1956
	global_store_dwordx4 v[34:35], v[24:27], off offset:-1940
	v_sub_f32_e32 v2, v218, v84
	v_mul_f32_e32 v120, 0x3fb8aa3b, v2
	v_sub_f32_e32 v2, v219, v85
	v_mul_f32_e32 v121, 0x3fb8aa3b, v2
	v_sub_f32_e32 v2, v88, v84
	v_mul_f32_e32 v2, 0x3fb8aa3b, v2
	v_exp_f32_e32 v16, v2
	v_sub_f32_e32 v2, v89, v85
	v_mul_f32_e32 v2, 0x3fb8aa3b, v2
	v_exp_f32_e32 v17, v2
	v_sub_f32_e32 v2, v90, v84
	v_mul_f32_e32 v2, 0x3fb8aa3b, v2
	v_exp_f32_e32 v18, v2
	v_sub_f32_e32 v2, v91, v85
	v_mul_f32_e32 v2, 0x3fb8aa3b, v2
	v_exp_f32_e32 v19, v2
	v_sub_f32_e32 v2, v92, v84
	v_mul_f32_e32 v2, 0x3fb8aa3b, v2
	v_exp_f32_e32 v20, v2
	v_sub_f32_e32 v2, v93, v85
	v_mul_f32_e32 v2, 0x3fb8aa3b, v2
	v_exp_f32_e32 v21, v2
	v_sub_f32_e32 v2, v94, v84
	v_mul_f32_e32 v2, 0x3fb8aa3b, v2
	v_exp_f32_e32 v22, v2
	v_sub_f32_e32 v2, v95, v85
	v_mul_f32_e32 v2, 0x3fb8aa3b, v2
	v_exp_f32_e32 v23, v2
	v_sub_f32_e32 v2, v96, v84
	v_mul_f32_e32 v2, 0x3fb8aa3b, v2
	v_exp_f32_e32 v24, v2
	v_sub_f32_e32 v2, v40, v85
	v_mul_f32_e32 v2, 0x3fb8aa3b, v2
	v_exp_f32_e32 v25, v2
	v_sub_f32_e32 v2, v41, v84
	v_mul_f32_e32 v2, 0x3fb8aa3b, v2
	v_exp_f32_e32 v26, v2
	v_sub_f32_e32 v2, v42, v85
	v_mul_f32_e32 v2, 0x3fb8aa3b, v2
	v_exp_f32_e32 v27, v2
	v_sub_f32_e32 v2, v43, v84
	v_mul_f32_e32 v2, 0x3fb8aa3b, v2
	v_exp_f32_e32 v28, v2
	v_sub_f32_e32 v2, v44, v85
	v_mul_f32_e32 v2, 0x3fb8aa3b, v2
	v_exp_f32_e32 v29, v2
	v_sub_f32_e32 v2, v45, v84
	v_mul_f32_e32 v2, 0x3fb8aa3b, v2
	v_exp_f32_e32 v30, v2
	v_sub_f32_e32 v2, v46, v85
	v_mul_f32_e32 v2, 0x3fb8aa3b, v2
	v_exp_f32_e32 v31, v2
	v_sub_f32_e32 v2, v47, v84
	v_mul_f32_e32 v2, 0x3fb8aa3b, v2
	v_exp_f32_e32 v34, v2
	v_sub_f32_e32 v2, v48, v85
	v_mul_f32_e32 v2, 0x3fb8aa3b, v2
; __device__ __forceinline__ unsigned cvt_pk_bf16(float lo, float hi) { const f32x2_cv v = {lo, hi}; return __builtin_bit_cast(unsigned, __builtin_convertvector(v, bf16x2_cv)); }
; __device__ __forceinline__ float bf_lo(unsigned u) { return __uint_as_float(u << 16); }
; __device__ __forceinline__ float bf_hi(unsigned u) { return __uint_as_float(u & 0xffff0000u); }
; #define LAS __attribute__((address_space(3)))
; __device__ __forceinline__ void hgrn_prep_item(const bf16_t* Z, const float* lbl, unsigned char* REC, int cidx, int h, LAS unsigned char* wl, int lane) {
;     ...
;     const float ref0 = cv[15][0], ref1 = cv[15][1];
;     const float eref0 = __expf(ref0), eref1 = __expf(ref1), eL0 = __expf(cum[0] - ref0), eL1 = __expf(cum[1] - ref1);
; #pragma unroll
;     for (int t = 0; t < 32; ++t) { cv[t][0] = __expf(cv[t][0] - ref0); cv[t][1] = __expf(cv[t][1] - ref1); }
;     float ri[32][2];
; #pragma unroll
;     for (int t = 0; t < 32; ++t) { ri[t][0] = __builtin_amdgcn_rcpf(cv[t][0]); ri[t][1] = __builtin_amdgcn_rcpf(cv[t][1]); }
; #pragma unroll
;     for (int t = 0; t < 32; ++t) {
;         const float q0 = bf_lo(qraw[t]), q1 = bf_hi(qraw[t]);
;         *(LAS unsigned*)(Xs + t * 132 + k0) = cvt_pk_bf16(q0 * cv[t][0] * eref0, q1 * cv[t][1] * eref1);
;         *(LAS unsigned*)(Ys + t * 132 + k0) = cvt_pk_bf16(bf_lo(omp[t]) * ri[t][0], bf_hi(omp[t]) * ri[t][1]);
;     }
	v_exp_f32_e32 v35, v2
	v_sub_f32_e32 v2, v49, v84
	v_mul_f32_e32 v2, 0x3fb8aa3b, v2
	v_exp_f32_e32 v36, v2
	v_sub_f32_e32 v2, v50, v85
	v_mul_f32_e32 v2, 0x3fb8aa3b, v2
	v_exp_f32_e32 v37, v2
	v_sub_f32_e32 v2, v51, v84
	v_mul_f32_e32 v2, 0x3fb8aa3b, v2
	v_exp_f32_e32 v38, v2
	v_sub_f32_e32 v2, v52, v85
	v_mul_f32_e32 v2, 0x3fb8aa3b, v2
	v_exp_f32_e32 v39, v2
	v_sub_f32_e32 v2, v53, v84
	v_mul_f32_e32 v2, 0x3fb8aa3b, v2
	v_exp_f32_e32 v40, v2
	v_sub_f32_e32 v2, v54, v85
	v_mul_f32_e32 v2, 0x3fb8aa3b, v2
	v_exp_f32_e32 v41, v2
	v_sub_f32_e32 v2, v55, v84
	v_mul_f32_e32 v2, 0x3fb8aa3b, v2
	v_exp_f32_e32 v42, v2
	v_sub_f32_e32 v2, v60, v85
	v_mul_f32_e32 v2, 0x3fb8aa3b, v2
	v_exp_f32_e32 v43, v2
	v_sub_f32_e32 v2, v61, v84
	v_mul_f32_e32 v2, 0x3fb8aa3b, v2
	v_exp_f32_e32 v44, v2
	v_sub_f32_e32 v2, v62, v85
	v_mul_f32_e32 v2, 0x3fb8aa3b, v2
	v_exp_f32_e32 v45, v2
	v_sub_f32_e32 v2, v63, v84
	v_mul_f32_e32 v2, 0x3fb8aa3b, v2
	v_exp_f32_e32 v46, v2
	v_sub_f32_e32 v2, v64, v85
	v_mul_f32_e32 v2, 0x3fb8aa3b, v2
	v_exp_f32_e32 v47, v2
	v_sub_f32_e32 v2, v84, v84
	v_mul_f32_e32 v2, 0x3fb8aa3b, v2
	v_exp_f32_e32 v48, v2
	v_sub_f32_e32 v2, v85, v85
	v_mul_f32_e32 v2, 0x3fb8aa3b, v2
	v_exp_f32_e32 v49, v2
	v_sub_f32_e32 v2, v56, v84
	v_mul_f32_e32 v2, 0x3fb8aa3b, v2
	v_exp_f32_e32 v50, v2
	v_sub_f32_e32 v2, v57, v85
	v_mul_f32_e32 v2, 0x3fb8aa3b, v2
	v_exp_f32_e32 v51, v2
	v_sub_f32_e32 v2, v58, v84
	v_mul_f32_e32 v2, 0x3fb8aa3b, v2
	v_exp_f32_e32 v52, v2
	v_sub_f32_e32 v2, v59, v85
	v_mul_f32_e32 v2, 0x3fb8aa3b, v2
	v_exp_f32_e32 v53, v2
	v_sub_f32_e32 v2, v65, v84
	v_mul_f32_e32 v2, 0x3fb8aa3b, v2
	v_exp_f32_e32 v54, v2
	v_sub_f32_e32 v2, v86, v85
	v_mul_f32_e32 v2, 0x3fb8aa3b, v2
	v_exp_f32_e32 v55, v2
	v_sub_f32_e32 v2, v87, v84
	v_mul_f32_e32 v2, 0x3fb8aa3b, v2
	v_exp_f32_e32 v56, v2
	v_sub_f32_e32 v2, v97, v85
	v_mul_f32_e32 v2, 0x3fb8aa3b, v2
	v_exp_f32_e32 v57, v2
	v_sub_f32_e32 v2, v98, v84
	v_mul_f32_e32 v2, 0x3fb8aa3b, v2
	v_exp_f32_e32 v58, v2
	v_sub_f32_e32 v2, v99, v85
	v_mul_f32_e32 v2, 0x3fb8aa3b, v2
	v_exp_f32_e32 v59, v2
	v_sub_f32_e32 v2, v100, v84
	v_mul_f32_e32 v2, 0x3fb8aa3b, v2
	v_exp_f32_e32 v60, v2
	v_sub_f32_e32 v2, v101, v85
	v_mul_f32_e32 v2, 0x3fb8aa3b, v2
	v_exp_f32_e32 v61, v2
	v_sub_f32_e32 v2, v102, v84
	v_mul_f32_e32 v2, 0x3fb8aa3b, v2
	v_exp_f32_e32 v62, v2
	v_sub_f32_e32 v2, v103, v85
	v_mul_f32_e32 v2, 0x3fb8aa3b, v2
	v_exp_f32_e32 v63, v2
	v_sub_f32_e32 v2, v104, v84
	v_mul_f32_e32 v2, 0x3fb8aa3b, v2
	v_exp_f32_e32 v64, v2
	v_sub_f32_e32 v2, v105, v85
	v_mul_f32_e32 v2, 0x3fb8aa3b, v2
	v_exp_f32_e32 v65, v2
	v_sub_f32_e32 v2, v106, v84
	v_mul_f32_e32 v2, 0x3fb8aa3b, v2
	v_exp_f32_e32 v14, v2
	v_sub_f32_e32 v2, v107, v85
	v_mul_f32_e32 v2, 0x3fb8aa3b, v2
	v_exp_f32_e32 v15, v2
	v_sub_f32_e32 v2, v108, v84
	v_mul_f32_e32 v2, 0x3fb8aa3b, v2
	v_exp_f32_e32 v12, v2
	v_sub_f32_e32 v2, v109, v85
	v_mul_f32_e32 v2, 0x3fb8aa3b, v2
	v_exp_f32_e32 v13, v2
	v_sub_f32_e32 v2, v110, v84
	v_mul_f32_e32 v2, 0x3fb8aa3b, v2
	v_exp_f32_e32 v10, v2
	v_sub_f32_e32 v2, v111, v85
	v_mul_f32_e32 v2, 0x3fb8aa3b, v2
	v_exp_f32_e32 v11, v2
	v_sub_f32_e32 v2, v112, v84
	v_mul_f32_e32 v2, 0x3fb8aa3b, v2
	v_exp_f32_e32 v8, v2
	v_sub_f32_e32 v2, v113, v85
	v_mul_f32_e32 v2, 0x3fb8aa3b, v2
	v_exp_f32_e32 v9, v2
	v_sub_f32_e32 v2, v114, v84
	v_mul_f32_e32 v2, 0x3fb8aa3b, v2
	v_exp_f32_e32 v6, v2
	v_sub_f32_e32 v2, v115, v85
	v_mul_f32_e32 v2, 0x3fb8aa3b, v2
	v_exp_f32_e32 v7, v2
	v_sub_f32_e32 v2, v116, v84
	v_mul_f32_e32 v2, 0x3fb8aa3b, v2
	v_mul_f32_e32 v0, 0x3fb8aa3b, v84
	v_mul_f32_e32 v1, 0x3fb8aa3b, v85
	v_exp_f32_e32 v4, v2
	v_sub_f32_e32 v2, v117, v85
	v_mul_f32_e32 v2, 0x3fb8aa3b, v2
	v_exp_f32_e32 v0, v0
	v_exp_f32_e32 v1, v1
	v_exp_f32_e32 v5, v2
	v_sub_f32_e32 v2, v118, v84
	v_sub_f32_e32 v3, v119, v85
	v_rcp_f32_e32 v84, v16
	v_rcp_f32_e32 v85, v17
	v_pk_mul_f32 v[16:17], v[16:17], v[184:185]
	v_rcp_f32_e32 v86, v18
	v_pk_mul_f32 v[184:185], v[0:1], v[16:17]
	v_rcp_f32_e32 v87, v19
	v_cvt_pk_bf16_f32 v32, v184, v185
	v_pk_mul_f32 v[184:185], v[84:85], v[122:123]
	v_rcp_f32_e32 v88, v20
	v_cvt_pk_bf16_f32 v171, v184, v185
	v_lshlrev_b32_e32 v184, 16, v130
	v_and_b32_e32 v185, 0xffff0000, v130
	v_pk_mul_f32 v[18:19], v[18:19], v[184:185]
	v_rcp_f32_e32 v89, v21
	v_pk_mul_f32 v[184:185], v[0:1], v[18:19]
	v_rcp_f32_e32 v90, v22
	v_cvt_pk_bf16_f32 v130, v184, v185
	ds_write2_b32 v224, v32, v130 offset1:66
	v_lshlrev_b32_e32 v130, 16, v131
	v_and_b32_e32 v131, 0xffff0000, v131
	v_pk_mul_f32 v[184:185], v[86:87], v[130:131]
	v_rcp_f32_e32 v91, v23
	v_cvt_pk_bf16_f32 v32, v184, v185
	v_lshlrev_b32_e32 v184, 16, v140
	v_and_b32_e32 v185, 0xffff0000, v140
	v_pk_mul_f32 v[20:21], v[20:21], v[184:185]
	v_lshlrev_b32_e32 v140, 16, v141
	v_pk_mul_f32 v[184:185], v[0:1], v[20:21]
	v_and_b32_e32 v141, 0xffff0000, v141
	ds_write2_b32 v173, v171, v32 offset0:64 offset1:130
	v_cvt_pk_bf16_f32 v32, v184, v185
	v_pk_mul_f32 v[184:185], v[88:89], v[140:141]
	v_rcp_f32_e32 v92, v24
	v_cvt_pk_bf16_f32 v171, v184, v185
	v_lshlrev_b32_e32 v184, 16, v146
	v_and_b32_e32 v185, 0xffff0000, v146
	v_pk_mul_f32 v[22:23], v[22:23], v[184:185]
	v_rcp_f32_e32 v93, v25
	v_pk_mul_f32 v[184:185], v[0:1], v[22:23]
	v_add_u32_e32 v173, 0x2200, v224
	v_cvt_pk_bf16_f32 v146, v184, v185
	ds_write2_b32 v224, v32, v146 offset0:132 offset1:198
	v_lshlrev_b32_e32 v146, 16, v147
	v_and_b32_e32 v147, 0xffff0000, v147
	v_pk_mul_f32 v[184:185], v[90:91], v[146:147]
	v_rcp_f32_e32 v94, v26
	v_cvt_pk_bf16_f32 v32, v184, v185
	v_lshlrev_b32_e32 v184, 16, v156
	v_and_b32_e32 v185, 0xffff0000, v156
	v_pk_mul_f32 v[24:25], v[24:25], v[184:185]
	v_lshlrev_b32_e32 v156, 16, v157
; __device__ __forceinline__ unsigned cvt_pk_bf16(float lo, float hi) { const f32x2_cv v = {lo, hi}; return __builtin_bit_cast(unsigned, __builtin_convertvector(v, bf16x2_cv)); }
; __device__ __forceinline__ float bf_lo(unsigned u) { return __uint_as_float(u << 16); }
; __device__ __forceinline__ float bf_hi(unsigned u) { return __uint_as_float(u & 0xffff0000u); }
; #define LAS __attribute__((address_space(3)))
; __device__ __forceinline__ void hgrn_prep_item(const bf16_t* Z, const float* lbl, unsigned char* REC, int cidx, int h, LAS unsigned char* wl, int lane) {
;     ...
; #pragma unroll
;     for (int t = 0; t < 32; ++t) {
;         const float q0 = bf_lo(qraw[t]), q1 = bf_hi(qraw[t]);
;         *(LAS unsigned*)(Xs + t * 132 + k0) = cvt_pk_bf16(q0 * cv[t][0] * eref0, q1 * cv[t][1] * eref1);
;         *(LAS unsigned*)(Ys + t * 132 + k0) = cvt_pk_bf16(bf_lo(omp[t]) * ri[t][0], bf_hi(omp[t]) * ri[t][1]);
;     }
	v_pk_mul_f32 v[184:185], v[0:1], v[24:25]
	v_and_b32_e32 v157, 0xffff0000, v157
	ds_write2_b32 v173, v171, v32 offset0:68 offset1:134
	v_cvt_pk_bf16_f32 v32, v184, v185
	v_pk_mul_f32 v[184:185], v[92:93], v[156:157]
	v_rcp_f32_e32 v95, v27
	v_cvt_pk_bf16_f32 v171, v184, v185
	v_lshlrev_b32_e32 v184, 16, v162
	v_and_b32_e32 v185, 0xffff0000, v162
	v_pk_mul_f32 v[26:27], v[26:27], v[184:185]
	v_rcp_f32_e32 v96, v28
	v_pk_mul_f32 v[184:185], v[0:1], v[26:27]
	v_rcp_f32_e32 v97, v29
	v_cvt_pk_bf16_f32 v162, v184, v185
	ds_write2_b32 v225, v32, v162 offset0:8 offset1:74
	v_lshlrev_b32_e32 v162, 16, v163
	v_and_b32_e32 v163, 0xffff0000, v163
	v_pk_mul_f32 v[184:185], v[94:95], v[162:163]
	v_add_u32_e32 v173, 0x2400, v224
	v_cvt_pk_bf16_f32 v32, v184, v185
	v_lshlrev_b32_e32 v184, 16, v164
	v_and_b32_e32 v185, 0xffff0000, v164
	v_pk_mul_f32 v[28:29], v[28:29], v[184:185]
	v_lshlrev_b32_e32 v164, 16, v165
	v_pk_mul_f32 v[184:185], v[0:1], v[28:29]
	v_and_b32_e32 v165, 0xffff0000, v165
	ds_write2_b32 v173, v171, v32 offset0:72 offset1:138
	v_cvt_pk_bf16_f32 v32, v184, v185
	v_pk_mul_f32 v[184:185], v[96:97], v[164:165]
	v_rcp_f32_e32 v98, v30
	v_cvt_pk_bf16_f32 v171, v184, v185
	v_lshlrev_b32_e32 v184, 16, v166
	v_and_b32_e32 v185, 0xffff0000, v166
	v_rcp_f32_e32 v99, v31
	v_pk_mul_f32 v[30:31], v[30:31], v[184:185]
	v_rcp_f32_e32 v100, v34
	v_pk_mul_f32 v[184:185], v[0:1], v[30:31]
	v_rcp_f32_e32 v101, v35
	v_cvt_pk_bf16_f32 v166, v184, v185
	ds_write2_b32 v225, v32, v166 offset0:140 offset1:206
	v_lshlrev_b32_e32 v166, 16, v167
	v_and_b32_e32 v167, 0xffff0000, v167
	v_pk_mul_f32 v[184:185], v[98:99], v[166:167]
	v_add_u32_e32 v173, 0x2600, v224
	v_cvt_pk_bf16_f32 v32, v184, v185
	v_lshlrev_b32_e32 v184, 16, v168
	v_and_b32_e32 v185, 0xffff0000, v168
	v_pk_mul_f32 v[34:35], v[34:35], v[184:185]
	v_lshlrev_b32_e32 v168, 16, v169
	v_pk_mul_f32 v[184:185], v[0:1], v[34:35]
	v_and_b32_e32 v169, 0xffff0000, v169
	ds_write2_b32 v173, v171, v32 offset0:76 offset1:142
	v_cvt_pk_bf16_f32 v32, v184, v185
	v_pk_mul_f32 v[184:185], v[100:101], v[168:169]
	v_rcp_f32_e32 v102, v36
	v_cvt_pk_bf16_f32 v173, v184, v185
	v_lshlrev_b32_e32 v184, 16, v170
	v_and_b32_e32 v185, 0xffff0000, v170
	v_rcp_f32_e32 v103, v37
	v_pk_mul_f32 v[36:37], v[36:37], v[184:185]
	v_rcp_f32_e32 v104, v38
	v_pk_mul_f32 v[170:171], v[0:1], v[36:37]
	v_rcp_f32_e32 v105, v39
	v_cvt_pk_bf16_f32 v170, v170, v171
	ds_write2_b32 v226, v32, v170 offset0:16 offset1:82
	v_lshlrev_b32_e32 v170, 16, v66
	v_and_b32_e32 v171, 0xffff0000, v66
	v_pk_mul_f32 v[184:185], v[102:103], v[170:171]
	v_add_u32_e32 v66, 0x2800, v224
	v_cvt_pk_bf16_f32 v32, v184, v185
	v_lshlrev_b32_e32 v184, 16, v172
	v_and_b32_e32 v185, 0xffff0000, v172
	v_pk_mul_f32 v[38:39], v[38:39], v[184:185]
	ds_write2_b32 v66, v173, v32 offset0:80 offset1:146
	v_pk_mul_f32 v[172:173], v[0:1], v[38:39]
	v_rcp_f32_e32 v106, v40
	v_cvt_pk_bf16_f32 v32, v172, v173
	v_lshlrev_b32_e32 v172, 16, v67
	v_and_b32_e32 v173, 0xffff0000, v67
	v_pk_mul_f32 v[66:67], v[104:105], v[172:173]
	v_rcp_f32_e32 v107, v41
	v_cvt_pk_bf16_f32 v177, v66, v67
	v_lshlrev_b32_e32 v66, 16, v174
	v_and_b32_e32 v67, 0xffff0000, v174
	v_pk_mul_f32 v[40:41], v[40:41], v[66:67]
	v_lshlrev_b32_e32 v174, 16, v70
	v_pk_mul_f32 v[66:67], v[0:1], v[40:41]
	v_rcp_f32_e32 v110, v42
	v_cvt_pk_bf16_f32 v66, v66, v67
	ds_write2_b32 v226, v32, v66 offset0:148 offset1:214
	v_pk_mul_f32 v[66:67], v[106:107], v[174:175]
	v_rcp_f32_e32 v111, v43
	v_cvt_pk_bf16_f32 v32, v66, v67
	v_add_u32_e32 v66, 0x2a00, v224
	ds_write2_b32 v66, v177, v32 offset0:84 offset1:150
	v_lshlrev_b32_e32 v66, 16, v176
	v_and_b32_e32 v67, 0xffff0000, v176
	v_pk_mul_f32 v[42:43], v[42:43], v[66:67]
	v_lshlrev_b32_e32 v176, 16, v71
	v_pk_mul_f32 v[66:67], v[0:1], v[42:43]
	v_and_b32_e32 v177, 0xffff0000, v71
	v_cvt_pk_bf16_f32 v32, v66, v67
	v_pk_mul_f32 v[66:67], v[110:111], v[176:177]
	v_rcp_f32_e32 v114, v44
	v_rcp_f32_e32 v115, v45
	v_cvt_pk_bf16_f32 v70, v66, v67
	v_lshlrev_b32_e32 v66, 16, v178
	v_and_b32_e32 v67, 0xffff0000, v178
	v_pk_mul_f32 v[44:45], v[44:45], v[66:67]
	v_lshlrev_b32_e32 v178, 16, v72
	v_pk_mul_f32 v[66:67], v[0:1], v[44:45]
	v_rcp_f32_e32 v116, v46
	v_cvt_pk_bf16_f32 v66, v66, v67
	ds_write2_b32 v227, v32, v66 offset0:24 offset1:90
	v_pk_mul_f32 v[66:67], v[114:115], v[178:179]
	v_rcp_f32_e32 v117, v47
	v_cvt_pk_bf16_f32 v32, v66, v67
	v_add_u32_e32 v66, 0x2c00, v224
	ds_write2_b32 v66, v70, v32 offset0:88 offset1:154
	v_lshlrev_b32_e32 v66, 16, v180
	v_and_b32_e32 v67, 0xffff0000, v180
	v_pk_mul_f32 v[46:47], v[46:47], v[66:67]
	v_lshlrev_b32_e32 v180, 16, v68
	v_pk_mul_f32 v[66:67], v[0:1], v[46:47]
	v_rcp_f32_e32 v118, v48
	v_cvt_pk_bf16_f32 v32, v66, v67
	v_pk_mul_f32 v[66:67], v[116:117], v[180:181]
	v_rcp_f32_e32 v119, v49
	v_cvt_pk_bf16_f32 v68, v66, v67
	v_lshlrev_b32_e32 v66, 16, v182
	v_and_b32_e32 v67, 0xffff0000, v182
	v_pk_mul_f32 v[48:49], v[48:49], v[66:67]
	v_lshlrev_b32_e32 v182, 16, v69
	v_pk_mul_f32 v[66:67], v[0:1], v[48:49]
	v_rcp_f32_e32 v124, v50
	v_cvt_pk_bf16_f32 v66, v66, v67
	ds_write2_b32 v227, v32, v66 offset0:156 offset1:222
	v_pk_mul_f32 v[66:67], v[118:119], v[182:183]
	v_rcp_f32_e32 v125, v51
	v_cvt_pk_bf16_f32 v32, v66, v67
	v_add_u32_e32 v66, 0x2e00, v224
	ds_write2_b32 v66, v68, v32 offset0:92 offset1:158
	v_lshlrev_b32_e32 v66, 16, v126
	v_and_b32_e32 v67, 0xffff0000, v126
	v_pk_mul_f32 v[50:51], v[50:51], v[66:67]
	v_lshlrev_b32_e32 v184, 16, v74
	v_pk_mul_f32 v[66:67], v[0:1], v[50:51]
	v_and_b32_e32 v185, 0xffff0000, v74
	v_cvt_pk_bf16_f32 v32, v66, v67
	v_pk_mul_f32 v[66:67], v[124:125], v[184:185]
	v_rcp_f32_e32 v126, v52
	v_rcp_f32_e32 v127, v53
; __device__ __forceinline__ unsigned cvt_pk_bf16(float lo, float hi) { const f32x2_cv v = {lo, hi}; return __builtin_bit_cast(unsigned, __builtin_convertvector(v, bf16x2_cv)); }
; __device__ __forceinline__ float bf_lo(unsigned u) { return __uint_as_float(u << 16); }
; __device__ __forceinline__ float bf_hi(unsigned u) { return __uint_as_float(u & 0xffff0000u); }
; #define LAS __attribute__((address_space(3)))
; __device__ __forceinline__ void hgrn_prep_item(const bf16_t* Z, const float* lbl, unsigned char* REC, int cidx, int h, LAS unsigned char* wl, int lane) {
;     ...
;     const float ref0 = cv[15][0], ref1 = cv[15][1];
;     const float eref0 = __expf(ref0), eref1 = __expf(ref1), eL0 = __expf(cum[0] - ref0), eL1 = __expf(cum[1] - ref1);
; #pragma unroll
;     for (int t = 0; t < 32; ++t) { cv[t][0] = __expf(cv[t][0] - ref0); cv[t][1] = __expf(cv[t][1] - ref1); }
;     float ri[32][2];
; #pragma unroll
;     for (int t = 0; t < 32; ++t) { ri[t][0] = __builtin_amdgcn_rcpf(cv[t][0]); ri[t][1] = __builtin_amdgcn_rcpf(cv[t][1]); }
; #pragma unroll
;     for (int t = 0; t < 32; ++t) {
;         const float q0 = bf_lo(qraw[t]), q1 = bf_hi(qraw[t]);
;         *(LAS unsigned*)(Xs + t * 132 + k0) = cvt_pk_bf16(q0 * cv[t][0] * eref0, q1 * cv[t][1] * eref1);
;         *(LAS unsigned*)(Ys + t * 132 + k0) = cvt_pk_bf16(bf_lo(omp[t]) * ri[t][0], bf_hi(omp[t]) * ri[t][1]);
;     }
	v_cvt_pk_bf16_f32 v68, v66, v67
	v_lshlrev_b32_e32 v66, 16, v133
	v_and_b32_e32 v67, 0xffff0000, v133
	v_pk_mul_f32 v[52:53], v[52:53], v[66:67]
	v_rcp_f32_e32 v132, v54
	v_pk_mul_f32 v[66:67], v[0:1], v[52:53]
	v_rcp_f32_e32 v133, v55
	v_cvt_pk_bf16_f32 v66, v66, v67
	ds_write2_b32 v228, v32, v66 offset0:32 offset1:98
	v_pk_mul_f32 v[66:67], v[126:127], v[186:187]
	v_rcp_f32_e32 v134, v56
	v_cvt_pk_bf16_f32 v32, v66, v67
	v_add_u32_e32 v66, 0x3000, v224
	ds_write2_b32 v66, v68, v32 offset0:96 offset1:162
	v_lshlrev_b32_e32 v66, 16, v136
	v_and_b32_e32 v67, 0xffff0000, v136
	v_pk_mul_f32 v[54:55], v[54:55], v[66:67]
	v_rcp_f32_e32 v135, v57
	v_pk_mul_f32 v[66:67], v[0:1], v[54:55]
	v_rcp_f32_e32 v136, v58
	v_cvt_pk_bf16_f32 v32, v66, v67
	v_pk_mul_f32 v[66:67], v[132:133], v[188:189]
	v_rcp_f32_e32 v137, v59
	v_cvt_pk_bf16_f32 v68, v66, v67
	v_lshlrev_b32_e32 v66, 16, v139
	v_and_b32_e32 v67, 0xffff0000, v139
	v_pk_mul_f32 v[56:57], v[56:57], v[66:67]
	v_rcp_f32_e32 v138, v60
	v_pk_mul_f32 v[66:67], v[0:1], v[56:57]
	v_rcp_f32_e32 v139, v61
	v_cvt_pk_bf16_f32 v66, v66, v67
	ds_write2_b32 v228, v32, v66 offset0:164 offset1:230
	v_pk_mul_f32 v[66:67], v[134:135], v[190:191]
	v_rcp_f32_e32 v142, v62
	v_cvt_pk_bf16_f32 v32, v66, v67
	v_add_u32_e32 v66, 0x3200, v224
	ds_write2_b32 v66, v68, v32 offset0:100 offset1:166
	v_lshlrev_b32_e32 v66, 16, v144
	v_and_b32_e32 v67, 0xffff0000, v144
	v_pk_mul_f32 v[58:59], v[58:59], v[66:67]
	v_rcp_f32_e32 v143, v63
	v_pk_mul_f32 v[66:67], v[0:1], v[58:59]
	v_rcp_f32_e32 v144, v64
	v_cvt_pk_bf16_f32 v32, v66, v67
	v_pk_mul_f32 v[66:67], v[136:137], v[192:193]
	v_rcp_f32_e32 v145, v65
	v_cvt_pk_bf16_f32 v68, v66, v67
	v_lshlrev_b32_e32 v66, 16, v194
	v_and_b32_e32 v67, 0xffff0000, v194
	v_pk_mul_f32 v[60:61], v[60:61], v[66:67]
	v_lshlrev_b32_e32 v194, 16, v195
	v_pk_mul_f32 v[66:67], v[0:1], v[60:61]
	v_and_b32_e32 v195, 0xffff0000, v195
	v_cvt_pk_bf16_f32 v66, v66, v67
	ds_write2_b32 v229, v32, v66 offset0:40 offset1:106
	v_pk_mul_f32 v[66:67], v[138:139], v[194:195]
	v_rcp_f32_e32 v148, v14
	v_cvt_pk_bf16_f32 v32, v66, v67
	v_add_u32_e32 v66, 0x3400, v224
	ds_write2_b32 v66, v68, v32 offset0:104 offset1:170
	v_lshlrev_b32_e32 v66, 16, v196
	v_and_b32_e32 v67, 0xffff0000, v196
	v_pk_mul_f32 v[62:63], v[62:63], v[66:67]
	v_lshlrev_b32_e32 v196, 16, v197
	v_pk_mul_f32 v[66:67], v[0:1], v[62:63]
	v_and_b32_e32 v197, 0xffff0000, v197
	v_cvt_pk_bf16_f32 v32, v66, v67
	v_pk_mul_f32 v[66:67], v[142:143], v[196:197]
	v_rcp_f32_e32 v149, v15
	v_cvt_pk_bf16_f32 v68, v66, v67
	v_lshlrev_b32_e32 v66, 16, v198
	v_and_b32_e32 v67, 0xffff0000, v198
	v_pk_mul_f32 v[64:65], v[64:65], v[66:67]
	v_lshlrev_b32_e32 v198, 16, v199
	v_pk_mul_f32 v[66:67], v[0:1], v[64:65]
	v_and_b32_e32 v199, 0xffff0000, v199
	v_cvt_pk_bf16_f32 v66, v66, v67
	ds_write2_b32 v229, v32, v66 offset0:172 offset1:238
	v_pk_mul_f32 v[66:67], v[144:145], v[198:199]
	v_rcp_f32_e32 v150, v12
	v_cvt_pk_bf16_f32 v32, v66, v67
	v_add_u32_e32 v66, 0x3600, v224
	ds_write2_b32 v66, v68, v32 offset0:108 offset1:174
	v_lshlrev_b32_e32 v66, 16, v200
	v_and_b32_e32 v67, 0xffff0000, v200
	v_pk_mul_f32 v[66:67], v[14:15], v[66:67]
	v_rcp_f32_e32 v151, v13
	v_pk_mul_f32 v[14:15], v[0:1], v[66:67]
	v_rcp_f32_e32 v152, v10
	v_cvt_pk_bf16_f32 v32, v14, v15
	v_pk_mul_f32 v[14:15], v[148:149], v[202:203]
	v_rcp_f32_e32 v153, v11
	v_cvt_pk_bf16_f32 v70, v14, v15
	v_lshlrev_b32_e32 v14, 16, v204
	v_and_b32_e32 v15, 0xffff0000, v204
	v_pk_mul_f32 v[68:69], v[12:13], v[14:15]
	v_rcp_f32_e32 v154, v8
	v_pk_mul_f32 v[12:13], v[0:1], v[68:69]
	v_rcp_f32_e32 v155, v9
	v_cvt_pk_bf16_f32 v12, v12, v13
	ds_write2_b32 v230, v32, v12 offset0:48 offset1:114
	v_pk_mul_f32 v[12:13], v[150:151], v[206:207]
	v_rcp_f32_e32 v160, v6
	v_cvt_pk_bf16_f32 v12, v12, v13
	v_add_u32_e32 v13, 0x3800, v224
	ds_write2_b32 v13, v70, v12 offset0:112 offset1:178
	v_lshlrev_b32_e32 v12, 16, v208
	v_and_b32_e32 v13, 0xffff0000, v208
	v_pk_mul_f32 v[70:71], v[10:11], v[12:13]
	v_lshlrev_b32_e32 v208, 16, v209
	v_pk_mul_f32 v[10:11], v[0:1], v[70:71]
	v_and_b32_e32 v209, 0xffff0000, v209
	v_cvt_pk_bf16_f32 v12, v10, v11
	v_pk_mul_f32 v[10:11], v[152:153], v[208:209]
	v_rcp_f32_e32 v161, v7
	v_cvt_pk_bf16_f32 v13, v10, v11
	v_lshlrev_b32_e32 v10, 16, v210
	v_and_b32_e32 v11, 0xffff0000, v210
	v_pk_mul_f32 v[72:73], v[8:9], v[10:11]
	v_lshlrev_b32_e32 v210, 16, v211
	v_pk_mul_f32 v[8:9], v[0:1], v[72:73]
	v_and_b32_e32 v211, 0xffff0000, v211
	v_cvt_pk_bf16_f32 v8, v8, v9
	ds_write2_b32 v230, v12, v8 offset0:180 offset1:246
	v_pk_mul_f32 v[8:9], v[154:155], v[210:211]
	v_mul_f32_e32 v2, 0x3fb8aa3b, v2
	v_cvt_pk_bf16_f32 v8, v8, v9
	v_add_u32_e32 v9, 0x3a00, v224
	ds_write2_b32 v9, v13, v8 offset0:116 offset1:182
	v_lshlrev_b32_e32 v8, 16, v212
	v_and_b32_e32 v9, 0xffff0000, v212
	v_pk_mul_f32 v[74:75], v[6:7], v[8:9]
	v_lshlrev_b32_e32 v212, 16, v213
	v_pk_mul_f32 v[6:7], v[0:1], v[74:75]
	v_and_b32_e32 v213, 0xffff0000, v213
	v_cvt_pk_bf16_f32 v8, v6, v7
	v_pk_mul_f32 v[6:7], v[160:161], v[212:213]
	v_mul_f32_e32 v3, 0x3fb8aa3b, v3
	v_rcp_f32_e32 v158, v4
	v_rcp_f32_e32 v159, v5
	v_cvt_pk_bf16_f32 v9, v6, v7
	v_lshlrev_b32_e32 v6, 16, v214
	v_and_b32_e32 v7, 0xffff0000, v214
	v_exp_f32_e32 v2, v2
	v_exp_f32_e32 v3, v3
	v_pk_mul_f32 v[76:77], v[4:5], v[6:7]
	v_lshlrev_b32_e32 v214, 16, v215
	v_pk_mul_f32 v[4:5], v[0:1], v[76:77]
	v_and_b32_e32 v215, 0xffff0000, v215
	v_cvt_pk_bf16_f32 v4, v4, v5
	ds_write2_b32 v231, v8, v4 offset0:56 offset1:122
	v_pk_mul_f32 v[4:5], v[158:159], v[214:215]
	v_rcp_f32_e32 v108, v2
	v_rcp_f32_e32 v109, v3
	v_cvt_pk_bf16_f32 v4, v4, v5
	v_add_u32_e32 v5, 0x3c00, v224
; __device__ __forceinline__ unsigned cvt_pk_bf16(float lo, float hi) { const f32x2_cv v = {lo, hi}; return __builtin_bit_cast(unsigned, __builtin_convertvector(v, bf16x2_cv)); }
; __device__ __forceinline__ float bf_lo(unsigned u) { return __uint_as_float(u << 16); }
; __device__ __forceinline__ float bf_hi(unsigned u) { return __uint_as_float(u & 0xffff0000u); }
; #define LAS __attribute__((address_space(3)))
; __device__ __forceinline__ void hgrn_prep_item(const bf16_t* Z, const float* lbl, unsigned char* REC, int cidx, int h, LAS unsigned char* wl, int lane) {
;     ...
;         *(LAS unsigned*)(Xs + t * 132 + k0) = cvt_pk_bf16(q0 * cv[t][0] * eref0, q1 * cv[t][1] * eref1);
;         *(LAS unsigned*)(Ys + t * 132 + k0) = cvt_pk_bf16(bf_lo(omp[t]) * ri[t][0], bf_hi(omp[t]) * ri[t][1]);
;     }
;     {
;         u32x4* ke = (u32x4*)(R + R_KE + k0 * 64);
; #pragma unroll
;         for (int e = 0; e < 2; ++e) {
;             unsigned kep[16];
; #pragma unroll
;             for (int t2 = 0; t2 < 16; ++t2) kep[t2] = cvt_pk_bf16((e ? bf_hi(omp[2 * t2]) : bf_lo(omp[2 * t2])) * ((e ? eL1 : eL0) * ri[2 * t2][e]), (e ? bf_hi(omp[2 * t2 + 1]) : bf_lo(omp[2 * t2 + 1])) * ((e ? eL1 : eL0) * ri[2 * t2 + 1][e]));
; #pragma unroll
;             for (int q4 = 0; q4 < 4; ++q4) { ke[4 * e + q4] = (u32x4){kep[4 * q4], kep[4 * q4 + 1], kep[4 * q4 + 2], kep[4 * q4 + 3]}; }
	v_exp_f32_e32 v120, v120
	v_exp_f32_e32 v121, v121
	ds_write2_b32 v5, v9, v4 offset0:120 offset1:186
	v_lshlrev_b32_e32 v4, 16, v220
	v_and_b32_e32 v5, 0xffff0000, v220
	v_pk_mul_f32 v[78:79], v[2:3], v[4:5]
	v_lshlrev_b32_e32 v200, 16, v221
	v_pk_mul_f32 v[2:3], v[0:1], v[78:79]
	v_rcp_f32_e32 v112, v120
	v_cvt_pk_bf16_f32 v4, v2, v3
	v_pk_mul_f32 v[2:3], v[108:109], v[200:201]
	v_rcp_f32_e32 v113, v121
	v_cvt_pk_bf16_f32 v5, v2, v3
	v_lshlrev_b32_e32 v2, 16, v222
	v_and_b32_e32 v3, 0xffff0000, v222
	v_pk_mul_f32 v[80:81], v[120:121], v[2:3]
	v_lshlrev_b32_e32 v204, 16, v223
	v_pk_mul_f32 v[0:1], v[0:1], v[80:81]
	v_mov_b32_e32 v2, v122
	v_cvt_pk_bf16_f32 v0, v0, v1
	ds_write2_b32 v231, v4, v0 offset0:188 offset1:254
	v_pk_mul_f32 v[0:1], v[112:113], v[204:205]
	v_mov_b32_e32 v3, v130
	v_cvt_pk_bf16_f32 v0, v0, v1
	v_add_u32_e32 v1, 0x3e00, v224
	ds_write2_b32 v1, v5, v0 offset0:124 offset1:190
	v_mov_b32_e32 v0, v84
	v_mov_b32_e32 v1, v86
	v_pk_mul_f32 v[0:1], v[0:1], v[120:121] op_sel_hi:[1,0]
	v_mov_b32_e32 v4, v140
	v_pk_mul_f32 v[0:1], v[0:1], v[2:3]
	v_mov_b32_e32 v2, v88
	v_mov_b32_e32 v3, v90
	v_pk_mul_f32 v[2:3], v[2:3], v[120:121] op_sel_hi:[1,0]
	v_mov_b32_e32 v5, v146
	v_pk_mul_f32 v[2:3], v[2:3], v[4:5]
	v_cvt_pk_bf16_f32 v0, v0, v1
	v_cvt_pk_bf16_f32 v1, v2, v3
	v_mov_b32_e32 v2, v92
	v_mov_b32_e32 v3, v94
	v_pk_mul_f32 v[2:3], v[2:3], v[120:121] op_sel_hi:[1,0]
	v_mov_b32_e32 v4, v156
	v_mov_b32_e32 v5, v162
	v_pk_mul_f32 v[2:3], v[2:3], v[4:5]
	v_mov_b32_e32 v4, v96
	v_mov_b32_e32 v5, v98
	v_pk_mul_f32 v[4:5], v[4:5], v[120:121] op_sel_hi:[1,0]
	v_mov_b32_e32 v6, v164
	v_mov_b32_e32 v7, v166
	v_pk_mul_f32 v[4:5], v[4:5], v[6:7]
	v_cvt_pk_bf16_f32 v2, v2, v3
	v_cvt_pk_bf16_f32 v3, v4, v5
	v_mov_b32_e32 v4, v100
	v_mov_b32_e32 v5, v102
	v_pk_mul_f32 v[4:5], v[4:5], v[120:121] op_sel_hi:[1,0]
	v_mov_b32_e32 v6, v168
	v_mov_b32_e32 v7, v170
	v_pk_mul_f32 v[4:5], v[4:5], v[6:7]
	v_mov_b32_e32 v6, v104
	v_mov_b32_e32 v7, v106
	v_pk_mul_f32 v[6:7], v[6:7], v[120:121] op_sel_hi:[1,0]
	v_mov_b32_e32 v8, v172
	v_mov_b32_e32 v9, v174
	v_pk_mul_f32 v[6:7], v[6:7], v[8:9]
	v_cvt_pk_bf16_f32 v4, v4, v5
	v_cvt_pk_bf16_f32 v5, v6, v7
	v_mov_b32_e32 v6, v110
	v_mov_b32_e32 v7, v114
	v_pk_mul_f32 v[6:7], v[6:7], v[120:121] op_sel_hi:[1,0]
	v_mov_b32_e32 v8, v176
	v_mov_b32_e32 v9, v178
	v_pk_mul_f32 v[6:7], v[6:7], v[8:9]
	v_mov_b32_e32 v8, v116
	v_mov_b32_e32 v9, v118
	v_pk_mul_f32 v[8:9], v[8:9], v[120:121] op_sel_hi:[1,0]
	v_mov_b32_e32 v10, v180
	v_mov_b32_e32 v11, v182
	v_pk_mul_f32 v[8:9], v[8:9], v[10:11]
	v_cvt_pk_bf16_f32 v6, v6, v7
	v_cvt_pk_bf16_f32 v7, v8, v9
	v_mov_b32_e32 v8, v124
	v_mov_b32_e32 v9, v126
	v_pk_mul_f32 v[8:9], v[8:9], v[120:121] op_sel_hi:[1,0]
	v_mov_b32_e32 v10, v184
	v_mov_b32_e32 v11, v186
	v_pk_mul_f32 v[8:9], v[8:9], v[10:11]
	v_mov_b32_e32 v10, v132
	v_mov_b32_e32 v11, v134
	v_pk_mul_f32 v[10:11], v[10:11], v[120:121] op_sel_hi:[1,0]
	v_mov_b32_e32 v12, v188
	v_mov_b32_e32 v13, v190
	v_pk_mul_f32 v[10:11], v[10:11], v[12:13]
	v_cvt_pk_bf16_f32 v8, v8, v9
	v_cvt_pk_bf16_f32 v9, v10, v11
	v_mov_b32_e32 v10, v136
	v_mov_b32_e32 v11, v138
	v_pk_mul_f32 v[10:11], v[10:11], v[120:121] op_sel_hi:[1,0]
	v_mov_b32_e32 v12, v192
	v_mov_b32_e32 v13, v194
	v_pk_mul_f32 v[10:11], v[10:11], v[12:13]
	v_mov_b32_e32 v12, v142
	v_mov_b32_e32 v13, v144
	v_pk_mul_f32 v[12:13], v[12:13], v[120:121] op_sel_hi:[1,0]
	v_mov_b32_e32 v14, v196
	v_mov_b32_e32 v15, v198
	v_pk_mul_f32 v[12:13], v[12:13], v[14:15]
	v_cvt_pk_bf16_f32 v10, v10, v11
	v_cvt_pk_bf16_f32 v11, v12, v13
	v_mov_b32_e32 v12, v148
	v_mov_b32_e32 v13, v150
	v_pk_mul_f32 v[12:13], v[12:13], v[120:121] op_sel_hi:[1,0]
	v_mov_b32_e32 v14, v202
	v_mov_b32_e32 v15, v206
	v_pk_mul_f32 v[12:13], v[12:13], v[14:15]
	v_mov_b32_e32 v14, v152
	v_mov_b32_e32 v15, v154
	v_pk_mul_f32 v[14:15], v[14:15], v[120:121] op_sel_hi:[1,0]
	v_mov_b32_e32 v220, v208
	v_mov_b32_e32 v221, v210
	v_pk_mul_f32 v[14:15], v[14:15], v[220:221]
	v_cvt_pk_bf16_f32 v12, v12, v13
	v_cvt_pk_bf16_f32 v13, v14, v15
	v_mov_b32_e32 v14, v160
	v_mov_b32_e32 v15, v158
	v_pk_mul_f32 v[14:15], v[14:15], v[120:121] op_sel_hi:[1,0]
	v_mov_b32_e32 v220, v212
	v_mov_b32_e32 v221, v214
	v_pk_mul_f32 v[14:15], v[14:15], v[220:221]
	v_mov_b32_e32 v220, v108
	v_mov_b32_e32 v221, v112
	v_pk_mul_f32 v[220:221], v[120:121], v[220:221] op_sel_hi:[0,1]
	v_mov_b32_e32 v222, v200
	v_mov_b32_e32 v223, v204
	v_pk_mul_f32 v[220:221], v[220:221], v[222:223]
	v_cvt_pk_bf16_f32 v14, v14, v15
	v_cvt_pk_bf16_f32 v15, v220, v221
	v_add_co_u32_e32 v220, vcc, s62, v82
	v_mov_b32_e32 v158, v161
	s_nop 0
	v_addc_co_u32_e32 v221, vcc, -1, v83, vcc
	v_mov_b32_e32 v32, v121
	global_store_dwordx4 v[220:221], v[0:3], off offset:-2052
	global_store_dwordx4 v[220:221], v[4:7], off offset:-2036
	global_store_dwordx4 v[220:221], v[8:11], off offset:-2020
	global_store_dwordx4 v[220:221], v[12:15], off offset:-2004
	v_pk_mul_f32 v[0:1], v[158:159], v[32:33] op_sel_hi:[1,0]
	v_mov_b32_e32 v214, v213
	v_pk_mul_f32 v[0:1], v[0:1], v[214:215]
	v_mov_b32_e32 v154, v153
	v_mov_b32_e32 v150, v149
	v_cvt_pk_bf16_f32 v2, v0, v1
	v_pk_mul_f32 v[0:1], v[154:155], v[32:33] op_sel_hi:[1,0]
	v_mov_b32_e32 v210, v209
	v_pk_mul_f32 v[4:5], v[150:151], v[32:33] op_sel_hi:[1,0]
	v_mov_b32_e32 v206, v203
	v_pk_mul_f32 v[0:1], v[0:1], v[210:211]
	v_pk_mul_f32 v[4:5], v[4:5], v[206:207]
	v_mov_b32_e32 v144, v143
	v_cvt_pk_bf16_f32 v1, v0, v1
	v_cvt_pk_bf16_f32 v0, v4, v5
	v_pk_mul_f32 v[4:5], v[144:145], v[32:33] op_sel_hi:[1,0]
	v_mov_b32_e32 v198, v197
	v_pk_mul_f32 v[4:5], v[4:5], v[198:199]
	v_mov_b32_e32 v138, v137
	v_cvt_pk_bf16_f32 v7, v4, v5
; __device__ __forceinline__ unsigned cvt_pk_bf16(float lo, float hi) { const f32x2_cv v = {lo, hi}; return __builtin_bit_cast(unsigned, __builtin_convertvector(v, bf16x2_cv)); }
; __device__ __forceinline__ float bf_lo(unsigned u) { return __uint_as_float(u << 16); }
; __device__ __forceinline__ float bf_hi(unsigned u) { return __uint_as_float(u & 0xffff0000u); }
; #define LAS __attribute__((address_space(3)))
; #define LDS_WAIT() asm volatile("s_waitcnt lgkmcnt(0)" ::: "memory")
; __device__ __forceinline__ void hgrn_prep_item(const bf16_t* Z, const float* lbl, unsigned char* REC, int cidx, int h, LAS unsigned char* wl, int lane) {
;     ...
;             for (int t2 = 0; t2 < 16; ++t2) kep[t2] = cvt_pk_bf16((e ? bf_hi(omp[2 * t2]) : bf_lo(omp[2 * t2])) * ((e ? eL1 : eL0) * ri[2 * t2][e]), (e ? bf_hi(omp[2 * t2 + 1]) : bf_lo(omp[2 * t2 + 1])) * ((e ? eL1 : eL0) * ri[2 * t2 + 1][e]));
; #pragma unroll
;             for (int q4 = 0; q4 < 4; ++q4) { ke[4 * e + q4] = (u32x4){kep[4 * q4], kep[4 * q4 + 1], kep[4 * q4 + 2], kep[4 * q4 + 3]}; }
;         }
;         float2 dd; dd.x = __expf(cum[0]); dd.y = __expf(cum[1]); *(float2*)(R + R_DEC + k0 * 4) = dd;
;     }
;     LDS_WAIT();
; #pragma unroll
;     for (int tb = 0; tb < 2; ++tb)
; #pragma unroll
;         for (int kk = 0; kk < 4; ++kk) {
;             const u32x2 lo = *(const LAS u32x2*)(Xs + (16 * tb + c16) * 132 + 32 * kk + 4 * g), hi = *(const LAS u32x2*)(Xs + (16 * tb + c16) * 132 + 32 * kk + 16 + 4 * g);
;             *(u32x4*)(R + R_QD + ((tb * 4 + kk) * 64 + lane) * 16) = (u32x4){lo.x, lo.y, hi.x, hi.y};
;         }
;     LDS_WAIT();
; #pragma unroll
;     for (int t = 0; t < 32; ++t) {
;         const float q0 = bf_lo(qraw[t]), q1 = bf_hi(qraw[t]);
;         *(LAS unsigned*)(Xs + t * 132 + k0) = cvt_pk_bf16(q0 * cv[t][0], q1 * cv[t][1]);
	v_pk_mul_f32 v[4:5], v[138:139], v[32:33] op_sel_hi:[1,0]
	v_mov_b32_e32 v194, v193
	v_pk_mul_f32 v[4:5], v[4:5], v[194:195]
	v_mov_b32_e32 v134, v133
	v_mov_b32_e32 v126, v125
	v_cvt_pk_bf16_f32 v6, v4, v5
	v_pk_mul_f32 v[4:5], v[134:135], v[32:33] op_sel_hi:[1,0]
	v_mov_b32_e32 v190, v189
	v_pk_mul_f32 v[8:9], v[126:127], v[32:33] op_sel_hi:[1,0]
	v_mov_b32_e32 v186, v185
	v_pk_mul_f32 v[4:5], v[4:5], v[190:191]
	v_pk_mul_f32 v[8:9], v[8:9], v[186:187]
	v_mov_b32_e32 v118, v117
	v_cvt_pk_bf16_f32 v5, v4, v5
	v_cvt_pk_bf16_f32 v4, v8, v9
	v_pk_mul_f32 v[8:9], v[118:119], v[32:33] op_sel_hi:[1,0]
	v_mov_b32_e32 v182, v181
	v_pk_mul_f32 v[8:9], v[8:9], v[182:183]
	v_mov_b32_e32 v114, v111
	v_cvt_pk_bf16_f32 v11, v8, v9
	v_pk_mul_f32 v[8:9], v[114:115], v[32:33] op_sel_hi:[1,0]
	v_mov_b32_e32 v178, v177
	v_pk_mul_f32 v[8:9], v[8:9], v[178:179]
	v_mov_b32_e32 v106, v105
	v_mov_b32_e32 v102, v101
	v_cvt_pk_bf16_f32 v10, v8, v9
	v_pk_mul_f32 v[8:9], v[106:107], v[32:33] op_sel_hi:[1,0]
	v_mov_b32_e32 v174, v173
	v_pk_mul_f32 v[12:13], v[102:103], v[32:33] op_sel_hi:[1,0]
	v_mov_b32_e32 v170, v169
	v_pk_mul_f32 v[8:9], v[8:9], v[174:175]
	v_pk_mul_f32 v[12:13], v[12:13], v[170:171]
	v_mov_b32_e32 v98, v97
	v_cvt_pk_bf16_f32 v9, v8, v9
	v_cvt_pk_bf16_f32 v8, v12, v13
	v_pk_mul_f32 v[12:13], v[98:99], v[32:33] op_sel_hi:[1,0]
	v_mov_b32_e32 v166, v165
	v_pk_mul_f32 v[12:13], v[12:13], v[166:167]
	v_mov_b32_e32 v94, v93
	v_cvt_pk_bf16_f32 v15, v12, v13
	v_pk_mul_f32 v[12:13], v[94:95], v[32:33] op_sel_hi:[1,0]
	v_mov_b32_e32 v162, v157
	v_pk_mul_f32 v[12:13], v[12:13], v[162:163]
	v_mov_b32_e32 v90, v89
	v_mov_b32_e32 v86, v85
	v_cvt_pk_bf16_f32 v14, v12, v13
	v_pk_mul_f32 v[12:13], v[90:91], v[32:33] op_sel_hi:[1,0]
	v_mov_b32_e32 v146, v141
	v_pk_mul_f32 v[82:83], v[86:87], v[32:33] op_sel_hi:[1,0]
	v_mov_b32_e32 v130, v123
	v_mov_b32_e32 v112, v109
	v_pk_mul_f32 v[12:13], v[12:13], v[146:147]
	v_pk_mul_f32 v[82:83], v[82:83], v[130:131]
	v_pk_mul_f32 v[84:85], v[32:33], v[112:113] op_sel_hi:[0,1]
	v_mov_b32_e32 v204, v201
	v_cvt_pk_bf16_f32 v13, v12, v13
	v_cvt_pk_bf16_f32 v12, v82, v83
	v_pk_mul_f32 v[84:85], v[84:85], v[204:205]
	v_and_b32_e32 v82, 15, v217
	v_cvt_pk_bf16_f32 v3, v84, v85
	global_store_dwordx4 v[220:221], v[12:15], off offset:-1988
	global_store_dwordx4 v[220:221], v[8:11], off offset:-1972
	global_store_dwordx4 v[220:221], v[4:7], off offset:-1956
	global_store_dwordx4 v[220:221], v[0:3], off offset:-1940
	v_lshlrev_b32_e32 v32, 4, v217
	v_lshl_add_u64 v[6:7], s[10:11], 0, v[32:33]
	v_mul_f32_e32 v0, 0x3fb8aa3b, v218
	v_mul_f32_e32 v1, 0x3fb8aa3b, v219
	v_exp_f32_e32 v0, v0
	v_exp_f32_e32 v1, v1
	v_lshrrev_b32_e32 v2, 4, v217
	v_lshlrev_b32_e32 v3, 3, v217
	v_lshlrev_b32_e32 v83, 3, v2
	global_store_dwordx2 v3, v[0:1], s[10:11] offset:-4
	v_mul_u32_u24_e32 v0, 0x108, v82
	s_waitcnt lgkmcnt(0)
	v_add3_u32 v4, s1, v0, v83
	v_lshlrev_b32_e32 v84, 2, v2
	ds_read2_b64 v[0:3], v4 offset1:4
	v_add_co_u32_e32 v8, vcc, s63, v6
	v_add_u32_e32 v32, 0x1000, v4
	s_nop 0
	v_addc_co_u32_e32 v9, vcc, -1, v7, vcc
	s_waitcnt lgkmcnt(0)
	global_store_dwordx4 v[8:9], v[0:3], off offset:-2052
	ds_read2_b64 v[0:3], v4 offset0:8 offset1:12
	v_add_u32_e32 v5, 0x2000, v4
	s_waitcnt lgkmcnt(0)
	global_store_dwordx4 v[8:9], v[0:3], off offset:-1028
	ds_read2_b64 v[0:3], v4 offset0:16 offset1:20
	s_waitcnt lgkmcnt(0)
	global_store_dwordx4 v[8:9], v[0:3], off offset:-4
	ds_read2_b64 v[0:3], v4 offset0:24 offset1:28
	v_add_co_u32_e32 v8, vcc, s64, v6
	s_nop 1
	v_addc_co_u32_e32 v9, vcc, -1, v7, vcc
	s_waitcnt lgkmcnt(0)
	global_store_dwordx4 v[8:9], v[0:3], off offset:-3076
	ds_read2_b64 v[0:3], v32 offset0:16 offset1:20
	v_add_co_u32_e32 v6, vcc, s62, v6
	s_waitcnt lgkmcnt(0)
	global_store_dwordx4 v[8:9], v[0:3], off offset:-2052
	ds_read2_b64 v[0:3], v32 offset0:24 offset1:28
	v_addc_co_u32_e32 v7, vcc, -1, v7, vcc
	v_cmp_gt_u32_e32 vcc, v84, v82
	s_waitcnt lgkmcnt(0)
	global_store_dwordx4 v[8:9], v[0:3], off offset:-1028
	ds_read2_b64 v[0:3], v32 offset0:32 offset1:36
	s_waitcnt lgkmcnt(0)
	global_store_dwordx4 v[8:9], v[0:3], off offset:-4
	ds_read2_b64 v[0:3], v32 offset0:40 offset1:44
	s_waitcnt lgkmcnt(0)
	global_store_dwordx4 v[6:7], v[0:3], off offset:-3076
	s_nop 1
	v_cvt_pk_bf16_f32 v0, v16, v17
	v_cvt_pk_bf16_f32 v1, v18, v19
	s_waitcnt lgkmcnt(0)
; __device__ __forceinline__ unsigned cvt_pk_bf16(float lo, float hi) { const f32x2_cv v = {lo, hi}; return __builtin_bit_cast(unsigned, __builtin_convertvector(v, bf16x2_cv)); }
; __device__ __forceinline__ void hgrn_prep_item(const bf16_t* Z, const float* lbl, unsigned char* REC, int cidx, int h, LAS unsigned char* wl, int lane) {
;     ...
; #pragma unroll
;     for (int t = 0; t < 32; ++t) {
;         const float q0 = bf_lo(qraw[t]), q1 = bf_hi(qraw[t]);
;         *(LAS unsigned*)(Xs + t * 132 + k0) = cvt_pk_bf16(q0 * cv[t][0], q1 * cv[t][1]);
;     }
;     LDS_WAIT();
;     f32x4 a00 = {0.f, 0.f, 0.f, 0.f}, a10 = a00, a11 = a00;
; #pragma unroll
;     for (int kk = 0; kk < 4; ++kk) {
;         bf16x8 qf[2], kf[2];
; #pragma unroll
;         for (int b = 0; b < 2; ++b) {
;             const u32x2 qlo = *(const LAS u32x2*)(Xs + (16 * b + c16) * 132 + 32 * kk + 4 * g), qhi = *(const LAS u32x2*)(Xs + (16 * b + c16) * 132 + 32 * kk + 16 + 4 * g);
;             const u32x2 klo = *(const LAS u32x2*)(Ys + (16 * b + c16) * 132 + 32 * kk + 4 * g), khi = *(const LAS u32x2*)(Ys + (16 * b + c16) * 132 + 32 * kk + 16 + 4 * g);
;             qf[b] = __builtin_bit_cast(bf16x8, ((u32x4){qlo.x, qlo.y, qhi.x, qhi.y})); kf[b] = __builtin_bit_cast(bf16x8, ((u32x4){klo.x, klo.y, khi.x, khi.y}));
;         }
;         a00 = __builtin_amdgcn_mfma_f32_16x16x32_bf16(kf[0], qf[0], a00, 0, 0, 0);
;         a10 = __builtin_amdgcn_mfma_f32_16x16x32_bf16(kf[0], qf[1], a10, 0, 0, 0);
;         a11 = __builtin_amdgcn_mfma_f32_16x16x32_bf16(kf[1], qf[1], a11, 0, 0, 0);
;     }
; #pragma unroll
;     for (int i = 0; i < 4; ++i) if (4 * g + i > c16) { a00[i] = 0.f; a11[i] = 0.f; }
;     u32x2 w;
;     w.x = cvt_pk_bf16(a00[0], a00[1]); w.y = cvt_pk_bf16(a00[2], a00[3]); *(u32x2*)(R + R_A + (c16 * 32 + 4 * g) * 2) = w;
;     w.x = 0u; w.y = 0u; *(u32x2*)(R + R_A + (c16 * 32 + 16 + 4 * g) * 2) = w;
;     w.x = cvt_pk_bf16(a10[0], a10[1]); w.y = cvt_pk_bf16(a10[2], a10[3]); *(u32x2*)(R + R_A + ((16 + c16) * 32 + 4 * g) * 2) = w;
;     w.x = cvt_pk_bf16(a11[0], a11[1]); w.y = cvt_pk_bf16(a11[2], a11[3]); *(u32x2*)(R + R_A + ((16 + c16) * 32 + 16 + 4 * g) * 2) = w;
;     LDS_WAIT();
; }
; __global__ void __launch_bounds__(NTHR, 2) hybrid_fwd(Args args) {
;     ...
;         for (int cidx = bx; cidx < M / 32; cidx += G) hgrn_prep_item(Zb, args.in[I_LB], REC, cidx, wave, lds + wave * PREP_WSTRIDE, lane);
	ds_write2_b32 v224, v0, v1 offset1:66
	v_cvt_pk_bf16_f32 v0, v20, v21
	v_cvt_pk_bf16_f32 v1, v22, v23
	ds_write2_b32 v224, v0, v1 offset0:132 offset1:198
	v_cvt_pk_bf16_f32 v0, v24, v25
	v_cvt_pk_bf16_f32 v1, v26, v27
	ds_write2_b32 v225, v0, v1 offset0:8 offset1:74
	v_cvt_pk_bf16_f32 v0, v28, v29
	v_cvt_pk_bf16_f32 v1, v30, v31
	ds_write2_b32 v225, v0, v1 offset0:140 offset1:206
	v_cvt_pk_bf16_f32 v0, v34, v35
	v_cvt_pk_bf16_f32 v1, v36, v37
	ds_write2_b32 v226, v0, v1 offset0:16 offset1:82
	v_cvt_pk_bf16_f32 v0, v38, v39
	v_cvt_pk_bf16_f32 v1, v40, v41
	ds_write2_b32 v226, v0, v1 offset0:148 offset1:214
	v_cvt_pk_bf16_f32 v0, v42, v43
	v_cvt_pk_bf16_f32 v1, v44, v45
	ds_write2_b32 v227, v0, v1 offset0:24 offset1:90
	v_cvt_pk_bf16_f32 v0, v46, v47
	v_cvt_pk_bf16_f32 v1, v48, v49
	ds_write2_b32 v227, v0, v1 offset0:156 offset1:222
	v_cvt_pk_bf16_f32 v0, v50, v51
	v_cvt_pk_bf16_f32 v1, v52, v53
	ds_write2_b32 v228, v0, v1 offset0:32 offset1:98
	v_cvt_pk_bf16_f32 v0, v54, v55
	v_cvt_pk_bf16_f32 v1, v56, v57
	ds_write2_b32 v228, v0, v1 offset0:164 offset1:230
	v_cvt_pk_bf16_f32 v0, v58, v59
	v_cvt_pk_bf16_f32 v1, v60, v61
	ds_write2_b32 v229, v0, v1 offset0:40 offset1:106
	v_cvt_pk_bf16_f32 v0, v62, v63
	v_cvt_pk_bf16_f32 v1, v64, v65
	ds_write2_b32 v229, v0, v1 offset0:172 offset1:238
	v_cvt_pk_bf16_f32 v0, v66, v67
	v_cvt_pk_bf16_f32 v1, v68, v69
	ds_write2_b32 v230, v0, v1 offset0:48 offset1:114
	v_cvt_pk_bf16_f32 v0, v70, v71
	v_cvt_pk_bf16_f32 v1, v72, v73
	ds_write2_b32 v230, v0, v1 offset0:180 offset1:246
	v_cvt_pk_bf16_f32 v0, v74, v75
	v_cvt_pk_bf16_f32 v1, v76, v77
	ds_write2_b32 v231, v0, v1 offset0:56 offset1:122
	v_cvt_pk_bf16_f32 v0, v78, v79
	v_cvt_pk_bf16_f32 v1, v80, v81
	ds_write2_b32 v231, v0, v1 offset0:188 offset1:254
	s_waitcnt lgkmcnt(0)
	v_add_u32_e32 v30, 0x3000, v4
	ds_read2_b64 v[0:3], v4 offset1:4
	ds_read2_b64 v[6:9], v5 offset0:32 offset1:36
	ds_read2_b64 v[10:13], v32 offset0:16 offset1:20
	ds_read2_b64 v[14:17], v30 offset0:48 offset1:52
	s_waitcnt lgkmcnt(2)
	v_mfma_f32_16x16x32_bf16 v[0:3], v[6:9], v[0:3], 0
	s_waitcnt lgkmcnt(1)
	v_mfma_f32_16x16x32_bf16 v[6:9], v[6:9], v[10:13], 0
	s_waitcnt lgkmcnt(0)
	v_mfma_f32_16x16x32_bf16 v[10:13], v[14:17], v[10:13], 0
	ds_read2_b64 v[14:17], v4 offset0:8 offset1:12
	ds_read2_b64 v[18:21], v5 offset0:40 offset1:44
	ds_read2_b64 v[22:25], v32 offset0:24 offset1:28
	ds_read2_b64 v[26:29], v30 offset0:56 offset1:60
	s_waitcnt lgkmcnt(2)
	v_mfma_f32_16x16x32_bf16 v[0:3], v[18:21], v[14:17], v[0:3]
	s_waitcnt lgkmcnt(1)
	v_mfma_f32_16x16x32_bf16 v[6:9], v[18:21], v[22:25], v[6:9]
	s_waitcnt lgkmcnt(0)
	v_mfma_f32_16x16x32_bf16 v[10:13], v[26:29], v[22:25], v[10:13]
	ds_read2_b64 v[14:17], v4 offset0:16 offset1:20
	ds_read2_b64 v[18:21], v5 offset0:48 offset1:52
	ds_read2_b64 v[22:25], v32 offset0:32 offset1:36
	ds_read2_b64 v[26:29], v30 offset0:64 offset1:68
	s_waitcnt lgkmcnt(2)
	v_mfma_f32_16x16x32_bf16 v[14:17], v[18:21], v[14:17], v[0:3]
	s_waitcnt lgkmcnt(1)
	v_mfma_f32_16x16x32_bf16 v[0:3], v[18:21], v[22:25], v[6:9]
	s_waitcnt lgkmcnt(0)
	v_mfma_f32_16x16x32_bf16 v[18:21], v[26:29], v[22:25], v[10:13]
	ds_read2_b64 v[22:25], v4 offset0:24 offset1:28
	ds_read2_b64 v[4:7], v5 offset0:56 offset1:60
	s_nop 0
	ds_read2_b64 v[8:11], v32 offset0:40 offset1:44
	ds_read2_b64 v[26:29], v30 offset0:72 offset1:76
	s_waitcnt lgkmcnt(2)
	v_mfma_f32_16x16x32_bf16 v[12:15], v[4:7], v[22:25], v[14:17]
	v_mov_b32_e32 v22, s0
	s_waitcnt lgkmcnt(0)
	v_mfma_f32_16x16x32_bf16 v[16:19], v[26:29], v[8:11], v[18:21]
	s_nop 2
	v_mov_b32_e32 v20, s0
	s_nop 0
	v_cndmask_b32_e32 v20, v12, v20, vcc
	s_nop 1
	v_cndmask_b32_e32 v21, v16, v22, vcc
	v_cmp_lt_u32_e32 vcc, v84, v82
	v_mfma_f32_16x16x32_bf16 v[0:3], v[4:7], v[8:11], v[0:3]
	v_lshl_or_b32 v6, v82, 6, v83
	v_cndmask_b32_e32 v12, v20, v12, vcc
	v_or_b32_e32 v20, 2, v84
	v_cndmask_b32_e32 v13, 0, v13, vcc
	v_cndmask_b32_e32 v16, v21, v16, vcc
	v_cndmask_b32_e32 v17, 0, v17, vcc
	v_cmp_gt_u32_e32 vcc, v20, v82
	v_or_b32_e32 v20, 3, v84
	v_cvt_pk_bf16_f32 v4, v12, v13
	v_cndmask_b32_e64 v14, v14, 0, vcc
	v_cndmask_b32_e64 v18, v18, 0, vcc
	v_cmp_gt_u32_e32 vcc, v20, v82
	v_cvt_pk_bf16_f32 v0, v0, v1
	v_cvt_pk_bf16_f32 v1, v2, v3
	v_cndmask_b32_e64 v15, v15, 0, vcc
	v_cndmask_b32_e64 v19, v19, 0, vcc
	v_cvt_pk_bf16_f32 v5, v14, v15
	global_store_dwordx2 v6, v[4:5], s[10:11] offset:-2052
	global_store_dwordx2 v6, v[232:233], s[10:11] offset:-2020
	global_store_dwordx2 v6, v[0:1], s[10:11] offset:-1028
	v_cvt_pk_bf16_f32 v0, v16, v17
	v_cvt_pk_bf16_f32 v1, v18, v19
	global_store_dwordx2 v6, v[0:1], s[10:11] offset:-996
	s_waitcnt lgkmcnt(0)
	s_add_u32 s10, s10, s6
	s_mul_hi_i32 s6, s90, 0x35000
	s_addc_u32 s11, s11, s6
	s_cmpk_gt_i32 s65, 0x43f
	s_cbranch_scc0 .LBB0_434

; #define LAS __attribute__((address_space(3)))
; #define CH_RAWBAR() do { asm volatile("s_waitcnt lgkmcnt(0)" ::: "memory"); __builtin_amdgcn_s_barrier(); asm volatile("" ::: "memory"); } while (0)
; #define CH_WAIT(EX) do { if (wave < 3) CH_WAITN(8 + (EX)); else if (wave == 3) CH_WAITN(6 + (EX)); else CH_WAITN(6); } while (0)
; __device__ __forceinline__ void ch_issue(const unsigned char* Rl, LAS unsigned char* dst, int wave) {
;     __builtin_amdgcn_global_load_lds((const unsigned*)(Rl + wave * 1024), (LAS unsigned*)(dst + wave * 1024), 16, 0, 0);
;     __builtin_amdgcn_global_load_lds((const unsigned*)(Rl + (wave + 8) * 1024), (LAS unsigned*)(dst + (wave + 8) * 1024), 16, 0, 0);
;     __builtin_amdgcn_global_load_lds((const unsigned*)(Rl + (wave + 16) * 1024), (LAS unsigned*)(dst + (wave + 16) * 1024), 16, 0, 0);
;     if (wave < 3) __builtin_amdgcn_global_load_lds((const unsigned*)(Rl + (wave + 24) * 1024), (LAS unsigned*)(dst + (wave + 24) * 1024), 16, 0, 0);
; }
; __device__ __forceinline__ void hgrn_chain(const unsigned char* REC, const float* s0, float* sout, bf16_t* MIX,
;                                            int cidx0, int nchunks, int h, int vhalf, LAS unsigned char* lds, int wave, int lane) {
;     asm volatile("" : "+v"(lane)); __builtin_assume(lane >= 0 && lane < 64);
;     const int c16 = lane & 15, g = lane >> 4, v0 = 64 * vhalf + 16 * (wave & 3);
;     const bool comp = wave < 4;
;     f32x4 S[8];
; #pragma unroll
;     for (int kb = 0; kb < 8; ++kb)
; #pragma unroll
;         for (int i = 0; i < 4; ++i) S[kb][i] = (s0 && comp) ? s0[(size_t)(16 * kb + 4 * g + i) * 128 + v0 + c16] : 0.f;
;     bf16_t* mo = MIX + (size_t)(cidx0 * 32 + c16) * D + 1024 + h * 128 + v0 + 4 * g;
;     const unsigned char* Rl = REC + ((size_t)cidx0 * 8 + h) * REC_STRIDE + lane * 16;
;     const unsigned char* Rlast = Rl + (size_t)(nchunks - 1) * 8 * REC_STRIDE;
;     asm volatile("s_waitcnt vmcnt(0)" ::: "memory");
;     const unsigned char* Ri = Rl;
; #pragma unroll
;     for (int cc = 0; cc < CH_NS - 1; ++cc) { ch_issue(Ri, lds + cc * CH_SLOT, wave); Ri = Ri < Rlast ? Ri + 8 * REC_STRIDE : Rlast; }
;     CH_WAIT(0);
;     CH_RAWBAR();
;     int slot = 0, islot = CH_NS - 1;
.LBB0_595:
	s_lshl_b32 s6, s79, 4
	s_and_b32 s8, s6, 0xffffff00
	s_ashr_i32 s10, s79, 1
	s_ashr_i32 s9, s8, 31
	s_and_b32 s11, s10, 7
	s_lshl_b64 s[6:7], s[8:9], 3
	s_or_b32 s6, s6, s11
	s_mulk_i32 s7, 0x6a00
	s_mul_hi_u32 s9, s6, 0x6a00
	s_add_i32 s9, s9, s7
	s_mulk_i32 s6, 0x6a00
	s_waitcnt vmcnt(0)
	v_mov_b32_e32 v10, v128
	s_add_u32 s6, s94, s6
	s_addc_u32 s7, s95, s9
	v_lshlrev_b32_e32 v120, 4, v10
	v_lshl_add_u64 v[0:1], s[6:7], 0, v[120:121]
	s_waitcnt vmcnt(0)
	s_and_b64 vcc, exec, s[88:89]
	s_cbranch_vccnz .Lch_pro_done
	s_mul_i32 s12, s96, 7
	s_add_i32 s100, s12, 0xffff9000
	s_add_u32 s98, s6, s100
	s_addc_u32 s99, s7, 0
	s_movk_i32 s101, 0x1800
	s_cmp_eq_u32 s96, 0x1c00
	s_cselect_b32 s101, 0x1400, s101
	v_mov_b32_e32 v164, v120
	v_add_u32_e32 v165, 0x400, v120
	v_add_u32_e32 v166, 0x800, v120
	v_add_u32_e32 v167, 0xc00, v120
	v_add_u32_e32 v168, 0x1000, v120
	v_add_u32_e32 v169, 0x1400, v120
	v_add_u32_e32 v170, s101, v120
	s_mov_b64 s[12:13], s[98:99]
	s_mov_b32 s6, s100
	s_mov_b32 m0, s6
	s_nop 0
	global_load_lds_dwordx4 v164, s[12:13]
	s_add_i32 m0, s6, 0x400
	s_nop 0
	global_load_lds_dwordx4 v165, s[12:13]
	s_add_i32 m0, s6, 0x800
	s_nop 0
	global_load_lds_dwordx4 v166, s[12:13]
	s_add_i32 m0, s6, 0xc00
	s_nop 0
	global_load_lds_dwordx4 v167, s[12:13]
	s_add_i32 m0, s6, 0x1000
	s_nop 0
	global_load_lds_dwordx4 v168, s[12:13]
	s_add_i32 m0, s6, 0x1400
	s_nop 0
	global_load_lds_dwordx4 v169, s[12:13]
	s_add_i32 m0, s6, s101
	s_nop 0
	global_load_lds_dwordx4 v170, s[12:13]
	s_add_u32 s12, s98, 0x35000
	s_addc_u32 s13, s99, 0
	s_add_i32 s6, s100, 0x6c00
	s_mov_b32 m0, s6
	s_nop 0
	global_load_lds_dwordx4 v164, s[12:13]
	s_add_i32 m0, s6, 0x400
	s_nop 0
	global_load_lds_dwordx4 v165, s[12:13]
	s_add_i32 m0, s6, 0x800
	s_nop 0
	global_load_lds_dwordx4 v166, s[12:13]
	s_add_i32 m0, s6, 0xc00
	s_nop 0
	global_load_lds_dwordx4 v167, s[12:13]
	s_add_i32 m0, s6, 0x1000
	s_nop 0
	global_load_lds_dwordx4 v168, s[12:13]
	s_add_i32 m0, s6, 0x1400
	s_nop 0
	global_load_lds_dwordx4 v169, s[12:13]
	s_add_i32 m0, s6, s101
	s_nop 0
	global_load_lds_dwordx4 v170, s[12:13]
	s_add_u32 s12, s98, 0x6a000
	s_addc_u32 s13, s99, 0
	s_add_i32 s6, s100, 0xd800
	s_mov_b32 m0, s6
	s_nop 0
	global_load_lds_dwordx4 v164, s[12:13]
	s_add_i32 m0, s6, 0x400
	s_nop 0
	global_load_lds_dwordx4 v165, s[12:13]
	s_add_i32 m0, s6, 0x800
	s_nop 0
	global_load_lds_dwordx4 v166, s[12:13]
	s_add_i32 m0, s6, 0xc00
	s_nop 0
	global_load_lds_dwordx4 v167, s[12:13]
	s_add_i32 m0, s6, 0x1000
	s_nop 0
	global_load_lds_dwordx4 v168, s[12:13]
	s_add_i32 m0, s6, 0x1400
	s_nop 0
	global_load_lds_dwordx4 v169, s[12:13]
	s_add_i32 m0, s6, s101
	s_nop 0
	global_load_lds_dwordx4 v170, s[12:13]
	s_waitcnt vmcnt(14)
.Lch_pro_done:
.LBB0_603:
	s_mov_b64 s[12:13], 0x9f000
	s_lshl_b32 s9, s79, 6
	v_lshl_add_u64 v[44:45], v[0:1], 0, s[12:13]
	s_and_b32 s9, s9, 64
	v_readlane_b32 s12, v236, 30
	s_or_b32 s14, s9, s12
	s_mov_b64 s[12:13], 0x34cb000
	v_and_b32_e32 v50, 15, v10
	v_lshl_add_u64 v[46:47], v[0:1], 0, s[12:13]
	v_lshlrev_b32_e32 v0, 6, v10
	v_or_b32_e32 v68, 0xc00, v0
	v_or_b32_e32 v73, 0x1c00, v0
	v_lshl_or_b32 v0, s8, 5, v50
	v_ashrrev_i32_e32 v1, 31, v0
	v_lshrrev_b32_e32 v2, 1, v10
	v_lshlrev_b64 v[0:1], 12, v[0:1]
	s_lshl_b32 s8, s11, 8
	v_and_b32_e32 v2, 24, v2
	v_lshrrev_b32_e32 v58, 2, v10
	v_or3_b32 v0, v0, s8, v2
	s_lshl_b32 s8, s14, 1
	v_readlane_b32 s9, v236, 44
	v_and_b32_e32 v59, 12, v58
	s_waitcnt lgkmcnt(0)
	s_barrier
	s_add_u32 s8, s9, s8
	v_readlane_b32 s9, v236, 45
	v_or_b32_e32 v57, 16, v59
	v_or_b32_e32 v56, 32, v59
	v_or_b32_e32 v55, 48, v59
	v_or_b32_e32 v54, 64, v59
	v_or_b32_e32 v53, 0x50, v59
	v_or_b32_e32 v52, 0x60, v59
	v_or_b32_e32 v51, 0x70, v59
	v_or_b32_e32 v60, s14, v50
	s_addc_u32 s9, s9, 0
	v_mov_b32_e32 v28, 0
	v_and_b32_e32 v61, 48, v10
	v_lshlrev_b32_e32 v62, 6, v60
	v_lshlrev_b32_e32 v63, 6, v50
	v_lshlrev_b32_e32 v64, 2, v59
	v_lshlrev_b32_e32 v65, 2, v57
	v_lshlrev_b32_e32 v66, 2, v56
	v_lshlrev_b32_e32 v67, 2, v55
	v_lshlrev_b32_e32 v69, 2, v54
	v_lshlrev_b32_e32 v70, 2, v53
	v_lshlrev_b32_e32 v71, 2, v52
	v_lshlrev_b32_e32 v72, 2, v51
	v_lshl_add_u64 v[48:49], s[8:9], 0, v[0:1]
	s_mov_b32 s15, 3
	s_mov_b32 s11, 0
	s_mov_b32 s16, 0
	v_mov_b32_e32 v29, v28
	v_mov_b32_e32 v30, v28
	v_mov_b32_e32 v31, v28
	v_mov_b32_e32 v24, v28
	v_mov_b32_e32 v25, v28
	v_mov_b32_e32 v26, v28
	v_mov_b32_e32 v27, v28
	v_mov_b32_e32 v20, v28
	v_mov_b32_e32 v21, v28
	v_mov_b32_e32 v22, v28
	v_mov_b32_e32 v23, v28
	v_mov_b32_e32 v16, v28
	v_mov_b32_e32 v17, v28
	v_mov_b32_e32 v18, v28
	v_mov_b32_e32 v19, v28
	v_mov_b32_e32 v12, v28
	v_mov_b32_e32 v13, v28
	v_mov_b32_e32 v14, v28
	v_mov_b32_e32 v15, v28
	v_mov_b32_e32 v8, v28
	v_mov_b32_e32 v9, v28
	v_mov_b32_e32 v10, v28
	v_mov_b32_e32 v11, v28
	v_mov_b32_e32 v4, v28
	v_mov_b32_e32 v5, v28
	v_mov_b32_e32 v6, v28
	v_mov_b32_e32 v7, v28
	v_mov_b32_e32 v0, v28
	v_mov_b32_e32 v1, v28
	v_mov_b32_e32 v2, v28
	v_mov_b32_e32 v3, v28
	s_branch .LBB0_605

; __device__ __forceinline__ void hgrn_chain(const unsigned char* REC, const float* s0, float* sout, bf16_t* MIX,
;                                            int cidx0, int nchunks, int h, int vhalf, LAS unsigned char* lds, int wave, int lane) {
;     ...
;     for (int c = 0; c < nchunks; ++c) {
;         ch_issue(Ri, lds + islot * CH_SLOT, wave); Ri = Ri < Rlast ? Ri + 8 * REC_STRIDE : Rlast;
;         islot = islot == CH_NS - 1 ? 0 : islot + 1;
;         const LAS unsigned char* R = lds + slot * CH_SLOT;
;         slot = slot == CH_NS - 1 ? 0 : slot + 1;
;         if (comp) {
;             bf16x8 QDf[2][4], KEf[8], ITf, Af[2]; f32x4 DEC[8];
; #pragma unroll
;             for (int kb = 0; kb < 8; ++kb) { DEC[kb] = *(const LAS f32x4*)(R + R_DEC + (16 * kb + 4 * g) * 4); KEf[kb] = *(const LAS bf16x8*)(R + R_KE + ((16 * kb + c16) * 32 + 8 * g) * 2); }
;             ITf = *(const LAS bf16x8*)(R + R_IT + ((v0 + c16) * 32 + 8 * g) * 2);
; #pragma unroll
;             for (int tb = 0; tb < 2; ++tb) {
;                 Af[tb] = *(const LAS bf16x8*)(R + R_A + ((16 * tb + c16) * 32 + 8 * g) * 2);
; #pragma unroll
;                 for (int kk = 0; kk < 4; ++kk) QDf[tb][kk] = *(const LAS bf16x8*)(R + R_QD + ((tb * 4 + kk) * 64 + lane) * 16);
;             }
;             bf16x8 Sb[4];
; #pragma unroll
;             for (int kk = 0; kk < 4; ++kk) {
;                 u32x4 sb; sb.x = cvt_pk_bf16(S[2 * kk][0], S[2 * kk][1]); sb.y = cvt_pk_bf16(S[2 * kk][2], S[2 * kk][3]);
;                 sb.z = cvt_pk_bf16(S[2 * kk + 1][0], S[2 * kk + 1][1]); sb.w = cvt_pk_bf16(S[2 * kk + 1][2], S[2 * kk + 1][3]);
;                 Sb[kk] = __builtin_bit_cast(bf16x8, sb);
;             }
; #pragma unroll
;             for (int kb = 0; kb < 8; ++kb) S[kb] = __builtin_amdgcn_mfma_f32_16x16x32_bf16(KEf[kb], ITf, S[kb] * DEC[kb], 0, 0, 0);
;             f32x4 o0 = {0.f, 0.f, 0.f, 0.f}, o1 = o0;
;             o0 = __builtin_amdgcn_mfma_f32_16x16x32_bf16(ITf, Af[0], o0, 0, 0, 0);
;             o1 = __builtin_amdgcn_mfma_f32_16x16x32_bf16(ITf, Af[1], o1, 0, 0, 0);
; #pragma unroll
;             for (int kk = 0; kk < 4; ++kk) { o0 = __builtin_amdgcn_mfma_f32_16x16x32_bf16(Sb[kk], QDf[0][kk], o0, 0, 0, 0); o1 = __builtin_amdgcn_mfma_f32_16x16x32_bf16(Sb[kk], QDf[1][kk], o1, 0, 0, 0); }
;             u32x2 w; w.x = cvt_pk_bf16(o0[0], o0[1]); w.y = cvt_pk_bf16(o0[2], o0[3]);
.LBB0_605:
	s_and_b64 vcc, exec, s[88:89]
	s_cbranch_vccnz .Lch_comp_new
	s_add_i32 s12, s11, 3
	s_min_u32 s12, s12, 0xff
	s_mul_i32 s12, s12, 0x35000
	s_add_u32 s12, s98, s12
	s_addc_u32 s13, s99, 0
	s_mul_i32 s6, s15, 0x6c00
	s_add_i32 s6, s6, s100
	s_mov_b32 m0, s6
	s_nop 0
	global_load_lds_dwordx4 v164, s[12:13]
	s_add_i32 m0, s6, 0x400
	s_nop 0
	global_load_lds_dwordx4 v165, s[12:13]
	s_add_i32 m0, s6, 0x800
	s_nop 0
	global_load_lds_dwordx4 v166, s[12:13]
	s_add_i32 m0, s6, 0xc00
	s_nop 0
	global_load_lds_dwordx4 v167, s[12:13]
	s_add_i32 m0, s6, 0x1000
	s_nop 0
	global_load_lds_dwordx4 v168, s[12:13]
	s_add_i32 m0, s6, 0x1400
	s_nop 0
	global_load_lds_dwordx4 v169, s[12:13]
	s_add_i32 m0, s6, s101
	s_nop 0
	global_load_lds_dwordx4 v170, s[12:13]
	s_mov_b64 s[8:9], -1
	s_waitcnt vmcnt(14)
	s_branch .LBB0_604
.Lch_comp_new:
	s_mul_i32 s12, s16, 0x6c00
	v_add_u32_e32 v36, s12, v61
	v_add_u32_e32 v39, s12, v120
	v_add_u32_e32 v37, v36, v63
	v_add_u32_e32 v38, v36, v62
	ds_read_b128 v[32:35], v38 offset:16384
	ds_read_b128 v[164:167], v36 offset:26624
	ds_read_b128 v[196:199], v37 offset:8192
	ds_read_b128 v[168:171], v36 offset:26688
	ds_read_b128 v[200:203], v37 offset:9216
	ds_read_b128 v[172:175], v36 offset:26752
	ds_read_b128 v[204:207], v37 offset:10240
	ds_read_b128 v[176:179], v36 offset:26816
	ds_read_b128 v[208:211], v37 offset:11264
	ds_read_b128 v[180:183], v36 offset:26880
	ds_read_b128 v[212:215], v37 offset:12288
	ds_read_b128 v[184:187], v36 offset:26944
	ds_read_b128 v[216:219], v37 offset:13312
	ds_read_b128 v[188:191], v36 offset:27008
	ds_read_b128 v[220:223], v37 offset:14336
	s_mov_b64 s[8:9], 0
	v_cvt_pk_bf16_f32 v110, v28, v29
	v_cvt_pk_bf16_f32 v111, v30, v31
	v_cvt_pk_bf16_f32 v112, v24, v25
	v_cvt_pk_bf16_f32 v113, v26, v27
	v_cvt_pk_bf16_f32 v114, v20, v21
	v_cvt_pk_bf16_f32 v115, v22, v23
	v_cvt_pk_bf16_f32 v116, v16, v17
	v_cvt_pk_bf16_f32 v117, v18, v19
	v_cvt_pk_bf16_f32 v130, v12, v13
	v_cvt_pk_bf16_f32 v131, v14, v15
	v_cvt_pk_bf16_f32 v132, v8, v9
	v_cvt_pk_bf16_f32 v133, v10, v11
	v_cvt_pk_bf16_f32 v134, v4, v5
	v_cvt_pk_bf16_f32 v135, v6, v7
	v_cvt_pk_bf16_f32 v136, v0, v1
	v_cvt_pk_bf16_f32 v137, v2, v3
	s_waitcnt lgkmcnt(12)
	v_pk_mul_f32 v[28:29], v[28:29], v[164:165]
	v_pk_mul_f32 v[30:31], v[30:31], v[166:167]
	ds_read_b128 v[192:195], v36 offset:27072
	ds_read_b128 v[224:227], v37 offset:15360
	v_mfma_f32_16x16x32_bf16 v[28:31], v[196:199], v[32:35], v[28:31]
	s_waitcnt lgkmcnt(12)
	v_pk_mul_f32 v[24:25], v[24:25], v[168:169]
	v_pk_mul_f32 v[26:27], v[26:27], v[170:171]
	ds_read_b128 v[228:231], v37 offset:24576
	ds_read_b128 v[232:235], v37 offset:25600
	v_mfma_f32_16x16x32_bf16 v[24:27], v[200:203], v[32:35], v[24:27]
	s_waitcnt lgkmcnt(12)
	v_pk_mul_f32 v[20:21], v[20:21], v[172:173]
	v_pk_mul_f32 v[22:23], v[22:23], v[174:175]
	ds_read_b128 v[78:81], v39
	ds_read_b128 v[82:85], v39 offset:4096
	v_mfma_f32_16x16x32_bf16 v[20:23], v[204:207], v[32:35], v[20:23]
	s_waitcnt lgkmcnt(12)
	v_pk_mul_f32 v[16:17], v[16:17], v[176:177]
	v_pk_mul_f32 v[18:19], v[18:19], v[178:179]
	ds_read_b128 v[86:89], v39 offset:1024
	ds_read_b128 v[90:93], v39 offset:5120
	v_mfma_f32_16x16x32_bf16 v[16:19], v[208:211], v[32:35], v[16:19]
	s_waitcnt lgkmcnt(12)
	v_pk_mul_f32 v[12:13], v[12:13], v[180:181]
	v_pk_mul_f32 v[14:15], v[14:15], v[182:183]
	ds_read_b128 v[94:97], v39 offset:2048
	ds_read_b128 v[98:101], v39 offset:6144
	v_mfma_f32_16x16x32_bf16 v[12:15], v[212:215], v[32:35], v[12:15]
	s_waitcnt lgkmcnt(12)
	v_pk_mul_f32 v[8:9], v[8:9], v[184:185]
	v_pk_mul_f32 v[10:11], v[10:11], v[186:187]
	ds_read_b128 v[102:105], v39 offset:3072
	ds_read_b128 v[106:109], v39 offset:7168
	v_mfma_f32_16x16x32_bf16 v[8:11], v[216:219], v[32:35], v[8:11]
	s_waitcnt lgkmcnt(12)
	v_pk_mul_f32 v[4:5], v[4:5], v[188:189]
	v_pk_mul_f32 v[6:7], v[6:7], v[190:191]
	s_nop 1
	v_mfma_f32_16x16x32_bf16 v[4:7], v[220:223], v[32:35], v[4:7]
	s_waitcnt lgkmcnt(10)
	v_pk_mul_f32 v[0:1], v[0:1], v[192:193]
	v_pk_mul_f32 v[2:3], v[2:3], v[194:195]
	s_nop 1
	v_mfma_f32_16x16x32_bf16 v[0:3], v[224:227], v[32:35], v[0:3]
	s_waitcnt lgkmcnt(8)
	v_mfma_f32_16x16x32_bf16 v[138:141], v[32:35], v[228:231], 0
	v_mfma_f32_16x16x32_bf16 v[146:149], v[32:35], v[232:235], 0
	s_waitcnt lgkmcnt(7)
	v_mfma_f32_16x16x32_bf16 v[138:141], v[110:113], v[78:81], v[138:141]
	s_waitcnt lgkmcnt(6)
	v_mfma_f32_16x16x32_bf16 v[146:149], v[110:113], v[82:85], v[146:149]
	s_waitcnt lgkmcnt(5)
	v_mfma_f32_16x16x32_bf16 v[138:141], v[114:117], v[86:89], v[138:141]
	s_waitcnt lgkmcnt(4)
	v_mfma_f32_16x16x32_bf16 v[146:149], v[114:117], v[90:93], v[146:149]
	s_waitcnt lgkmcnt(3)
	v_mfma_f32_16x16x32_bf16 v[138:141], v[130:133], v[94:97], v[138:141]
	s_waitcnt lgkmcnt(2)
	v_mfma_f32_16x16x32_bf16 v[146:149], v[130:133], v[98:101], v[146:149]
	s_waitcnt lgkmcnt(1)
	v_mfma_f32_16x16x32_bf16 v[138:141], v[134:137], v[102:105], v[138:141]
	s_waitcnt lgkmcnt(0)
	v_mfma_f32_16x16x32_bf16 v[146:149], v[134:137], v[106:109], v[146:149]
	s_mov_b32 s12, 0xffff0000
	s_nop 6
	v_cvt_pk_bf16_f32 v36, v138, v139
	v_cvt_pk_bf16_f32 v37, v140, v141
	v_add_co_u32_e32 v38, vcc, s12, v48
	v_cvt_pk_bf16_f32 v40, v146, v147
	s_nop 0
	v_addc_co_u32_e32 v39, vcc, -1, v49, vcc
	v_cvt_pk_bf16_f32 v41, v148, v149
	global_store_dwordx2 v[38:39], v[36:37], off
	global_store_dwordx2 v[48:49], v[40:41], off
	s_branch .LBB0_604

; #define LAS __attribute__((address_space(3)))
; __device__ __forceinline__ void attn_item(const bf16_t* Z, const float* ck, const float* cv, const float* btab, const float* sinks, bf16_t* MIX, int item, LAS unsigned char* lds, int tid, int wave, int lane) {
;     ...
;     for (int i = tid; i < 1024; i += NTHR) bts[i] = btab[(kvh * 4 + (i >> 8)) * 256 + (i & 255)];
;     const int c16 = lane & 15, g = lane >> 4, gh = wave >> 1, qhalf = wave & 1, hq = kvh * 4 + gh;
;     bf16x8 Qf[2][4];
; #pragma unroll
;     for (int nb = 0; nb < 2; ++nb)
; #pragma unroll
;         for (int kk = 0; kk < 4; ++kk) Qf[nb][kk] = *(const bf16x8*)(Z + (size_t)(qrow0 + qhalf * 32 + nb * 16 + c16) * DIN + ZQ + hq * 128 + 32 * kk + 8 * g);
;     const float sink = sinks[hq];
;     __syncthreads();
;     f32x4 sacc[12][2];
; #pragma unroll
;     for (int mb = 0; mb < 12; ++mb) { sacc[mb][0] = (f32x4){0.f, 0.f, 0.f, 0.f}; sacc[mb][1] = (f32x4){0.f, 0.f, 0.f, 0.f};
; #pragma unroll
;         for (int kk = 0; kk < 4; ++kk) { const bf16x8 Kf = *(const LAS bf16x8*)(Ks + (16 * mb + c16) * KS_STRIDE + 32 * kk + 8 * g);
;             sacc[mb][0] = __builtin_amdgcn_mfma_f32_16x16x32_bf16(Kf, Qf[0][kk], sacc[mb][0], 0, 0, 0);
;             sacc[mb][1] = __builtin_amdgcn_mfma_f32_16x16x32_bf16(Kf, Qf[1][kk], sacc[mb][1], 0, 0, 0); } }
.LBB0_642:
	global_load_dword v4, v[0:1], off
	v_add_co_u32_e32 v2, vcc, 0x200, v2
	s_xor_b64 s[8:9], vcc, -1
	s_and_b64 s[8:9], exec, s[8:9]
	v_lshl_add_u64 v[0:1], v[0:1], 0, s[86:87]
	s_or_b64 s[6:7], s[8:9], s[6:7]
	s_waitcnt vmcnt(0)
	ds_write_b32 v3, v4
	v_add_u32_e32 v3, 0x800, v3
	s_andn2_b64 exec, exec, s[6:7]
	s_cbranch_execnz .LBB0_642
	s_or_b64 exec, exec, s[6:7]
	s_lshl_b32 s6, s14, 2
	v_readlane_b32 s7, v236, 37
	s_add_i32 s8, s6, s7
	v_and_b32_e32 v149, 15, v125
	v_readlane_b32 s6, v236, 36
	s_lshl_b32 s76, s8, 8
	v_and_b32_e32 v122, -16, v125
	v_or_b32_e32 v126, s6, v149
	s_add_u32 s6, s68, s76
	s_addc_u32 s7, s69, 0
	v_mov_b32_e32 v123, v121
	v_add_u32_e32 v6, s20, v126
	v_lshl_add_u64 v[4:5], s[6:7], 0, v[122:123]
	v_mad_u64_u32 v[0:1], s[6:7], v6, s74, v[4:5]
	v_add_u32_e32 v6, 16, v6
	v_mad_u64_u32 v[4:5], s[6:7], v6, s74, v[4:5]
	global_load_dwordx4 v[76:79], v[0:1], off
	global_load_dwordx4 v[64:67], v[0:1], off offset:64
	global_load_dwordx4 v[56:59], v[0:1], off offset:128
	s_nop 0
	global_load_dwordx4 v[0:3], v[0:1], off offset:192
	s_nop 0
	global_load_dwordx4 v[84:87], v[4:5], off
	global_load_dwordx4 v[80:83], v[4:5], off offset:64
	global_load_dwordx4 v[68:71], v[4:5], off offset:128
	global_load_dwordx4 v[60:63], v[4:5], off offset:192
	s_lshl_b32 s6, s8, 2
	v_mov_b32_e32 v4, s6
	s_load_dwordx2 s[6:7], s[42:43], 0x88
	s_movk_i32 s8, 0x110
	v_or_b32_e32 v146, 0x70, v125
	v_or_b32_e32 v148, 48, v125
	v_or_b32_e32 v123, 0xb0, v125
	s_waitcnt lgkmcnt(0)
	global_load_dword v150, v4, s[6:7]
	v_and_b32_e32 v4, 48, v125
	v_add_u32_e32 v124, 0, v4
	v_mad_u32_u24 v44, v149, s8, v124
	s_barrier
	ds_read_b128 v[4:7], v44
	ds_read_b128 v[12:15], v44 offset:64
	v_mad_u64_u32 v[46:47], s[6:7], v146, s8, v[124:125]
	v_mad_u64_u32 v[28:29], s[6:7], v148, s8, v[124:125]
	v_lshrrev_b32_e32 v127, 4, v125
	v_mad_u64_u32 v[124:125], s[6:7], v123, s8, v[124:125]
	v_writelane_b32 v236, s20, 54
	v_lshlrev_b32_e32 v120, 3, v127
	v_readlane_b32 s6, v236, 38
	v_or_b32_e32 v147, 64, v149
	s_waitcnt vmcnt(8) lgkmcnt(1)
	v_mfma_f32_16x16x32_bf16 v[8:11], v[4:7], v[76:79], 0
	ds_read_b128 v[16:19], v44 offset:4416
	ds_read_b128 v[20:23], v44 offset:8768
	ds_read_b128 v[32:35], v44 offset:21824
	s_waitcnt vmcnt(4)
	v_mfma_f32_16x16x32_bf16 v[4:7], v[4:7], v[84:87], 0
	ds_read_b128 v[36:39], v44 offset:26176
	ds_read_b128 v[40:43], v46 offset:64
	ds_read_b128 v[24:27], v28 offset:64
	s_waitcnt lgkmcnt(6)
	v_mfma_f32_16x16x32_bf16 v[8:11], v[12:15], v[64:67], v[8:11]
	ds_read_b128 v[108:111], v44 offset:34880
	ds_read_b128 v[112:115], v44 offset:35008
	ds_read_b128 v[116:119], v44 offset:39232
	s_waitcnt vmcnt(3)
	v_mfma_f32_16x16x32_bf16 v[4:7], v[12:15], v[80:83], v[4:7]
	ds_read_b128 v[12:15], v44 offset:128
	ds_read_b128 v[134:137], v44 offset:43584
	s_waitcnt lgkmcnt(1)
	v_mfma_f32_16x16x32_bf16 v[8:11], v[12:15], v[56:59], v[8:11]
	s_waitcnt vmcnt(2)
	v_mfma_f32_16x16x32_bf16 v[4:7], v[12:15], v[68:71], v[4:7]
	ds_read_b128 v[12:15], v44 offset:192
	s_waitcnt lgkmcnt(0)
	v_mfma_f32_16x16x32_bf16 v[48:51], v[12:15], v[0:3], v[8:11]
	s_nop 2
	ds_read_b128 v[8:11], v44 offset:4352
	s_waitcnt vmcnt(1)
	v_mfma_f32_16x16x32_bf16 v[4:7], v[12:15], v[60:63], v[4:7]
	s_waitcnt lgkmcnt(0)
	v_mfma_f32_16x16x32_bf16 v[12:15], v[8:11], v[76:79], 0
	v_mfma_f32_16x16x32_bf16 v[8:11], v[8:11], v[84:87], 0
	v_mfma_f32_16x16x32_bf16 v[12:15], v[16:19], v[64:67], v[12:15]
	v_mfma_f32_16x16x32_bf16 v[8:11], v[16:19], v[80:83], v[8:11]
	ds_read_b128 v[16:19], v44 offset:4480
	s_waitcnt lgkmcnt(0)
	v_mfma_f32_16x16x32_bf16 v[12:15], v[16:19], v[56:59], v[12:15]
	v_mfma_f32_16x16x32_bf16 v[8:11], v[16:19], v[68:71], v[8:11]
	ds_read_b128 v[16:19], v44 offset:4544
	s_waitcnt lgkmcnt(0)
	v_mfma_f32_16x16x32_bf16 v[52:55], v[16:19], v[0:3], v[12:15]
	s_nop 3
	ds_read_b128 v[12:15], v44 offset:8704
	v_mfma_f32_16x16x32_bf16 v[8:11], v[16:19], v[60:63], v[8:11]
	s_waitcnt lgkmcnt(0)
	v_mfma_f32_16x16x32_bf16 v[16:19], v[12:15], v[76:79], 0
	v_mfma_f32_16x16x32_bf16 v[12:15], v[12:15], v[84:87], 0
	v_mfma_f32_16x16x32_bf16 v[16:19], v[20:23], v[64:67], v[16:19]
	v_mfma_f32_16x16x32_bf16 v[12:15], v[20:23], v[80:83], v[12:15]
	ds_read_b128 v[20:23], v44 offset:8832
	s_waitcnt lgkmcnt(0)
	v_mfma_f32_16x16x32_bf16 v[16:19], v[20:23], v[56:59], v[16:19]
	v_mfma_f32_16x16x32_bf16 v[12:15], v[20:23], v[68:71], v[12:15]
	ds_read_b128 v[20:23], v44 offset:8896
	s_waitcnt lgkmcnt(0)
	v_mfma_f32_16x16x32_bf16 v[72:75], v[20:23], v[0:3], v[16:19]
	s_nop 3
	ds_read_b128 v[16:19], v28
	v_mfma_f32_16x16x32_bf16 v[12:15], v[20:23], v[60:63], v[12:15]
	s_waitcnt lgkmcnt(0)
	v_mfma_f32_16x16x32_bf16 v[20:23], v[16:19], v[76:79], 0
	v_mfma_f32_16x16x32_bf16 v[16:19], v[16:19], v[84:87], 0
	v_mfma_f32_16x16x32_bf16 v[20:23], v[24:27], v[64:67], v[20:23]
	v_mfma_f32_16x16x32_bf16 v[16:19], v[24:27], v[80:83], v[16:19]
	ds_read_b128 v[24:27], v28 offset:128
	s_waitcnt lgkmcnt(0)
	v_mfma_f32_16x16x32_bf16 v[20:23], v[24:27], v[56:59], v[20:23]
	v_mfma_f32_16x16x32_bf16 v[16:19], v[24:27], v[68:71], v[16:19]
	ds_read_b128 v[24:27], v28 offset:192
	ds_read_b128 v[28:31], v44 offset:17472
	s_waitcnt lgkmcnt(1)
	v_mfma_f32_16x16x32_bf16 v[88:91], v[24:27], v[0:3], v[20:23]
	s_nop 2
	ds_read_b128 v[20:23], v44 offset:17408
	v_mfma_f32_16x16x32_bf16 v[16:19], v[24:27], v[60:63], v[16:19]
	s_waitcnt lgkmcnt(0)
	v_mfma_f32_16x16x32_bf16 v[24:27], v[20:23], v[76:79], 0
	v_mfma_f32_16x16x32_bf16 v[20:23], v[20:23], v[84:87], 0
	v_mfma_f32_16x16x32_bf16 v[24:27], v[28:31], v[64:67], v[24:27]
	v_mfma_f32_16x16x32_bf16 v[20:23], v[28:31], v[80:83], v[20:23]
	ds_read_b128 v[28:31], v44 offset:17536
	s_waitcnt lgkmcnt(0)
; #define LAS __attribute__((address_space(3)))
; __device__ __forceinline__ void attn_item(const bf16_t* Z, const float* ck, const float* cv, const float* btab, const float* sinks, bf16_t* MIX, int item, LAS unsigned char* lds, int tid, int wave, int lane) {
;     ...
;     f32x4 sacc[12][2];
; #pragma unroll
;     for (int mb = 0; mb < 12; ++mb) { sacc[mb][0] = (f32x4){0.f, 0.f, 0.f, 0.f}; sacc[mb][1] = (f32x4){0.f, 0.f, 0.f, 0.f};
; #pragma unroll
;         for (int kk = 0; kk < 4; ++kk) { const bf16x8 Kf = *(const LAS bf16x8*)(Ks + (16 * mb + c16) * KS_STRIDE + 32 * kk + 8 * g);
;             sacc[mb][0] = __builtin_amdgcn_mfma_f32_16x16x32_bf16(Kf, Qf[0][kk], sacc[mb][0], 0, 0, 0);
;             sacc[mb][1] = __builtin_amdgcn_mfma_f32_16x16x32_bf16(Kf, Qf[1][kk], sacc[mb][1], 0, 0, 0); } }
;     float inv[2];
;     const float scale = 0.08838834764831845f;
; #pragma unroll
;     for (int nb = 0; nb < 2; ++nb) {
;         const int qidx = qhalf * 32 + nb * 16 + c16; float mx = -3.0e38f;
; #pragma unroll
;         for (int mb = 0; mb < 12; ++mb)
; #pragma unroll
;             for (int i = 0; i < 4; ++i) { const int kidx = 16 * mb + 4 * g + i; float s = sacc[mb][nb][i] * scale + bts[gh * 256 + kidx - qidx + 63]; s = kidx < kmin ? -1e30f : s; sacc[mb][nb][i] = s; mx = fmaxf(mx, s); }
	v_mfma_f32_16x16x32_bf16 v[24:27], v[28:31], v[56:59], v[24:27]
	v_mfma_f32_16x16x32_bf16 v[20:23], v[28:31], v[68:71], v[20:23]
	ds_read_b128 v[28:31], v44 offset:17600
	s_waitcnt lgkmcnt(0)
	v_mfma_f32_16x16x32_bf16 v[92:95], v[28:31], v[0:3], v[24:27]
	s_nop 3
	ds_read_b128 v[24:27], v44 offset:21760
	v_mfma_f32_16x16x32_bf16 v[20:23], v[28:31], v[60:63], v[20:23]
	s_waitcnt lgkmcnt(0)
	v_mfma_f32_16x16x32_bf16 v[28:31], v[24:27], v[76:79], 0
	v_mfma_f32_16x16x32_bf16 v[24:27], v[24:27], v[84:87], 0
	v_mfma_f32_16x16x32_bf16 v[28:31], v[32:35], v[64:67], v[28:31]
	v_mfma_f32_16x16x32_bf16 v[24:27], v[32:35], v[80:83], v[24:27]
	ds_read_b128 v[32:35], v44 offset:21888
	s_waitcnt lgkmcnt(0)
	v_mfma_f32_16x16x32_bf16 v[28:31], v[32:35], v[56:59], v[28:31]
	v_mfma_f32_16x16x32_bf16 v[24:27], v[32:35], v[68:71], v[24:27]
	ds_read_b128 v[32:35], v44 offset:21952
	s_waitcnt lgkmcnt(0)
	v_mfma_f32_16x16x32_bf16 v[96:99], v[32:35], v[0:3], v[28:31]
	s_nop 3
	ds_read_b128 v[28:31], v44 offset:26112
	v_mfma_f32_16x16x32_bf16 v[24:27], v[32:35], v[60:63], v[24:27]
	s_waitcnt lgkmcnt(0)
	v_mfma_f32_16x16x32_bf16 v[32:35], v[28:31], v[76:79], 0
	v_mfma_f32_16x16x32_bf16 v[28:31], v[28:31], v[84:87], 0
	v_mfma_f32_16x16x32_bf16 v[32:35], v[36:39], v[64:67], v[32:35]
	v_mfma_f32_16x16x32_bf16 v[28:31], v[36:39], v[80:83], v[28:31]
	ds_read_b128 v[36:39], v44 offset:26240
	s_waitcnt lgkmcnt(0)
	v_mfma_f32_16x16x32_bf16 v[32:35], v[36:39], v[56:59], v[32:35]
	v_mfma_f32_16x16x32_bf16 v[28:31], v[36:39], v[68:71], v[28:31]
	ds_read_b128 v[36:39], v44 offset:26304
	s_waitcnt lgkmcnt(0)
	v_mfma_f32_16x16x32_bf16 v[100:103], v[36:39], v[0:3], v[32:35]
	s_nop 3
	ds_read_b128 v[32:35], v46
	v_mfma_f32_16x16x32_bf16 v[28:31], v[36:39], v[60:63], v[28:31]
	s_waitcnt lgkmcnt(0)
	v_mfma_f32_16x16x32_bf16 v[36:39], v[32:35], v[76:79], 0
	v_mfma_f32_16x16x32_bf16 v[32:35], v[32:35], v[84:87], 0
	v_mfma_f32_16x16x32_bf16 v[36:39], v[40:43], v[64:67], v[36:39]
	v_mfma_f32_16x16x32_bf16 v[32:35], v[40:43], v[80:83], v[32:35]
	ds_read_b128 v[40:43], v46 offset:128
	s_waitcnt lgkmcnt(0)
	v_mfma_f32_16x16x32_bf16 v[36:39], v[40:43], v[56:59], v[36:39]
	v_mfma_f32_16x16x32_bf16 v[32:35], v[40:43], v[68:71], v[32:35]
	ds_read_b128 v[40:43], v46 offset:192
	s_waitcnt lgkmcnt(0)
	v_mfma_f32_16x16x32_bf16 v[104:107], v[40:43], v[0:3], v[36:39]
	s_nop 3
	ds_read_b128 v[36:39], v44 offset:34816
	v_mfma_f32_16x16x32_bf16 v[32:35], v[40:43], v[60:63], v[32:35]
	s_waitcnt lgkmcnt(0)
	v_mfma_f32_16x16x32_bf16 v[40:43], v[36:39], v[76:79], 0
	v_mfma_f32_16x16x32_bf16 v[36:39], v[36:39], v[84:87], 0
	v_mfma_f32_16x16x32_bf16 v[40:43], v[108:111], v[64:67], v[40:43]
	v_mfma_f32_16x16x32_bf16 v[36:39], v[108:111], v[80:83], v[36:39]
	ds_read_b128 v[108:111], v44 offset:34944
	s_waitcnt lgkmcnt(0)
	v_mfma_f32_16x16x32_bf16 v[40:43], v[108:111], v[56:59], v[40:43]
	v_mfma_f32_16x16x32_bf16 v[36:39], v[108:111], v[68:71], v[36:39]
	v_mfma_f32_16x16x32_bf16 v[108:111], v[112:115], v[0:3], v[40:43]
	s_nop 5
	ds_read_b128 v[40:43], v44 offset:39168
	v_mfma_f32_16x16x32_bf16 v[36:39], v[112:115], v[60:63], v[36:39]
	s_waitcnt lgkmcnt(0)
	v_mfma_f32_16x16x32_bf16 v[112:115], v[40:43], v[76:79], 0
	v_mfma_f32_16x16x32_bf16 v[40:43], v[40:43], v[84:87], 0
	v_mfma_f32_16x16x32_bf16 v[112:115], v[116:119], v[64:67], v[112:115]
	v_mfma_f32_16x16x32_bf16 v[40:43], v[116:119], v[80:83], v[40:43]
	ds_read_b128 v[116:119], v44 offset:39296
	s_waitcnt lgkmcnt(0)
	v_mfma_f32_16x16x32_bf16 v[112:115], v[116:119], v[56:59], v[112:115]
	v_mfma_f32_16x16x32_bf16 v[40:43], v[116:119], v[68:71], v[40:43]
	ds_read_b128 v[116:119], v44 offset:39360
	s_waitcnt lgkmcnt(0)
	v_mfma_f32_16x16x32_bf16 v[112:115], v[116:119], v[0:3], v[112:115]
	v_mfma_f32_16x16x32_bf16 v[40:43], v[116:119], v[60:63], v[40:43]
	ds_read_b128 v[116:119], v44 offset:43520
	s_waitcnt lgkmcnt(0)
	v_mfma_f32_16x16x32_bf16 v[130:133], v[116:119], v[76:79], 0
	v_mfma_f32_16x16x32_bf16 v[116:119], v[116:119], v[84:87], 0
	v_mfma_f32_16x16x32_bf16 v[130:133], v[134:137], v[64:67], v[130:133]
	v_mfma_f32_16x16x32_bf16 v[116:119], v[134:137], v[80:83], v[116:119]
	ds_read_b128 v[134:137], v44 offset:43648
	ds_read_b128 v[44:47], v44 offset:43712
	s_waitcnt lgkmcnt(1)
	v_mfma_f32_16x16x32_bf16 v[130:133], v[134:137], v[56:59], v[130:133]
	v_mfma_f32_16x16x32_bf16 v[134:137], v[134:137], v[68:71], v[116:119]
	s_waitcnt lgkmcnt(0)
	v_mfma_f32_16x16x32_bf16 v[116:119], v[44:47], v[0:3], v[130:133]
	s_nop 4
	ds_read_b128 v[130:133], v124
	s_waitcnt lgkmcnt(0)
	v_mfma_f32_16x16x32_bf16 v[76:79], v[130:133], v[76:79], 0
	v_mfma_f32_16x16x32_bf16 v[84:87], v[130:133], v[84:87], 0
	ds_read_b128 v[130:133], v124 offset:64
	s_waitcnt lgkmcnt(0)
	v_mfma_f32_16x16x32_bf16 v[64:67], v[130:133], v[64:67], v[76:79]
	v_mfma_f32_16x16x32_bf16 v[76:79], v[130:133], v[80:83], v[84:87]
	ds_read_b128 v[80:83], v124 offset:128
	s_waitcnt lgkmcnt(0)
	v_mfma_f32_16x16x32_bf16 v[56:59], v[80:83], v[56:59], v[64:67]
	v_mfma_f32_16x16x32_bf16 v[64:67], v[80:83], v[68:71], v[76:79]
	ds_read_b128 v[68:71], v124 offset:192
	v_mfma_f32_16x16x32_bf16 v[44:47], v[44:47], v[60:63], v[134:137]
	s_waitcnt lgkmcnt(0)
	v_mfma_f32_16x16x32_bf16 v[56:59], v[68:71], v[0:3], v[56:59]
	v_mfma_f32_16x16x32_bf16 v[0:3], v[68:71], v[60:63], v[64:67]
	v_and_b32_e32 v61, 64, v144
	v_xor_b32_e32 v60, 16, v144
	v_add_u32_e32 v61, 64, v61
	v_cmp_lt_i32_e32 vcc, v60, v61
	v_lshlrev_b32_e32 v62, 2, v127
	v_cmp_gt_u32_e64 s[68:69], s66, v62
	v_cndmask_b32_e32 v60, v144, v60, vcc
	v_lshlrev_b32_e32 v151, 2, v60
	v_xor_b32_e32 v60, 32, v144
	v_cmp_lt_i32_e32 vcc, v60, v61
	s_nop 1
	v_cndmask_b32_e32 v60, v144, v60, vcc
	v_lshlrev_b32_e32 v152, 2, v60
	v_sub_u32_e32 v60, s6, v126
	v_lshlrev_b32_e32 v60, 2, v60
	v_add3_u32 v156, s78, v60, v122
	ds_read2_b32 v[60:61], v156 offset0:63 offset1:79
	v_readlane_b32 s6, v236, 39
	ds_read2_b32 v[154:155], v156 offset0:191 offset1:207
	s_waitcnt lgkmcnt(1)
; __device__ __forceinline__ void attn_item(const bf16_t* Z, const float* ck, const float* cv, const float* btab, const float* sinks, bf16_t* MIX, int item, LAS unsigned char* lds, int tid, int wave, int lane) {
;     ...
;         const int qidx = qhalf * 32 + nb * 16 + c16; float mx = -3.0e38f;
; #pragma unroll
;         for (int mb = 0; mb < 12; ++mb)
; #pragma unroll
;             for (int i = 0; i < 4; ++i) { const int kidx = 16 * mb + 4 * g + i; float s = sacc[mb][nb][i] * scale + bts[gh * 256 + kidx - qidx + 63]; s = kidx < kmin ? -1e30f : s; sacc[mb][nb][i] = s; mx = fmaxf(mx, s); }
;         mx = fmaxf(mx, __shfl_xor(mx, 16)); mx = fmaxf(mx, __shfl_xor(mx, 32)); mx = fmaxf(mx, sink);
	v_fmamk_f32 v48, v48, 0x3db504f3, v60
	v_sub_u32_e32 v60, s6, v126
	v_lshlrev_b32_e32 v60, 2, v60
	v_add3_u32 v153, s78, v60, v122
	ds_read2_b32 v[78:79], v153 offset0:79 offset1:80
	ds_read2_b32 v[80:81], v153 offset0:80 offset1:81
	ds_read2_b32 v[82:83], v153 offset0:81 offset1:82
	ds_read2_b32 v[84:85], v153 offset0:95 offset1:96
	v_cndmask_b32_e64 v158, v48, v145, s[68:69]
	v_or_b32_e32 v48, 1, v62
	s_waitcnt lgkmcnt(3)
	v_fmamk_f32 v49, v49, 0x3db504f3, v79
	v_cmp_gt_u32_e64 s[70:71], s66, v48
	ds_read2_b32 v[86:87], v153 offset0:96 offset1:97
	ds_read2_b32 v[122:123], v153 offset0:97 offset1:98
	ds_read2_b32 v[124:125], v153 offset0:111 offset1:112
	ds_read2_b32 v[126:127], v153 offset0:112 offset1:113
	v_cndmask_b32_e64 v79, v49, v145, s[70:71]
	v_or_b32_e32 v49, 2, v62
	v_cmp_gt_u32_e64 s[6:7], s66, v49
	v_or_b32_e32 v49, 3, v62
	s_waitcnt lgkmcnt(6)
	v_fmamk_f32 v50, v50, 0x3db504f3, v81
	v_cmp_gt_u32_e64 s[8:9], s66, v49
	v_or_b32_e32 v49, 16, v62
	v_cndmask_b32_e64 v81, v50, v145, s[6:7]
	s_waitcnt lgkmcnt(5)
	v_fmamk_f32 v50, v51, 0x3db504f3, v83
	v_cmp_gt_u32_e64 s[10:11], s66, v49
	v_or_b32_e32 v49, 17, v62
	v_cndmask_b32_e64 v83, v50, v145, s[8:9]
	s_waitcnt lgkmcnt(4)
	v_fmamk_f32 v50, v53, 0x3db504f3, v85
	v_cmp_gt_u32_e64 s[12:13], s66, v49
	v_or_b32_e32 v49, 18, v62
	v_max3_f32 v48, v158, s75, v79
	v_fmac_f32_e32 v61, 0x3db504f3, v52
	v_cndmask_b32_e64 v85, v50, v145, s[12:13]
	s_waitcnt lgkmcnt(3)
	v_fmamk_f32 v50, v54, 0x3db504f3, v87
	v_cmp_gt_u32_e64 s[14:15], s66, v49
	v_or_b32_e32 v49, 19, v62
	v_max3_f32 v48, v48, v81, v83
	v_cndmask_b32_e64 v159, v61, v145, s[10:11]
	v_cndmask_b32_e64 v87, v50, v145, s[14:15]
	s_waitcnt lgkmcnt(2)
	v_fmamk_f32 v50, v55, 0x3db504f3, v123
	v_cmp_gt_u32_e64 s[16:17], s66, v49
	v_max3_f32 v48, v48, v159, v85
	v_or_b32_e32 v51, 32, v62
	v_cndmask_b32_e64 v123, v50, v145, s[16:17]
	v_max3_f32 v50, v48, v87, v123
	ds_read2_b32 v[48:49], v156 offset0:95 offset1:111
	v_cmp_gt_u32_e64 s[18:19], s66, v51
	s_waitcnt lgkmcnt(2)
	v_fmamk_f32 v51, v73, 0x3db504f3, v125
	ds_read2_b32 v[130:131], v153 offset0:113 offset1:114
	ds_read2_b32 v[132:133], v153 offset0:127 offset1:128
	ds_read2_b32 v[134:135], v153 offset0:129 offset1:130
	ds_read2_b32 v[138:139], v153 offset0:161 offset1:162
	s_waitcnt lgkmcnt(4)
	v_fmamk_f32 v48, v72, 0x3db504f3, v48
	v_cndmask_b32_e64 v160, v48, v145, s[18:19]
	v_or_b32_e32 v48, 33, v62
	v_cmp_gt_u32_e64 s[20:21], s66, v48
	v_fmac_f32_e32 v49, 0x3db504f3, v88
	ds_read2_b32 v[136:137], v153 offset0:145 offset1:146
	ds_read2_b32 v[54:55], v153 offset0:239 offset1:240
	v_cndmask_b32_e64 v125, v51, v145, s[20:21]
	v_max3_f32 v48, v50, v160, v125
	v_or_b32_e32 v50, 34, v62
	v_cmp_gt_u32_e64 s[22:23], s66, v50
	v_or_b32_e32 v50, 35, v62
	v_cmp_gt_u32_e64 s[24:25], s66, v50
	v_or_b32_e32 v50, 48, v62
	v_cmp_gt_u32_e64 s[26:27], s66, v50
	s_waitcnt lgkmcnt(4)
	v_fmamk_f32 v50, v89, 0x3db504f3, v133
	ds_read2_b32 v[88:89], v153 offset0:128 offset1:129
	v_fmamk_f32 v51, v74, 0x3db504f3, v127
	v_cndmask_b32_e64 v161, v49, v145, s[26:27]
	v_or_b32_e32 v49, 49, v62
	v_cndmask_b32_e64 v127, v51, v145, s[22:23]
	v_fmamk_f32 v51, v75, 0x3db504f3, v131
	v_cmp_gt_u32_e64 s[28:29], s66, v49
	v_or_b32_e32 v49, 50, v62
	v_cndmask_b32_e64 v131, v51, v145, s[24:25]
	v_cndmask_b32_e64 v133, v50, v145, s[28:29]
	v_cmp_gt_u32_e64 s[30:31], s66, v49
	v_or_b32_e32 v49, 51, v62
	ds_read2_b32 v[74:75], v153 offset0:192 offset1:193
	s_waitcnt lgkmcnt(1)
	v_fmamk_f32 v50, v90, 0x3db504f3, v89
	v_max3_f32 v48, v48, v127, v131
	v_cndmask_b32_e64 v89, v50, v145, s[30:31]
	v_fmamk_f32 v50, v91, 0x3db504f3, v135
	v_cmp_gt_u32_e64 s[34:35], s66, v49
	v_max3_f32 v48, v48, v161, v133
	ds_read2_b32 v[90:91], v153 offset0:143 offset1:144
	ds_read2_b32 v[140:141], v153 offset0:177 offset1:178
	ds_read2_b32 v[64:65], v153 offset0:223 offset1:224
	v_cndmask_b32_e64 v135, v50, v145, s[34:35]
	v_max3_f32 v50, v48, v89, v135
	ds_read2_b32 v[48:49], v156 offset0:127 offset1:143
	v_or_b32_e32 v51, 64, v62
	v_cmp_gt_u32_e64 s[36:37], s66, v51
	s_waitcnt lgkmcnt(3)
	v_fmamk_f32 v51, v93, 0x3db504f3, v91
	ds_read2_b32 v[76:77], v153 offset0:191 offset1:192
	ds_read2_b32 v[60:61], v153 offset0:225 offset1:226
	s_waitcnt lgkmcnt(2)
	v_fmamk_f32 v48, v92, 0x3db504f3, v48
	ds_read2_b32 v[92:93], v153 offset0:144 offset1:145
	v_cndmask_b32_e64 v162, v48, v145, s[36:37]
	v_or_b32_e32 v48, 0x41, v62
	v_cmp_gt_u32_e64 s[38:39], s66, v48
	v_fmac_f32_e32 v49, 0x3db504f3, v96
	ds_read2_b32 v[72:73], v153 offset0:193 offset1:194
	v_cndmask_b32_e64 v91, v51, v145, s[38:39]
	v_max3_f32 v48, v50, v162, v91
	v_or_b32_e32 v50, 0x42, v62
	s_waitcnt lgkmcnt(1)
	v_fmamk_f32 v51, v94, 0x3db504f3, v93
	v_cmp_gt_u32_e64 s[40:41], s66, v50
	v_or_b32_e32 v50, 0x43, v62
	v_cmp_gt_u32_e64 s[42:43], s66, v50
	v_cndmask_b32_e64 v93, v51, v145, s[40:41]
	v_fmamk_f32 v51, v95, 0x3db504f3, v137
	ds_read2_b32 v[94:95], v153 offset0:159 offset1:160
	v_or_b32_e32 v50, 0x50, v62
	v_cmp_gt_u32_e64 s[44:45], s66, v50
	v_cndmask_b32_e64 v137, v51, v145, s[42:43]
	ds_read2_b32 v[70:71], v153 offset0:207 offset1:208
	s_waitcnt lgkmcnt(1)
	v_fmamk_f32 v50, v97, 0x3db504f3, v95
	ds_read2_b32 v[96:97], v153 offset0:160 offset1:161
	v_cndmask_b32_e64 v163, v49, v145, s[44:45]
	v_or_b32_e32 v49, 0x51, v62
	v_cmp_gt_u32_e64 s[46:47], s66, v49
	v_or_b32_e32 v49, 0x52, v62
	v_cmp_gt_u32_e64 s[48:49], s66, v49
	v_cndmask_b32_e64 v95, v50, v145, s[46:47]
	s_waitcnt lgkmcnt(0)
; __device__ __forceinline__ void attn_item(const bf16_t* Z, const float* ck, const float* cv, const float* btab, const float* sinks, bf16_t* MIX, int item, LAS unsigned char* lds, int tid, int wave, int lane) {
;     ...
;         const int qidx = qhalf * 32 + nb * 16 + c16; float mx = -3.0e38f;
; #pragma unroll
;         for (int mb = 0; mb < 12; ++mb)
; #pragma unroll
;             for (int i = 0; i < 4; ++i) { const int kidx = 16 * mb + 4 * g + i; float s = sacc[mb][nb][i] * scale + bts[gh * 256 + kidx - qidx + 63]; s = kidx < kmin ? -1e30f : s; sacc[mb][nb][i] = s; mx = fmaxf(mx, s); }
;         mx = fmaxf(mx, __shfl_xor(mx, 16)); mx = fmaxf(mx, __shfl_xor(mx, 32)); mx = fmaxf(mx, sink);
;         float sum = 0.f;
; #pragma unroll
;         for (int mb = 0; mb < 12; ++mb)
; #pragma unroll
;             for (int i = 0; i < 4; ++i) { const float e = __expf(sacc[mb][nb][i] - mx); sum += e; sacc[mb][nb][i] = e; }
;         sum += __shfl_xor(sum, 16); sum += __shfl_xor(sum, 32); sum += __expf(sink - mx);
;         inv[nb] = 1.0f / sum;
;     }
	v_fmamk_f32 v50, v98, 0x3db504f3, v97
	v_or_b32_e32 v49, 0x53, v62
	v_max3_f32 v48, v48, v93, v137
	v_cndmask_b32_e64 v97, v50, v145, s[48:49]
	v_fmamk_f32 v50, v99, 0x3db504f3, v139
	v_cmp_gt_u32_e64 s[50:51], s66, v49
	v_max3_f32 v48, v48, v163, v95
	ds_read2_b32 v[98:99], v153 offset0:175 offset1:176
	ds_read2_b32 v[68:69], v153 offset0:208 offset1:209
	v_cndmask_b32_e64 v139, v50, v145, s[50:51]
	v_max3_f32 v50, v48, v97, v139
	ds_read2_b32 v[48:49], v156 offset0:159 offset1:175
	v_or_b32_e32 v51, 0x60, v62
	s_waitcnt lgkmcnt(2)
	v_fmamk_f32 v52, v101, 0x3db504f3, v99
	v_cmp_gt_u32_e64 s[52:53], s66, v51
	v_or_b32_e32 v51, 0x61, v62
	s_waitcnt lgkmcnt(0)
	v_fmamk_f32 v48, v100, 0x3db504f3, v48
	ds_read2_b32 v[100:101], v153 offset0:176 offset1:177
	ds_read2_b32 v[66:67], v153 offset0:209 offset1:210
	v_cmp_gt_u32_e64 s[54:55], s66, v51
	v_or_b32_e32 v51, 0x62, v62
	v_cmp_gt_u32_e64 s[56:57], s66, v51
	v_or_b32_e32 v51, 0x63, v62
	v_cmp_gt_u32_e64 s[58:59], s66, v51
	v_or_b32_e32 v51, 0x70, v62
	v_cndmask_b32_e64 v99, v52, v145, s[54:55]
	s_waitcnt lgkmcnt(1)
	v_fmamk_f32 v52, v102, 0x3db504f3, v101
	v_fmac_f32_e32 v49, 0x3db504f3, v104
	v_cmp_gt_u32_e64 s[60:61], s66, v51
	v_cndmask_b32_e64 v48, v48, v145, s[52:53]
	v_cndmask_b32_e64 v101, v52, v145, s[56:57]
	v_fmamk_f32 v52, v103, 0x3db504f3, v141
	v_cndmask_b32_e64 v103, v49, v145, s[60:61]
	v_or_b32_e32 v49, 0x71, v62
	v_max3_f32 v50, v50, v48, v99
	v_cndmask_b32_e64 v102, v52, v145, s[58:59]
	v_fmamk_f32 v51, v105, 0x3db504f3, v77
	v_cmp_gt_u32_e64 s[62:63], s66, v49
	v_max3_f32 v50, v50, v101, v102
	v_fmac_f32_e32 v155, 0x3db504f3, v112
	v_cndmask_b32_e64 v104, v51, v145, s[62:63]
	v_max3_f32 v49, v50, v103, v104
	v_or_b32_e32 v50, 0x72, v62
	v_cmp_gt_u32_e64 s[64:65], s66, v50
	v_or_b32_e32 v50, 0x73, v62
	ds_read2_b32 v[62:63], v153 offset0:224 offset1:225
	ds_read2_b32 v[52:53], v153 offset0:240 offset1:241
	v_fmamk_f32 v51, v106, 0x3db504f3, v75
	v_cndmask_b32_e64 v105, v51, v145, s[64:65]
	v_fmamk_f32 v51, v107, 0x3db504f3, v73
	v_cmp_gt_u32_e64 s[66:67], s66, v50
	v_fmamk_f32 v107, v108, 0x3db504f3, v154
	v_fmamk_f32 v108, v109, 0x3db504f3, v71
	v_cndmask_b32_e64 v106, v51, v145, s[66:67]
	ds_read2_b32 v[50:51], v153 offset0:241 offset1:242
	s_waitcnt lgkmcnt(2)
	v_fmamk_f32 v112, v114, 0x3db504f3, v63
	ds_read_b32 v114, v156 offset:892
	v_max3_f32 v49, v49, v105, v106
	v_max3_f32 v49, v49, v107, v108
	v_fmamk_f32 v109, v110, 0x3db504f3, v69
	v_fmamk_f32 v110, v111, 0x3db504f3, v67
	v_fmamk_f32 v111, v113, 0x3db504f3, v65
	v_fmamk_f32 v113, v115, 0x3db504f3, v61
	s_waitcnt lgkmcnt(0)
	v_fmac_f32_e32 v114, 0x3db504f3, v116
	v_fmamk_f32 v115, v117, 0x3db504f3, v55
	v_fmamk_f32 v116, v118, 0x3db504f3, v53
	v_fmamk_f32 v117, v119, 0x3db504f3, v51
	ds_read2_b32 v[118:119], v156 offset0:239 offset1:240
	v_max3_f32 v49, v49, v109, v110
	ds_read2_b32 v[156:157], v156 offset0:241 offset1:242
	v_max3_f32 v49, v49, v155, v111
	v_max3_f32 v49, v49, v112, v113
	v_max3_f32 v49, v49, v114, v115
	v_max3_f32 v49, v49, v116, v117
	s_waitcnt lgkmcnt(1)
	v_fmamk_f32 v118, v56, 0x3db504f3, v118
	v_fmac_f32_e32 v119, 0x3db504f3, v57
	v_max3_f32 v49, v49, v118, v119
	s_waitcnt lgkmcnt(0)
	v_fmamk_f32 v141, v58, 0x3db504f3, v156
	v_fmac_f32_e32 v157, 0x3db504f3, v59
	v_max3_f32 v49, v49, v141, v157
	ds_bpermute_b32 v51, v151, v49
	v_fmac_f32_e32 v52, 0x3db504f3, v1
	ds_read_b32 v1, v153 offset:968
	v_fmac_f32_e32 v78, 0x3db504f3, v8
	v_fmac_f32_e32 v80, 0x3db504f3, v9
	s_waitcnt lgkmcnt(1)
	v_max_f32_e32 v51, v51, v51
	v_max_f32_e32 v49, v49, v51
	ds_bpermute_b32 v51, v152, v49
	v_fmac_f32_e32 v82, 0x3db504f3, v10
	v_fmac_f32_e32 v84, 0x3db504f3, v12
	v_fmac_f32_e32 v86, 0x3db504f3, v13
	v_fmac_f32_e32 v122, 0x3db504f3, v14
	s_waitcnt vmcnt(0) lgkmcnt(0)
	v_max3_f32 v154, v49, v51, v150
	v_sub_f32_e32 v49, v158, v154
	v_mul_f32_e32 v49, 0x3fb8aa3b, v49
	v_sub_f32_e32 v51, v79, v154
	v_exp_f32_e32 v49, v49
	v_mul_f32_e32 v51, 0x3fb8aa3b, v51
	v_exp_f32_e32 v51, v51
	v_sub_f32_e32 v61, v123, v154
	v_add_f32_e32 v53, 0, v49
	v_mul_f32_e32 v61, 0x3fb8aa3b, v61
	v_add_f32_e32 v55, v51, v53
	v_sub_f32_e32 v53, v81, v154
	v_mul_f32_e32 v53, 0x3fb8aa3b, v53
	v_exp_f32_e32 v53, v53
	v_exp_f32_e32 v61, v61
	v_sub_f32_e32 v77, v135, v154
	v_mul_f32_e32 v77, 0x3fb8aa3b, v77
	v_add_f32_e32 v56, v53, v55
	v_sub_f32_e32 v55, v83, v154
	v_mul_f32_e32 v55, 0x3fb8aa3b, v55
	v_exp_f32_e32 v55, v55
	v_exp_f32_e32 v77, v77
	v_sub_f32_e32 v48, v48, v154
	v_mul_f32_e32 v48, 0x3fb8aa3b, v48
	v_add_f32_e32 v57, v55, v56
	v_sub_f32_e32 v56, v159, v154
	v_mul_f32_e32 v56, 0x3fb8aa3b, v56
	v_exp_f32_e32 v56, v56
	v_sub_f32_e32 v123, v157, v154
	v_mul_f32_e32 v123, 0x3fb8aa3b, v123
	v_exp_f32_e32 v123, v123
	v_add_f32_e32 v58, v56, v57
	v_sub_f32_e32 v57, v85, v154
	v_mul_f32_e32 v57, 0x3fb8aa3b, v57
	v_exp_f32_e32 v57, v57
	v_fmac_f32_e32 v124, 0x3db504f3, v16
	v_fmac_f32_e32 v126, 0x3db504f3, v17
	v_fmac_f32_e32 v130, 0x3db504f3, v18
	v_add_f32_e32 v59, v57, v58
	v_sub_f32_e32 v58, v87, v154
	v_mul_f32_e32 v58, 0x3fb8aa3b, v58
	v_exp_f32_e32 v58, v58
	v_fmac_f32_e32 v132, 0x3db504f3, v20
	v_fmac_f32_e32 v88, 0x3db504f3, v21
	v_cndmask_b32_e64 v21, v88, v145, s[38:39]
	v_add_f32_e32 v59, v58, v59
	v_add_f32_e32 v63, v61, v59
	v_sub_f32_e32 v59, v160, v154
	v_mul_f32_e32 v59, 0x3fb8aa3b, v59
	v_exp_f32_e32 v59, v59
	v_fmac_f32_e32 v134, 0x3db504f3, v22
	v_cndmask_b32_e64 v20, v134, v145, s[40:41]
	v_fmac_f32_e32 v90, 0x3db504f3, v24
	v_add_f32_e32 v65, v59, v63
	v_sub_f32_e32 v63, v125, v154
	v_mul_f32_e32 v63, 0x3fb8aa3b, v63
	v_exp_f32_e32 v63, v63
	v_fmac_f32_e32 v92, 0x3db504f3, v25
	v_cndmask_b32_e64 v18, v90, v145, s[44:45]
; __device__ __forceinline__ unsigned cvt_pk_bf16(float lo, float hi) { const f32x2_cv v = {lo, hi}; return __builtin_bit_cast(unsigned, __builtin_convertvector(v, bf16x2_cv)); }
; __device__ __forceinline__ void attn_item(const bf16_t* Z, const float* ck, const float* cv, const float* btab, const float* sinks, bf16_t* MIX, int item, LAS unsigned char* lds, int tid, int wave, int lane) {
;     ...
;             for (int i = 0; i < 4; ++i) { const int kidx = 16 * mb + 4 * g + i; float s = sacc[mb][nb][i] * scale + bts[gh * 256 + kidx - qidx + 63]; s = kidx < kmin ? -1e30f : s; sacc[mb][nb][i] = s; mx = fmaxf(mx, s); }
;         mx = fmaxf(mx, __shfl_xor(mx, 16)); mx = fmaxf(mx, __shfl_xor(mx, 32)); mx = fmaxf(mx, sink);
;         float sum = 0.f;
; #pragma unroll
;         for (int mb = 0; mb < 12; ++mb)
; #pragma unroll
;             for (int i = 0; i < 4; ++i) { const float e = __expf(sacc[mb][nb][i] - mx); sum += e; sacc[mb][nb][i] = e; }
;         sum += __shfl_xor(sum, 16); sum += __shfl_xor(sum, 32); sum += __expf(sink - mx);
;         inv[nb] = 1.0f / sum;
;     }
;     bf16x8 Pf[2][6];
; #pragma unroll
;     for (int nb = 0; nb < 2; ++nb)
; #pragma unroll
;         for (int ks = 0; ks < 6; ++ks) { u32x4 p; p.x = cvt_pk_bf16(sacc[2 * ks][nb][0], sacc[2 * ks][nb][1]); p.y = cvt_pk_bf16(sacc[2 * ks][nb][2], sacc[2 * ks][nb][3]);
;             p.z = cvt_pk_bf16(sacc[2 * ks + 1][nb][0], sacc[2 * ks + 1][nb][1]); p.w = cvt_pk_bf16(sacc[2 * ks + 1][nb][2], sacc[2 * ks + 1][nb][3]); Pf[nb][ks] = __builtin_bit_cast(bf16x8, p); }
	v_cndmask_b32_e64 v17, v92, v145, s[46:47]
	v_add_f32_e32 v67, v63, v65
	v_sub_f32_e32 v65, v127, v154
	v_mul_f32_e32 v65, 0x3fb8aa3b, v65
	v_exp_f32_e32 v65, v65
	v_fmac_f32_e32 v136, 0x3db504f3, v26
	v_cndmask_b32_e64 v16, v136, v145, s[48:49]
	v_fmac_f32_e32 v94, 0x3db504f3, v28
	v_add_f32_e32 v69, v65, v67
	v_sub_f32_e32 v67, v131, v154
	v_mul_f32_e32 v67, 0x3fb8aa3b, v67
	v_exp_f32_e32 v67, v67
	v_fmac_f32_e32 v96, 0x3db504f3, v29
	v_cndmask_b32_e64 v14, v94, v145, s[52:53]
	v_cndmask_b32_e64 v13, v96, v145, s[54:55]
	v_add_f32_e32 v71, v67, v69
	v_sub_f32_e32 v69, v161, v154
	v_mul_f32_e32 v69, 0x3fb8aa3b, v69
	v_exp_f32_e32 v69, v69
	v_fmac_f32_e32 v138, 0x3db504f3, v30
	v_cndmask_b32_e64 v12, v138, v145, s[56:57]
	v_fmac_f32_e32 v98, 0x3db504f3, v32
	v_add_f32_e32 v73, v69, v71
	v_sub_f32_e32 v71, v133, v154
	v_mul_f32_e32 v71, 0x3fb8aa3b, v71
	v_exp_f32_e32 v71, v71
	v_fmac_f32_e32 v100, 0x3db504f3, v33
	v_cndmask_b32_e64 v10, v98, v145, s[60:61]
	v_cndmask_b32_e64 v9, v100, v145, s[62:63]
	v_add_f32_e32 v75, v71, v73
	v_sub_f32_e32 v73, v89, v154
	v_mul_f32_e32 v73, 0x3fb8aa3b, v73
	v_exp_f32_e32 v73, v73
	v_fmac_f32_e32 v140, 0x3db504f3, v34
	v_cndmask_b32_e64 v8, v140, v145, s[64:65]
	v_fmac_f32_e32 v76, 0x3db504f3, v36
	v_add_f32_e32 v75, v73, v75
	v_add_f32_e32 v79, v77, v75
	v_sub_f32_e32 v75, v162, v154
	v_mul_f32_e32 v75, 0x3fb8aa3b, v75
	v_exp_f32_e32 v75, v75
	v_fmac_f32_e32 v74, 0x3db504f3, v37
	v_fmac_f32_e32 v72, 0x3db504f3, v38
	v_fmac_f32_e32 v70, 0x3db504f3, v40
	v_add_f32_e32 v81, v75, v79
	v_sub_f32_e32 v79, v91, v154
	v_mul_f32_e32 v79, 0x3fb8aa3b, v79
	v_exp_f32_e32 v79, v79
	v_fmac_f32_e32 v68, 0x3db504f3, v41
	v_fmac_f32_e32 v66, 0x3db504f3, v42
	v_fmac_f32_e32 v64, 0x3db504f3, v44
	v_add_f32_e32 v83, v79, v81
	v_sub_f32_e32 v81, v93, v154
	v_mul_f32_e32 v81, 0x3fb8aa3b, v81
	v_exp_f32_e32 v81, v81
	v_sub_f32_e32 v93, v139, v154
	v_mul_f32_e32 v93, 0x3fb8aa3b, v93
	v_exp_f32_e32 v93, v93
	v_add_f32_e32 v85, v81, v83
	v_sub_f32_e32 v83, v137, v154
	v_mul_f32_e32 v83, 0x3fb8aa3b, v83
	v_exp_f32_e32 v83, v83
	v_cndmask_b32_e64 v139, v82, v145, s[14:15]
	v_cndmask_b32_e64 v82, v130, v145, s[30:31]
	v_fmac_f32_e32 v62, 0x3db504f3, v45
	v_add_f32_e32 v87, v83, v85
	v_sub_f32_e32 v85, v163, v154
	v_mul_f32_e32 v85, 0x3fb8aa3b, v85
	v_exp_f32_e32 v85, v85
	v_fmac_f32_e32 v60, 0x3db504f3, v46
	v_fmac_f32_e32 v54, 0x3db504f3, v0
	v_fmac_f32_e32 v50, 0x3db504f3, v2
	v_add_f32_e32 v89, v85, v87
	v_sub_f32_e32 v87, v95, v154
	v_mul_f32_e32 v87, 0x3fb8aa3b, v87
	v_exp_f32_e32 v87, v87
	v_fmac_f32_e32 v1, 0x3db504f3, v3
	v_cvt_pk_bf16_f32 v42, v56, v57
	v_add_u32_e32 v56, 0, v120
	v_add_f32_e32 v91, v87, v89
	v_sub_f32_e32 v89, v97, v154
	v_mul_f32_e32 v89, 0x3fb8aa3b, v89
	v_exp_f32_e32 v89, v89
	v_sub_f32_e32 v97, v101, v154
	v_mul_f32_e32 v97, 0x3fb8aa3b, v97
	v_exp_f32_e32 v97, v97
	v_add_f32_e32 v91, v89, v91
	v_add_f32_e32 v95, v93, v91
	v_exp_f32_e32 v91, v48
	v_sub_f32_e32 v101, v103, v154
	v_mul_f32_e32 v101, 0x3fb8aa3b, v101
	v_exp_f32_e32 v101, v101
	v_add_f32_e32 v48, v91, v95
	v_sub_f32_e32 v95, v99, v154
	v_mul_f32_e32 v95, 0x3fb8aa3b, v95
	v_exp_f32_e32 v95, v95
	v_sub_f32_e32 v99, v102, v154
	v_mul_f32_e32 v99, 0x3fb8aa3b, v99
	v_exp_f32_e32 v99, v99
	v_sub_f32_e32 v102, v104, v154
	v_mul_f32_e32 v102, 0x3fb8aa3b, v102
	v_sub_f32_e32 v103, v105, v154
	v_add_f32_e32 v48, v95, v48
	v_exp_f32_e32 v102, v102
	v_mul_f32_e32 v103, 0x3fb8aa3b, v103
	v_sub_f32_e32 v104, v106, v154
	v_add_f32_e32 v48, v97, v48
	v_exp_f32_e32 v103, v103
	v_mul_f32_e32 v104, 0x3fb8aa3b, v104
	v_sub_f32_e32 v105, v107, v154
	v_add_f32_e32 v48, v99, v48
	v_exp_f32_e32 v104, v104
	v_mul_f32_e32 v105, 0x3fb8aa3b, v105
	v_sub_f32_e32 v106, v108, v154
	v_add_f32_e32 v48, v101, v48
	v_exp_f32_e32 v105, v105
	v_mul_f32_e32 v106, 0x3fb8aa3b, v106
	v_sub_f32_e32 v107, v109, v154
	v_add_f32_e32 v48, v102, v48
	v_exp_f32_e32 v106, v106
	v_mul_f32_e32 v107, 0x3fb8aa3b, v107
	v_sub_f32_e32 v108, v110, v154
	v_add_f32_e32 v48, v103, v48
	v_exp_f32_e32 v107, v107
	v_mul_f32_e32 v108, 0x3fb8aa3b, v108
	v_sub_f32_e32 v109, v155, v154
	v_add_f32_e32 v48, v104, v48
	v_exp_f32_e32 v108, v108
	v_mul_f32_e32 v109, 0x3fb8aa3b, v109
	v_sub_f32_e32 v110, v111, v154
	v_add_f32_e32 v48, v105, v48
	v_exp_f32_e32 v109, v109
	v_mul_f32_e32 v110, 0x3fb8aa3b, v110
	v_sub_f32_e32 v111, v112, v154
	v_add_f32_e32 v48, v106, v48
	v_exp_f32_e32 v110, v110
	v_mul_f32_e32 v111, 0x3fb8aa3b, v111
	v_sub_f32_e32 v112, v113, v154
	v_add_f32_e32 v48, v107, v48
	v_exp_f32_e32 v111, v111
	v_mul_f32_e32 v112, 0x3fb8aa3b, v112
	v_sub_f32_e32 v113, v114, v154
	v_add_f32_e32 v48, v108, v48
	v_exp_f32_e32 v112, v112
	v_mul_f32_e32 v113, 0x3fb8aa3b, v113
	v_sub_f32_e32 v114, v115, v154
	v_add_f32_e32 v48, v109, v48
	v_exp_f32_e32 v113, v113
	v_mul_f32_e32 v114, 0x3fb8aa3b, v114
	v_sub_f32_e32 v115, v116, v154
	v_add_f32_e32 v48, v110, v48
	v_exp_f32_e32 v114, v114
	v_mul_f32_e32 v115, 0x3fb8aa3b, v115
	v_sub_f32_e32 v116, v117, v154
	v_add_f32_e32 v48, v111, v48
	v_exp_f32_e32 v115, v115
	v_mul_f32_e32 v116, 0x3fb8aa3b, v116
	v_sub_f32_e32 v117, v118, v154
	v_add_f32_e32 v48, v112, v48
	v_exp_f32_e32 v116, v116
	v_mul_f32_e32 v117, 0x3fb8aa3b, v117
	v_sub_f32_e32 v118, v119, v154
	v_add_f32_e32 v48, v113, v48
	v_exp_f32_e32 v117, v117
	v_mul_f32_e32 v118, 0x3fb8aa3b, v118
	v_sub_f32_e32 v119, v141, v154
	v_add_f32_e32 v48, v114, v48
	v_exp_f32_e32 v118, v118
	v_mul_f32_e32 v119, 0x3fb8aa3b, v119
	v_add_f32_e32 v48, v115, v48
	v_exp_f32_e32 v119, v119
	v_add_f32_e32 v48, v116, v48
	v_add_f32_e32 v48, v117, v48
	v_add_f32_e32 v48, v118, v48
	v_add_f32_e32 v48, v119, v48
	v_add_f32_e32 v48, v123, v48
	ds_bpermute_b32 v125, v151, v48
	v_cndmask_b32_e64 v141, v80, v145, s[12:13]
	v_cvt_pk_bf16_f32 v40, v49, v51
	v_cvt_pk_bf16_f32 v32, v59, v63
	v_cvt_pk_bf16_f32 v33, v65, v67
	s_waitcnt lgkmcnt(0)
; __device__ __forceinline__ void attn_item(const bf16_t* Z, const float* ck, const float* cv, const float* btab, const float* sinks, bf16_t* MIX, int item, LAS unsigned char* lds, int tid, int wave, int lane) {
;     ...
;     for (int nb = 0; nb < 2; ++nb) {
;         const int qidx = qhalf * 32 + nb * 16 + c16; float mx = -3.0e38f;
; #pragma unroll
;         for (int mb = 0; mb < 12; ++mb)
; #pragma unroll
;             for (int i = 0; i < 4; ++i) { const int kidx = 16 * mb + 4 * g + i; float s = sacc[mb][nb][i] * scale + bts[gh * 256 + kidx - qidx + 63]; s = kidx < kmin ? -1e30f : s; sacc[mb][nb][i] = s; mx = fmaxf(mx, s); }
;         mx = fmaxf(mx, __shfl_xor(mx, 16)); mx = fmaxf(mx, __shfl_xor(mx, 32)); mx = fmaxf(mx, sink);
;         float sum = 0.f;
; #pragma unroll
;         for (int mb = 0; mb < 12; ++mb)
; #pragma unroll
;             for (int i = 0; i < 4; ++i) { const float e = __expf(sacc[mb][nb][i] - mx); sum += e; sacc[mb][nb][i] = e; }
;         sum += __shfl_xor(sum, 16); sum += __shfl_xor(sum, 32); sum += __expf(sink - mx);
;         inv[nb] = 1.0f / sum;
;     }
	v_add_f32_e32 v48, v48, v125
	ds_bpermute_b32 v125, v152, v48
	v_cvt_pk_bf16_f32 v34, v69, v71
	v_cvt_pk_bf16_f32 v41, v53, v55
	v_cvt_pk_bf16_f32 v24, v75, v79
	v_cvt_pk_bf16_f32 v25, v81, v83
	s_waitcnt lgkmcnt(0)
	v_add_f32_e32 v48, v48, v125
	v_sub_f32_e32 v125, v150, v154
	v_mul_f32_e32 v125, 0x3fb8aa3b, v125
	v_exp_f32_e32 v125, v125
	ds_read2_b32 v[154:155], v153 offset0:63 offset1:64
	v_cvt_pk_bf16_f32 v26, v85, v87
	v_mov_b32_e32 v55, v121
	v_add_f32_e32 v48, v125, v48
	v_div_scale_f32 v125, vcc, v48, v48, 1.0
	v_rcp_f32_e32 v127, v125
	s_waitcnt lgkmcnt(0)
	v_fmac_f32_e32 v155, 0x3db504f3, v5
	v_fmamk_f32 v4, v4, 0x3db504f3, v154
	v_fma_f32 v131, -v125, v127, 1.0
	v_fmac_f32_e32 v127, v131, v127
	v_div_scale_f32 v131, vcc, 1.0, v48, 1.0
	v_mul_f32_e32 v133, v131, v127
	v_fma_f32 v135, -v125, v133, v131
	v_fmac_f32_e32 v133, v135, v127
	v_fma_f32 v125, -v125, v133, v131
	v_div_fmas_f32 v125, v125, v127, v133
	v_div_fixup_f32 v48, v125, v48, 1.0
	v_cndmask_b32_e64 v125, v155, v145, s[70:71]
	ds_read2_b32 v[154:155], v153 offset0:65 offset1:66
	v_cndmask_b32_e64 v127, v4, v145, s[68:69]
	v_max3_f32 v4, v127, s75, v125
	v_cndmask_b32_e64 v135, v84, v145, s[18:19]
	v_cndmask_b32_e64 v133, v86, v145, s[20:21]
	s_waitcnt lgkmcnt(0)
	v_fmamk_f32 v5, v6, 0x3db504f3, v154
	v_fmac_f32_e32 v155, 0x3db504f3, v7
	v_cndmask_b32_e64 v156, v5, v145, s[6:7]
	v_cndmask_b32_e64 v155, v155, v145, s[8:9]
	v_max3_f32 v4, v4, v156, v155
	v_cndmask_b32_e64 v154, v78, v145, s[10:11]
	v_max3_f32 v6, v4, v154, v141
	ds_read2_b32 v[4:5], v153 offset0:82 offset1:98
	v_cndmask_b32_e64 v131, v122, v145, s[22:23]
	v_cndmask_b32_e64 v86, v124, v145, s[26:27]
	v_cndmask_b32_e64 v84, v126, v145, s[28:29]
	v_cndmask_b32_e64 v78, v132, v145, s[36:37]
	s_waitcnt lgkmcnt(0)
	v_fmamk_f32 v4, v11, 0x3db504f3, v4
	v_cndmask_b32_e64 v137, v4, v145, s[16:17]
	v_max3_f32 v4, v6, v139, v137
	v_fmac_f32_e32 v5, 0x3db504f3, v15
	v_max3_f32 v4, v4, v135, v133
	v_cndmask_b32_e64 v122, v5, v145, s[24:25]
	v_max3_f32 v4, v4, v131, v122
	v_max3_f32 v6, v4, v86, v84
	ds_read2_b32 v[4:5], v153 offset0:114 offset1:130
	s_movk_i32 s8, 0x188
	v_mad_u32_u24 v49, v149, s8, v56
	v_add_u32_e32 v51, 0xc800, v49
	v_readlane_b32 s70, v236, 20
	s_waitcnt lgkmcnt(0)
	v_fmamk_f32 v4, v19, 0x3db504f3, v4
	v_cndmask_b32_e64 v80, v4, v145, s[34:35]
	v_max3_f32 v4, v6, v82, v80
	v_fmac_f32_e32 v5, 0x3db504f3, v23
	v_max3_f32 v4, v4, v78, v21
	v_cndmask_b32_e64 v19, v5, v145, s[42:43]
	v_max3_f32 v4, v4, v20, v19
	v_max3_f32 v6, v4, v18, v17
	ds_read2_b32 v[4:5], v153 offset0:146 offset1:162
	v_readlane_b32 s71, v236, 21
	v_readlane_b32 s68, v236, 18
	v_readlane_b32 s42, v236, 4
	v_readlane_b32 s69, v236, 19
	s_waitcnt lgkmcnt(0)
	v_fmamk_f32 v4, v27, 0x3db504f3, v4
	v_cndmask_b32_e64 v15, v4, v145, s[50:51]
	v_max3_f32 v4, v6, v16, v15
	ds_read2_b32 v[6:7], v153 offset0:178 offset1:194
	v_fmac_f32_e32 v5, 0x3db504f3, v31
	v_max3_f32 v4, v4, v14, v13
	v_cndmask_b32_e64 v11, v5, v145, s[58:59]
	v_max3_f32 v4, v4, v12, v11
	s_waitcnt lgkmcnt(0)
	v_fmamk_f32 v5, v35, 0x3db504f3, v6
	v_max3_f32 v4, v4, v10, v9
	v_cndmask_b32_e64 v6, v5, v145, s[66:67]
	v_max3_f32 v4, v4, v8, v6
	v_max3_f32 v4, v4, v76, v74
	v_fmac_f32_e32 v7, 0x3db504f3, v39
	v_max3_f32 v4, v4, v72, v7
	v_max3_f32 v22, v4, v70, v68
	ds_read2_b32 v[4:5], v153 offset0:210 offset1:226
	v_cvt_pk_bf16_f32 v35, v73, v77
	v_cvt_pk_bf16_f32 v27, v89, v93
	v_readlane_b32 s43, v236, 5
	s_waitcnt lgkmcnt(0)
	v_fmamk_f32 v4, v43, 0x3db504f3, v4
	v_max3_f32 v22, v22, v66, v4
	v_max3_f32 v22, v22, v64, v62
	v_fmac_f32_e32 v5, 0x3db504f3, v47
	v_max3_f32 v22, v22, v60, v5
	v_max3_f32 v0, v22, v54, v52
	v_max3_f32 v0, v0, v50, v1
	ds_bpermute_b32 v2, v151, v0
	v_cvt_pk_bf16_f32 v43, v58, v61
	s_waitcnt lgkmcnt(0)
	v_max_f32_e32 v2, v2, v2
	v_max_f32_e32 v0, v0, v2
	ds_bpermute_b32 v2, v152, v0
	s_waitcnt lgkmcnt(0)
	v_max3_f32 v0, v0, v2, v150
	v_sub_f32_e32 v3, v125, v0
	v_mul_f32_e32 v3, 0x3fb8aa3b, v3
	v_exp_f32_e32 v23, v3
	v_sub_f32_e32 v3, v156, v0
	v_mul_f32_e32 v3, 0x3fb8aa3b, v3
	v_exp_f32_e32 v28, v3
	v_sub_f32_e32 v3, v155, v0
	v_mul_f32_e32 v3, 0x3fb8aa3b, v3
	v_exp_f32_e32 v29, v3
	v_sub_f32_e32 v3, v154, v0
	v_mul_f32_e32 v3, 0x3fb8aa3b, v3
	v_exp_f32_e32 v30, v3
	v_sub_f32_e32 v3, v141, v0
	v_mul_f32_e32 v3, 0x3fb8aa3b, v3
	v_exp_f32_e32 v31, v3
	v_sub_f32_e32 v3, v139, v0
	v_mul_f32_e32 v3, 0x3fb8aa3b, v3
	v_exp_f32_e32 v36, v3
	v_sub_f32_e32 v3, v137, v0
	v_mul_f32_e32 v3, 0x3fb8aa3b, v3
	v_exp_f32_e32 v37, v3
	v_sub_f32_e32 v3, v135, v0
	v_mul_f32_e32 v3, 0x3fb8aa3b, v3
	v_exp_f32_e32 v38, v3
	v_sub_f32_e32 v3, v133, v0
	v_mul_f32_e32 v3, 0x3fb8aa3b, v3
	v_exp_f32_e32 v39, v3
	v_sub_f32_e32 v3, v131, v0
	v_mul_f32_e32 v3, 0x3fb8aa3b, v3
	v_exp_f32_e32 v88, v3
	v_sub_f32_e32 v3, v122, v0
	v_mul_f32_e32 v3, 0x3fb8aa3b, v3
	v_exp_f32_e32 v90, v3
	v_sub_f32_e32 v3, v86, v0
	v_mul_f32_e32 v3, 0x3fb8aa3b, v3
	v_exp_f32_e32 v86, v3
	v_sub_f32_e32 v3, v84, v0
	v_mul_f32_e32 v3, 0x3fb8aa3b, v3
	v_exp_f32_e32 v84, v3
	v_sub_f32_e32 v3, v82, v0
	v_mul_f32_e32 v3, 0x3fb8aa3b, v3
	v_exp_f32_e32 v82, v3
	v_sub_f32_e32 v3, v80, v0
	v_mul_f32_e32 v3, 0x3fb8aa3b, v3
	v_exp_f32_e32 v80, v3
	v_sub_f32_e32 v3, v78, v0
	v_mul_f32_e32 v3, 0x3fb8aa3b, v3
	v_exp_f32_e32 v78, v3
	v_sub_f32_e32 v3, v21, v0
	v_mul_f32_e32 v3, 0x3fb8aa3b, v3
	v_exp_f32_e32 v21, v3
	v_sub_f32_e32 v3, v20, v0
	v_mul_f32_e32 v3, 0x3fb8aa3b, v3
	v_exp_f32_e32 v20, v3
	v_sub_f32_e32 v3, v19, v0
	v_mul_f32_e32 v3, 0x3fb8aa3b, v3
	v_exp_f32_e32 v92, v3
	v_sub_f32_e32 v3, v18, v0
	v_mul_f32_e32 v3, 0x3fb8aa3b, v3
	v_exp_f32_e32 v94, v3
	v_sub_f32_e32 v3, v17, v0
	v_sub_f32_e32 v2, v127, v0
; __device__ __forceinline__ unsigned cvt_pk_bf16(float lo, float hi) { const f32x2_cv v = {lo, hi}; return __builtin_bit_cast(unsigned, __builtin_convertvector(v, bf16x2_cv)); }
; #define LAS __attribute__((address_space(3)))
; __device__ __forceinline__ void attn_item(const bf16_t* Z, const float* ck, const float* cv, const float* btab, const float* sinks, bf16_t* MIX, int item, LAS unsigned char* lds, int tid, int wave, int lane) {
;     ...
;         float sum = 0.f;
; #pragma unroll
;         for (int mb = 0; mb < 12; ++mb)
; #pragma unroll
;             for (int i = 0; i < 4; ++i) { const float e = __expf(sacc[mb][nb][i] - mx); sum += e; sacc[mb][nb][i] = e; }
;         sum += __shfl_xor(sum, 16); sum += __shfl_xor(sum, 32); sum += __expf(sink - mx);
;         inv[nb] = 1.0f / sum;
;     }
;     bf16x8 Pf[2][6];
; #pragma unroll
;     for (int nb = 0; nb < 2; ++nb)
; #pragma unroll
;         for (int ks = 0; ks < 6; ++ks) { u32x4 p; p.x = cvt_pk_bf16(sacc[2 * ks][nb][0], sacc[2 * ks][nb][1]); p.y = cvt_pk_bf16(sacc[2 * ks][nb][2], sacc[2 * ks][nb][3]);
;             p.z = cvt_pk_bf16(sacc[2 * ks + 1][nb][0], sacc[2 * ks + 1][nb][1]); p.w = cvt_pk_bf16(sacc[2 * ks + 1][nb][2], sacc[2 * ks + 1][nb][3]); Pf[nb][ks] = __builtin_bit_cast(bf16x8, p); }
; #pragma unroll
;     for (int db = 0; db < 8; ++db) {
;         f32x4 o0 = {0.f, 0.f, 0.f, 0.f}, o1 = {0.f, 0.f, 0.f, 0.f};
; #pragma unroll
;         for (int ks = 0; ks < 6; ++ks) { const LAS bf16_t* vp = VTs + (16 * db + c16) * VT_STRIDE + 32 * ks + 4 * g; const u32x2 lo = *(const LAS u32x2*)vp, hi = *(const LAS u32x2*)(vp + 16);
;             const bf16x8 Vf = __builtin_bit_cast(bf16x8, ((u32x4){lo.x, lo.y, hi.x, hi.y}));
;             o0 = __builtin_amdgcn_mfma_f32_16x16x32_bf16(Vf, Pf[0][ks], o0, 0, 0, 0);
;             o1 = __builtin_amdgcn_mfma_f32_16x16x32_bf16(Vf, Pf[1][ks], o1, 0, 0, 0); }
	v_mul_f32_e32 v3, 0x3fb8aa3b, v3
	v_mul_f32_e32 v2, 0x3fb8aa3b, v2
	v_exp_f32_e32 v96, v3
	v_sub_f32_e32 v3, v16, v0
	v_exp_f32_e32 v22, v2
	v_mul_f32_e32 v3, 0x3fb8aa3b, v3
	v_exp_f32_e32 v98, v3
	v_sub_f32_e32 v3, v15, v0
	v_mul_f32_e32 v3, 0x3fb8aa3b, v3
	v_exp_f32_e32 v15, v3
	v_sub_f32_e32 v3, v14, v0
	v_add_f32_e32 v2, 0, v22
	v_mul_f32_e32 v3, 0x3fb8aa3b, v3
	v_add_f32_e32 v2, v23, v2
	v_exp_f32_e32 v14, v3
	v_sub_f32_e32 v3, v13, v0
	v_add_f32_e32 v2, v28, v2
	v_mul_f32_e32 v3, 0x3fb8aa3b, v3
	v_add_f32_e32 v2, v29, v2
	v_exp_f32_e32 v13, v3
	v_sub_f32_e32 v3, v12, v0
	v_add_f32_e32 v2, v30, v2
	v_mul_f32_e32 v3, 0x3fb8aa3b, v3
	v_add_f32_e32 v2, v31, v2
	v_exp_f32_e32 v12, v3
	v_sub_f32_e32 v3, v11, v0
	v_add_f32_e32 v2, v36, v2
	v_mul_f32_e32 v3, 0x3fb8aa3b, v3
	v_add_f32_e32 v2, v37, v2
	v_exp_f32_e32 v100, v3
	v_sub_f32_e32 v3, v10, v0
	v_add_f32_e32 v2, v38, v2
	v_mul_f32_e32 v3, 0x3fb8aa3b, v3
	v_add_f32_e32 v2, v39, v2
	v_exp_f32_e32 v122, v3
	v_sub_f32_e32 v3, v9, v0
	v_add_f32_e32 v2, v88, v2
	v_mul_f32_e32 v3, 0x3fb8aa3b, v3
	v_add_f32_e32 v2, v90, v2
	v_exp_f32_e32 v124, v3
	v_sub_f32_e32 v3, v8, v0
	v_add_f32_e32 v2, v86, v2
	v_mul_f32_e32 v3, 0x3fb8aa3b, v3
	v_add_f32_e32 v2, v84, v2
	v_exp_f32_e32 v125, v3
	v_sub_f32_e32 v3, v6, v0
	v_add_f32_e32 v2, v82, v2
	v_mul_f32_e32 v3, 0x3fb8aa3b, v3
	v_add_f32_e32 v2, v80, v2
	v_exp_f32_e32 v6, v3
	v_sub_f32_e32 v3, v76, v0
	v_add_f32_e32 v2, v78, v2
	v_mul_f32_e32 v3, 0x3fb8aa3b, v3
	v_add_f32_e32 v2, v21, v2
	v_exp_f32_e32 v76, v3
	v_sub_f32_e32 v3, v74, v0
	v_add_f32_e32 v2, v20, v2
	v_mul_f32_e32 v3, 0x3fb8aa3b, v3
	v_add_f32_e32 v2, v92, v2
	v_exp_f32_e32 v74, v3
	v_sub_f32_e32 v3, v72, v0
	v_add_f32_e32 v2, v94, v2
	v_mul_f32_e32 v3, 0x3fb8aa3b, v3
	v_add_f32_e32 v2, v96, v2
	v_exp_f32_e32 v72, v3
	v_sub_f32_e32 v3, v7, v0
	v_add_f32_e32 v2, v98, v2
	v_mul_f32_e32 v3, 0x3fb8aa3b, v3
	v_add_f32_e32 v2, v15, v2
	v_exp_f32_e32 v7, v3
	v_sub_f32_e32 v3, v70, v0
	v_add_f32_e32 v2, v14, v2
	v_mul_f32_e32 v3, 0x3fb8aa3b, v3
	v_add_f32_e32 v2, v13, v2
	v_exp_f32_e32 v70, v3
	v_sub_f32_e32 v3, v68, v0
	v_add_f32_e32 v2, v12, v2
	v_mul_f32_e32 v3, 0x3fb8aa3b, v3
	v_add_f32_e32 v2, v100, v2
	v_exp_f32_e32 v68, v3
	v_sub_f32_e32 v3, v66, v0
	v_add_f32_e32 v2, v122, v2
	v_mul_f32_e32 v3, 0x3fb8aa3b, v3
	v_add_f32_e32 v2, v124, v2
	v_exp_f32_e32 v66, v3
	v_sub_f32_e32 v3, v4, v0
	v_add_f32_e32 v2, v125, v2
	v_mul_f32_e32 v3, 0x3fb8aa3b, v3
	v_add_f32_e32 v2, v6, v2
	v_exp_f32_e32 v4, v3
	v_sub_f32_e32 v3, v64, v0
	v_add_f32_e32 v2, v76, v2
	v_mul_f32_e32 v3, 0x3fb8aa3b, v3
	v_add_f32_e32 v2, v74, v2
	v_exp_f32_e32 v64, v3
	v_sub_f32_e32 v3, v62, v0
	v_add_f32_e32 v2, v72, v2
	v_mul_f32_e32 v3, 0x3fb8aa3b, v3
	v_add_f32_e32 v2, v7, v2
	v_exp_f32_e32 v62, v3
	v_sub_f32_e32 v3, v60, v0
	v_add_f32_e32 v2, v70, v2
	v_mul_f32_e32 v3, 0x3fb8aa3b, v3
	v_add_f32_e32 v2, v68, v2
	v_exp_f32_e32 v60, v3
	v_sub_f32_e32 v3, v5, v0
	v_add_f32_e32 v2, v66, v2
	v_mul_f32_e32 v3, 0x3fb8aa3b, v3
	v_add_f32_e32 v2, v4, v2
	v_exp_f32_e32 v5, v3
	v_add_f32_e32 v2, v64, v2
	v_add_f32_e32 v2, v62, v2
	v_add_f32_e32 v2, v60, v2
	v_add_f32_e32 v2, v5, v2
	v_cvt_pk_bf16_f32 v5, v60, v5
	ds_read2_b64 v[58:61], v51 offset0:128 offset1:132
	v_sub_f32_e32 v3, v54, v0
	v_mul_f32_e32 v3, 0x3fb8aa3b, v3
	v_cvt_pk_bf16_f32 v45, v28, v29
	v_cvt_pk_bf16_f32 v46, v30, v31
	v_cvt_pk_bf16_f32 v29, v20, v92
	v_cvt_pk_bf16_f32 v31, v98, v15
	v_cvt_pk_bf16_f32 v20, v14, v13
	v_cvt_pk_bf16_f32 v14, v70, v68
	v_cvt_pk_bf16_f32 v15, v66, v4
	ds_read2_b64 v[66:69], v51 offset0:136 offset1:140
	v_exp_f32_e32 v54, v3
	v_sub_f32_e32 v3, v52, v0
	v_mul_f32_e32 v3, 0x3fb8aa3b, v3
	v_exp_f32_e32 v52, v3
	v_sub_f32_e32 v3, v50, v0
	v_mul_f32_e32 v3, 0x3fb8aa3b, v3
	v_sub_f32_e32 v1, v1, v0
	v_cvt_pk_bf16_f32 v44, v22, v23
	v_cvt_pk_bf16_f32 v47, v36, v37
	v_exp_f32_e32 v126, v3
	v_mul_f32_e32 v1, 0x3fb8aa3b, v1
	v_cvt_pk_bf16_f32 v4, v64, v62
	s_waitcnt lgkmcnt(1)
	v_mfma_f32_16x16x32_bf16 v[62:65], v[58:61], v[40:43], 0
	v_exp_f32_e32 v127, v1
	v_add_f32_e32 v2, v54, v2
	v_add_f32_e32 v2, v52, v2
	v_mfma_f32_16x16x32_bf16 v[58:61], v[58:61], v[44:47], 0
	v_cvt_pk_bf16_f32 v36, v38, v39
	v_cvt_pk_bf16_f32 v37, v88, v90
	v_cvt_pk_bf16_f32 v38, v86, v84
	v_cvt_pk_bf16_f32 v39, v82, v80
	v_add_f32_e32 v2, v126, v2
	s_waitcnt lgkmcnt(0)
	v_mfma_f32_16x16x32_bf16 v[62:65], v[66:69], v[32:35], v[62:65]
	v_add_f32_e32 v1, v127, v2
	ds_bpermute_b32 v2, v151, v1
	v_sub_f32_e32 v0, v150, v0
	v_mfma_f32_16x16x32_bf16 v[58:61], v[66:69], v[36:39], v[58:61]
	ds_read2_b64 v[66:69], v51 offset0:144 offset1:148
	v_cvt_pk_bf16_f32 v28, v78, v21
	s_waitcnt lgkmcnt(1)
	v_add_f32_e32 v1, v1, v2
	ds_bpermute_b32 v2, v152, v1
	v_cvt_pk_bf16_f32 v30, v94, v96
	v_mul_f32_e32 v0, 0x3fb8aa3b, v0
	s_waitcnt lgkmcnt(1)
	v_mfma_f32_16x16x32_bf16 v[62:65], v[66:69], v[24:27], v[62:65]
	v_exp_f32_e32 v0, v0
	s_waitcnt lgkmcnt(0)
	v_add_f32_e32 v1, v1, v2
	v_cvt_pk_bf16_f32 v16, v91, v95
	v_mfma_f32_16x16x32_bf16 v[58:61], v[66:69], v[28:31], v[58:61]
	ds_read2_b64 v[66:69], v51 offset0:152 offset1:156
	v_add_f32_e32 v0, v0, v1
	v_div_scale_f32 v1, s[6:7], v0, v0, 1.0
	v_rcp_f32_e32 v2, v1
	v_cvt_pk_bf16_f32 v17, v97, v99
	v_cvt_pk_bf16_f32 v18, v101, v102
	v_cvt_pk_bf16_f32 v19, v103, v104
	v_cvt_pk_bf16_f32 v21, v12, v100
	v_cvt_pk_bf16_f32 v22, v122, v124
	v_cvt_pk_bf16_f32 v23, v125, v6
	s_waitcnt lgkmcnt(0)
; __device__ __forceinline__ unsigned cvt_pk_bf16(float lo, float hi) { const f32x2_cv v = {lo, hi}; return __builtin_bit_cast(unsigned, __builtin_convertvector(v, bf16x2_cv)); }
; #define LAS __attribute__((address_space(3)))
; __device__ __forceinline__ void attn_item(const bf16_t* Z, const float* ck, const float* cv, const float* btab, const float* sinks, bf16_t* MIX, int item, LAS unsigned char* lds, int tid, int wave, int lane) {
;     ...
; #pragma unroll
;     for (int db = 0; db < 8; ++db) {
;         f32x4 o0 = {0.f, 0.f, 0.f, 0.f}, o1 = {0.f, 0.f, 0.f, 0.f};
; #pragma unroll
;         for (int ks = 0; ks < 6; ++ks) { const LAS bf16_t* vp = VTs + (16 * db + c16) * VT_STRIDE + 32 * ks + 4 * g; const u32x2 lo = *(const LAS u32x2*)vp, hi = *(const LAS u32x2*)(vp + 16);
;             const bf16x8 Vf = __builtin_bit_cast(bf16x8, ((u32x4){lo.x, lo.y, hi.x, hi.y}));
;             o0 = __builtin_amdgcn_mfma_f32_16x16x32_bf16(Vf, Pf[0][ks], o0, 0, 0, 0);
;             o1 = __builtin_amdgcn_mfma_f32_16x16x32_bf16(Vf, Pf[1][ks], o1, 0, 0, 0); }
;         o0 = o0 * inv[0]; o1 = o1 * inv[1];
;         u32x2 w0, w1; w0.x = cvt_pk_bf16(o0[0], o0[1]); w0.y = cvt_pk_bf16(o0[2], o0[3]); w1.x = cvt_pk_bf16(o1[0], o1[1]); w1.y = cvt_pk_bf16(o1[2], o1[3]);
;         *(u32x2*)(MIX + (size_t)(qrow0 + qhalf * 32 + c16) * D + hq * 128 + 16 * db + 4 * g) = w0;
;         *(u32x2*)(MIX + (size_t)(qrow0 + qhalf * 32 + 16 + c16) * D + hq * 128 + 16 * db + 4 * g) = w1;
;     }
	v_mfma_f32_16x16x32_bf16 v[62:65], v[66:69], v[16:19], v[62:65]
	v_fma_f32 v3, -v1, v2, 1.0
	v_fmac_f32_e32 v2, v3, v2
	v_div_scale_f32 v3, vcc, 1.0, v0, 1.0
	v_mfma_f32_16x16x32_bf16 v[58:61], v[66:69], v[20:23], v[58:61]
	ds_read2_b64 v[66:69], v51 offset0:160 offset1:164
	v_mul_f32_e32 v8, v3, v2
	v_fma_f32 v9, -v1, v8, v3
	v_fmac_f32_e32 v8, v9, v2
	v_fma_f32 v1, -v1, v8, v3
	v_div_fmas_f32 v1, v1, v2, v8
	v_cvt_pk_bf16_f32 v8, v105, v106
	v_cvt_pk_bf16_f32 v9, v107, v108
	v_cvt_pk_bf16_f32 v10, v109, v110
	v_cvt_pk_bf16_f32 v11, v111, v112
	v_cvt_pk_bf16_f32 v12, v76, v74
	v_cvt_pk_bf16_f32 v13, v72, v7
	s_waitcnt lgkmcnt(0)
	v_mfma_f32_16x16x32_bf16 v[62:65], v[66:69], v[8:11], v[62:65]
	v_div_fixup_f32 v50, v1, v0, 1.0
	v_cvt_pk_bf16_f32 v0, v113, v114
	v_cvt_pk_bf16_f32 v1, v115, v116
	v_mfma_f32_16x16x32_bf16 v[58:61], v[66:69], v[12:15], v[58:61]
	ds_read2_b64 v[66:69], v51 offset0:168 offset1:172
	v_cvt_pk_bf16_f32 v2, v117, v118
	v_cvt_pk_bf16_f32 v3, v119, v123
	v_readlane_b32 s6, v236, 36
	v_readlane_b32 s7, v236, 54
	v_cvt_pk_bf16_f32 v6, v54, v52
	v_cvt_pk_bf16_f32 v7, v126, v127
	s_add_i32 s6, s7, s6
	s_waitcnt lgkmcnt(0)
	v_mfma_f32_16x16x32_bf16 v[62:65], v[66:69], v[0:3], v[62:65]
	v_add_u32_e32 v54, s6, v149
	v_lshlrev_b64 v[52:53], 12, v[54:55]
	v_add_u32_e32 v54, 16, v54
	v_mfma_f32_16x16x32_bf16 v[58:61], v[66:69], v[4:7], v[58:61]
	v_lshl_add_u64 v[52:53], s[70:71], 0, v[52:53]
	v_lshlrev_b64 v[54:55], 12, v[54:55]
	v_lshl_add_u64 v[52:53], v[52:53], 0, s[76:77]
	v_lshl_add_u64 v[54:55], s[70:71], 0, v[54:55]
	v_pk_mul_f32 v[64:65], v[48:49], v[64:65] op_sel_hi:[0,1]
	v_pk_mul_f32 v[62:63], v[48:49], v[62:63] op_sel_hi:[0,1]
	v_lshl_add_u64 v[52:53], v[52:53], 0, v[120:121]
	v_lshl_add_u64 v[54:55], v[54:55], 0, s[76:77]
	v_pk_mul_f32 v[60:61], v[60:61], v[50:51] op_sel_hi:[1,0]
	v_pk_mul_f32 v[58:59], v[58:59], v[50:51] op_sel_hi:[1,0]
	v_cvt_pk_bf16_f32 v62, v62, v63
	v_cvt_pk_bf16_f32 v63, v64, v65
	v_lshl_add_u64 v[54:55], v[54:55], 0, v[120:121]
	v_cvt_pk_bf16_f32 v58, v58, v59
	v_cvt_pk_bf16_f32 v59, v60, v61
	global_store_dwordx2 v[52:53], v[62:63], off
	global_store_dwordx2 v[54:55], v[58:59], off
	v_add_u32_e32 v51, 0xe000, v49
	ds_read2_b64 v[58:61], v51 offset0:144 offset1:148
	ds_read2_b64 v[66:69], v51 offset0:152 offset1:156
	s_waitcnt lgkmcnt(1)
	v_mfma_f32_16x16x32_bf16 v[62:65], v[58:61], v[40:43], 0
	v_mfma_f32_16x16x32_bf16 v[58:61], v[58:61], v[44:47], 0
	s_waitcnt lgkmcnt(0)
	v_mfma_f32_16x16x32_bf16 v[62:65], v[66:69], v[32:35], v[62:65]
	v_mfma_f32_16x16x32_bf16 v[58:61], v[66:69], v[36:39], v[58:61]
	ds_read2_b64 v[66:69], v51 offset0:160 offset1:164
	s_waitcnt lgkmcnt(0)
	v_mfma_f32_16x16x32_bf16 v[62:65], v[66:69], v[24:27], v[62:65]
	v_mfma_f32_16x16x32_bf16 v[58:61], v[66:69], v[28:31], v[58:61]
	ds_read2_b64 v[66:69], v51 offset0:168 offset1:172
	s_waitcnt lgkmcnt(0)
	v_mfma_f32_16x16x32_bf16 v[62:65], v[66:69], v[16:19], v[62:65]
	v_mfma_f32_16x16x32_bf16 v[58:61], v[66:69], v[20:23], v[58:61]
	ds_read2_b64 v[66:69], v51 offset0:176 offset1:180
	s_waitcnt lgkmcnt(0)
	v_mfma_f32_16x16x32_bf16 v[62:65], v[66:69], v[8:11], v[62:65]
	v_mfma_f32_16x16x32_bf16 v[58:61], v[66:69], v[12:15], v[58:61]
	ds_read2_b64 v[66:69], v51 offset0:184 offset1:188
	s_waitcnt lgkmcnt(0)
	v_mfma_f32_16x16x32_bf16 v[62:65], v[66:69], v[0:3], v[62:65]
	s_nop 7
	v_pk_mul_f32 v[64:65], v[48:49], v[64:65] op_sel_hi:[0,1]
	v_mfma_f32_16x16x32_bf16 v[58:61], v[66:69], v[4:7], v[58:61]
	v_mul_f32_e64 v62, v48, v62
	v_mul_f32_e64 v63, v48, v63
	v_cvt_pk_bf16_f32 v62, v62, v63
	v_cvt_pk_bf16_f32 v63, v64, v65
	v_add_u32_e32 v49, 0xf800, v49
	s_nop 2
	v_pk_mul_f32 v[60:61], v[60:61], v[50:51] op_sel_hi:[1,0]
	v_pk_mul_f32 v[58:59], v[58:59], v[50:51] op_sel_hi:[1,0]
	s_nop 0
	v_cvt_pk_bf16_f32 v58, v58, v59
	v_cvt_pk_bf16_f32 v59, v60, v61
	global_store_dwordx2 v[52:53], v[62:63], off offset:32
	global_store_dwordx2 v[54:55], v[58:59], off offset:32
	ds_read2_b64 v[58:61], v49 offset0:160 offset1:164
	ds_read2_b64 v[66:69], v49 offset0:168 offset1:172
	s_waitcnt lgkmcnt(1)
	v_mfma_f32_16x16x32_bf16 v[62:65], v[58:61], v[40:43], 0
	v_mfma_f32_16x16x32_bf16 v[58:61], v[58:61], v[44:47], 0
	s_waitcnt lgkmcnt(0)
	v_mfma_f32_16x16x32_bf16 v[62:65], v[66:69], v[32:35], v[62:65]
	v_mfma_f32_16x16x32_bf16 v[58:61], v[66:69], v[36:39], v[58:61]
	ds_read2_b64 v[66:69], v49 offset0:176 offset1:180
	s_waitcnt lgkmcnt(0)
	v_mfma_f32_16x16x32_bf16 v[62:65], v[66:69], v[24:27], v[62:65]
	v_mfma_f32_16x16x32_bf16 v[58:61], v[66:69], v[28:31], v[58:61]
	ds_read2_b64 v[66:69], v49 offset0:184 offset1:188
	s_waitcnt lgkmcnt(0)
	v_mfma_f32_16x16x32_bf16 v[62:65], v[66:69], v[16:19], v[62:65]
	v_mfma_f32_16x16x32_bf16 v[58:61], v[66:69], v[20:23], v[58:61]
	ds_read2_b64 v[66:69], v49 offset0:192 offset1:196
	s_waitcnt lgkmcnt(0)
	v_mfma_f32_16x16x32_bf16 v[62:65], v[66:69], v[8:11], v[62:65]
	v_mfma_f32_16x16x32_bf16 v[58:61], v[66:69], v[12:15], v[58:61]
	ds_read2_b64 v[66:69], v49 offset0:200 offset1:204
	s_waitcnt lgkmcnt(0)
	v_mfma_f32_16x16x32_bf16 v[62:65], v[66:69], v[0:3], v[62:65]
	s_nop 7
	v_pk_mul_f32 v[64:65], v[48:49], v[64:65] op_sel_hi:[0,1]
	v_mfma_f32_16x16x32_bf16 v[58:61], v[66:69], v[4:7], v[58:61]
	v_mul_f32_e64 v62, v48, v62
	v_mul_f32_e64 v63, v48, v63
	v_cvt_pk_bf16_f32 v62, v62, v63
	v_cvt_pk_bf16_f32 v63, v64, v65
	s_nop 3
	v_pk_mul_f32 v[60:61], v[50:51], v[60:61] op_sel_hi:[0,1]
	v_pk_mul_f32 v[58:59], v[50:51], v[58:59] op_sel_hi:[0,1]
	v_cvt_pk_bf16_f32 v58, v58, v59
	v_cvt_pk_bf16_f32 v59, v60, v61
	global_store_dwordx2 v[52:53], v[62:63], off offset:64
	global_store_dwordx2 v[54:55], v[58:59], off offset:64
	v_mad_u64_u32 v[58:59], s[6:7], v148, s8, v[56:57]
	v_add_u32_e32 v49, 0xc800, v58
	ds_read2_b64 v[58:61], v49 offset0:128 offset1:132
	ds_read2_b64 v[66:69], v49 offset0:136 offset1:140
	s_waitcnt lgkmcnt(1)
; __device__ __forceinline__ unsigned cvt_pk_bf16(float lo, float hi) { const f32x2_cv v = {lo, hi}; return __builtin_bit_cast(unsigned, __builtin_convertvector(v, bf16x2_cv)); }
; #define LAS __attribute__((address_space(3)))
; __device__ __forceinline__ void attn_item(const bf16_t* Z, const float* ck, const float* cv, const float* btab, const float* sinks, bf16_t* MIX, int item, LAS unsigned char* lds, int tid, int wave, int lane) {
;     ...
;     for (int db = 0; db < 8; ++db) {
;         f32x4 o0 = {0.f, 0.f, 0.f, 0.f}, o1 = {0.f, 0.f, 0.f, 0.f};
; #pragma unroll
;         for (int ks = 0; ks < 6; ++ks) { const LAS bf16_t* vp = VTs + (16 * db + c16) * VT_STRIDE + 32 * ks + 4 * g; const u32x2 lo = *(const LAS u32x2*)vp, hi = *(const LAS u32x2*)(vp + 16);
;             const bf16x8 Vf = __builtin_bit_cast(bf16x8, ((u32x4){lo.x, lo.y, hi.x, hi.y}));
;             o0 = __builtin_amdgcn_mfma_f32_16x16x32_bf16(Vf, Pf[0][ks], o0, 0, 0, 0);
;             o1 = __builtin_amdgcn_mfma_f32_16x16x32_bf16(Vf, Pf[1][ks], o1, 0, 0, 0); }
;         o0 = o0 * inv[0]; o1 = o1 * inv[1];
;         u32x2 w0, w1; w0.x = cvt_pk_bf16(o0[0], o0[1]); w0.y = cvt_pk_bf16(o0[2], o0[3]); w1.x = cvt_pk_bf16(o1[0], o1[1]); w1.y = cvt_pk_bf16(o1[2], o1[3]);
;         *(u32x2*)(MIX + (size_t)(qrow0 + qhalf * 32 + c16) * D + hq * 128 + 16 * db + 4 * g) = w0;
;         *(u32x2*)(MIX + (size_t)(qrow0 + qhalf * 32 + 16 + c16) * D + hq * 128 + 16 * db + 4 * g) = w1;
;     }
	v_mfma_f32_16x16x32_bf16 v[62:65], v[58:61], v[40:43], 0
	v_mfma_f32_16x16x32_bf16 v[58:61], v[58:61], v[44:47], 0
	s_waitcnt lgkmcnt(0)
	v_mfma_f32_16x16x32_bf16 v[62:65], v[66:69], v[32:35], v[62:65]
	v_mfma_f32_16x16x32_bf16 v[58:61], v[66:69], v[36:39], v[58:61]
	ds_read2_b64 v[66:69], v49 offset0:144 offset1:148
	s_waitcnt lgkmcnt(0)
	v_mfma_f32_16x16x32_bf16 v[62:65], v[66:69], v[24:27], v[62:65]
	v_mfma_f32_16x16x32_bf16 v[58:61], v[66:69], v[28:31], v[58:61]
	ds_read2_b64 v[66:69], v49 offset0:152 offset1:156
	s_waitcnt lgkmcnt(0)
	v_mfma_f32_16x16x32_bf16 v[62:65], v[66:69], v[16:19], v[62:65]
	v_mfma_f32_16x16x32_bf16 v[58:61], v[66:69], v[20:23], v[58:61]
	ds_read2_b64 v[66:69], v49 offset0:160 offset1:164
	s_waitcnt lgkmcnt(0)
	v_mfma_f32_16x16x32_bf16 v[62:65], v[66:69], v[8:11], v[62:65]
	v_mfma_f32_16x16x32_bf16 v[58:61], v[66:69], v[12:15], v[58:61]
	ds_read2_b64 v[66:69], v49 offset0:168 offset1:172
	s_waitcnt lgkmcnt(0)
	v_mfma_f32_16x16x32_bf16 v[62:65], v[66:69], v[0:3], v[62:65]
	s_nop 7
	v_pk_mul_f32 v[64:65], v[48:49], v[64:65] op_sel_hi:[0,1]
	v_mfma_f32_16x16x32_bf16 v[58:61], v[66:69], v[4:7], v[58:61]
	v_mul_f32_e64 v62, v48, v62
	v_mul_f32_e64 v63, v48, v63
	v_cvt_pk_bf16_f32 v62, v62, v63
	v_cvt_pk_bf16_f32 v63, v64, v65
	v_mad_u32_u24 v49, v147, s8, v56
	v_mad_u64_u32 v[56:57], s[6:7], v146, s8, v[56:57]
	s_nop 1
	v_pk_mul_f32 v[60:61], v[50:51], v[60:61] op_sel_hi:[0,1]
	v_pk_mul_f32 v[58:59], v[50:51], v[58:59] op_sel_hi:[0,1]
	v_cvt_pk_bf16_f32 v58, v58, v59
	v_cvt_pk_bf16_f32 v59, v60, v61
	global_store_dwordx2 v[52:53], v[62:63], off offset:96
	global_store_dwordx2 v[54:55], v[58:59], off offset:96
	v_add_u32_e32 v51, 0xc800, v49
	ds_read2_b64 v[58:61], v51 offset0:128 offset1:132
	ds_read2_b64 v[66:69], v51 offset0:136 offset1:140
	s_waitcnt lgkmcnt(1)
	v_mfma_f32_16x16x32_bf16 v[62:65], v[58:61], v[40:43], 0
	v_mfma_f32_16x16x32_bf16 v[58:61], v[58:61], v[44:47], 0
	s_waitcnt lgkmcnt(0)
	v_mfma_f32_16x16x32_bf16 v[62:65], v[66:69], v[32:35], v[62:65]
	v_mfma_f32_16x16x32_bf16 v[58:61], v[66:69], v[36:39], v[58:61]
	ds_read2_b64 v[66:69], v51 offset0:144 offset1:148
	s_waitcnt lgkmcnt(0)
	v_mfma_f32_16x16x32_bf16 v[62:65], v[66:69], v[24:27], v[62:65]
	v_mfma_f32_16x16x32_bf16 v[58:61], v[66:69], v[28:31], v[58:61]
	ds_read2_b64 v[66:69], v51 offset0:152 offset1:156
	s_waitcnt lgkmcnt(0)
	v_mfma_f32_16x16x32_bf16 v[62:65], v[66:69], v[16:19], v[62:65]
	v_mfma_f32_16x16x32_bf16 v[58:61], v[66:69], v[20:23], v[58:61]
	ds_read2_b64 v[66:69], v51 offset0:160 offset1:164
	s_waitcnt lgkmcnt(0)
	v_mfma_f32_16x16x32_bf16 v[62:65], v[66:69], v[8:11], v[62:65]
	v_mfma_f32_16x16x32_bf16 v[58:61], v[66:69], v[12:15], v[58:61]
	ds_read2_b64 v[66:69], v51 offset0:168 offset1:172
	s_waitcnt lgkmcnt(0)
	v_mfma_f32_16x16x32_bf16 v[62:65], v[66:69], v[0:3], v[62:65]
	s_nop 7
	v_pk_mul_f32 v[64:65], v[48:49], v[64:65] op_sel_hi:[0,1]
	v_mfma_f32_16x16x32_bf16 v[58:61], v[66:69], v[4:7], v[58:61]
	v_mul_f32_e64 v62, v48, v62
	v_mul_f32_e64 v63, v48, v63
	v_cvt_pk_bf16_f32 v62, v62, v63
	v_cvt_pk_bf16_f32 v63, v64, v65
	s_nop 3
	v_pk_mul_f32 v[60:61], v[50:51], v[60:61] op_sel_hi:[0,1]
	v_pk_mul_f32 v[58:59], v[50:51], v[58:59] op_sel_hi:[0,1]
	v_cvt_pk_bf16_f32 v58, v58, v59
	v_cvt_pk_bf16_f32 v59, v60, v61
	global_store_dwordx2 v[52:53], v[62:63], off offset:128
	global_store_dwordx2 v[54:55], v[58:59], off offset:128
	v_add_u32_e32 v51, 0xe000, v49
	ds_read2_b64 v[58:61], v51 offset0:144 offset1:148
	ds_read2_b64 v[66:69], v51 offset0:152 offset1:156
	s_waitcnt lgkmcnt(1)
	v_mfma_f32_16x16x32_bf16 v[62:65], v[58:61], v[40:43], 0
	v_mfma_f32_16x16x32_bf16 v[58:61], v[58:61], v[44:47], 0
	s_waitcnt lgkmcnt(0)
	v_mfma_f32_16x16x32_bf16 v[62:65], v[66:69], v[32:35], v[62:65]
	v_mfma_f32_16x16x32_bf16 v[58:61], v[66:69], v[36:39], v[58:61]
	ds_read2_b64 v[66:69], v51 offset0:160 offset1:164
	s_waitcnt lgkmcnt(0)
	v_mfma_f32_16x16x32_bf16 v[62:65], v[66:69], v[24:27], v[62:65]
	v_mfma_f32_16x16x32_bf16 v[58:61], v[66:69], v[28:31], v[58:61]
	ds_read2_b64 v[66:69], v51 offset0:168 offset1:172
	s_waitcnt lgkmcnt(0)
	v_mfma_f32_16x16x32_bf16 v[62:65], v[66:69], v[16:19], v[62:65]
	v_mfma_f32_16x16x32_bf16 v[58:61], v[66:69], v[20:23], v[58:61]
	ds_read2_b64 v[66:69], v51 offset0:176 offset1:180
	s_waitcnt lgkmcnt(0)
; __device__ __forceinline__ unsigned cvt_pk_bf16(float lo, float hi) { const f32x2_cv v = {lo, hi}; return __builtin_bit_cast(unsigned, __builtin_convertvector(v, bf16x2_cv)); }
; #define LAS __attribute__((address_space(3)))
; __device__ __forceinline__ void attn_item(const bf16_t* Z, const float* ck, const float* cv, const float* btab, const float* sinks, bf16_t* MIX, int item, LAS unsigned char* lds, int tid, int wave, int lane) {
;     ...
;     for (int db = 0; db < 8; ++db) {
;         f32x4 o0 = {0.f, 0.f, 0.f, 0.f}, o1 = {0.f, 0.f, 0.f, 0.f};
; #pragma unroll
;         for (int ks = 0; ks < 6; ++ks) { const LAS bf16_t* vp = VTs + (16 * db + c16) * VT_STRIDE + 32 * ks + 4 * g; const u32x2 lo = *(const LAS u32x2*)vp, hi = *(const LAS u32x2*)(vp + 16);
;             const bf16x8 Vf = __builtin_bit_cast(bf16x8, ((u32x4){lo.x, lo.y, hi.x, hi.y}));
;             o0 = __builtin_amdgcn_mfma_f32_16x16x32_bf16(Vf, Pf[0][ks], o0, 0, 0, 0);
;             o1 = __builtin_amdgcn_mfma_f32_16x16x32_bf16(Vf, Pf[1][ks], o1, 0, 0, 0); }
;         o0 = o0 * inv[0]; o1 = o1 * inv[1];
;         u32x2 w0, w1; w0.x = cvt_pk_bf16(o0[0], o0[1]); w0.y = cvt_pk_bf16(o0[2], o0[3]); w1.x = cvt_pk_bf16(o1[0], o1[1]); w1.y = cvt_pk_bf16(o1[2], o1[3]);
;         *(u32x2*)(MIX + (size_t)(qrow0 + qhalf * 32 + c16) * D + hq * 128 + 16 * db + 4 * g) = w0;
;         *(u32x2*)(MIX + (size_t)(qrow0 + qhalf * 32 + 16 + c16) * D + hq * 128 + 16 * db + 4 * g) = w1;
;     }
;     __syncthreads();
	v_mfma_f32_16x16x32_bf16 v[62:65], v[66:69], v[8:11], v[62:65]
	v_mfma_f32_16x16x32_bf16 v[58:61], v[66:69], v[12:15], v[58:61]
	ds_read2_b64 v[66:69], v51 offset0:184 offset1:188
	s_waitcnt lgkmcnt(0)
	v_mfma_f32_16x16x32_bf16 v[62:65], v[66:69], v[0:3], v[62:65]
	s_nop 7
	v_pk_mul_f32 v[64:65], v[48:49], v[64:65] op_sel_hi:[0,1]
	v_mfma_f32_16x16x32_bf16 v[58:61], v[66:69], v[4:7], v[58:61]
	v_mul_f32_e64 v62, v48, v62
	v_mul_f32_e64 v63, v48, v63
	v_cvt_pk_bf16_f32 v62, v62, v63
	v_cvt_pk_bf16_f32 v63, v64, v65
	v_add_u32_e32 v49, 0xf800, v49
	s_nop 2
	v_pk_mul_f32 v[60:61], v[50:51], v[60:61] op_sel_hi:[0,1]
	v_pk_mul_f32 v[58:59], v[50:51], v[58:59] op_sel_hi:[0,1]
	v_cvt_pk_bf16_f32 v58, v58, v59
	v_cvt_pk_bf16_f32 v59, v60, v61
	global_store_dwordx2 v[52:53], v[62:63], off offset:160
	global_store_dwordx2 v[54:55], v[58:59], off offset:160
	ds_read2_b64 v[58:61], v49 offset0:160 offset1:164
	ds_read2_b64 v[66:69], v49 offset0:168 offset1:172
	s_waitcnt lgkmcnt(1)
	v_mfma_f32_16x16x32_bf16 v[62:65], v[58:61], v[40:43], 0
	v_mfma_f32_16x16x32_bf16 v[58:61], v[58:61], v[44:47], 0
	s_waitcnt lgkmcnt(0)
	v_mfma_f32_16x16x32_bf16 v[62:65], v[66:69], v[32:35], v[62:65]
	v_mfma_f32_16x16x32_bf16 v[58:61], v[66:69], v[36:39], v[58:61]
	ds_read2_b64 v[66:69], v49 offset0:176 offset1:180
	s_waitcnt lgkmcnt(0)
	v_mfma_f32_16x16x32_bf16 v[62:65], v[66:69], v[24:27], v[62:65]
	v_mfma_f32_16x16x32_bf16 v[58:61], v[66:69], v[28:31], v[58:61]
	ds_read2_b64 v[66:69], v49 offset0:184 offset1:188
	s_waitcnt lgkmcnt(0)
	v_mfma_f32_16x16x32_bf16 v[62:65], v[66:69], v[16:19], v[62:65]
	v_mfma_f32_16x16x32_bf16 v[58:61], v[66:69], v[20:23], v[58:61]
	ds_read2_b64 v[66:69], v49 offset0:192 offset1:196
	s_waitcnt lgkmcnt(0)
	v_mfma_f32_16x16x32_bf16 v[62:65], v[66:69], v[8:11], v[62:65]
	v_mfma_f32_16x16x32_bf16 v[58:61], v[66:69], v[12:15], v[58:61]
	ds_read2_b64 v[66:69], v49 offset0:200 offset1:204
	s_waitcnt lgkmcnt(0)
	v_mfma_f32_16x16x32_bf16 v[62:65], v[66:69], v[0:3], v[62:65]
	s_nop 7
	v_pk_mul_f32 v[64:65], v[48:49], v[64:65] op_sel_hi:[0,1]
	v_mfma_f32_16x16x32_bf16 v[58:61], v[66:69], v[4:7], v[58:61]
	v_mul_f32_e64 v62, v48, v62
	v_mul_f32_e64 v63, v48, v63
	v_cvt_pk_bf16_f32 v62, v62, v63
	v_cvt_pk_bf16_f32 v63, v64, v65
	v_add_u32_e32 v49, 0xc800, v56
	s_nop 2
	v_pk_mul_f32 v[60:61], v[50:51], v[60:61] op_sel_hi:[0,1]
	v_pk_mul_f32 v[58:59], v[50:51], v[58:59] op_sel_hi:[0,1]
	v_cvt_pk_bf16_f32 v58, v58, v59
	v_cvt_pk_bf16_f32 v59, v60, v61
	global_store_dwordx2 v[52:53], v[62:63], off offset:192
	global_store_dwordx2 v[54:55], v[58:59], off offset:192
	ds_read2_b64 v[56:59], v49 offset0:128 offset1:132
	s_waitcnt lgkmcnt(0)
	v_mfma_f32_16x16x32_bf16 v[40:43], v[56:59], v[40:43], 0
	v_mfma_f32_16x16x32_bf16 v[44:47], v[56:59], v[44:47], 0
	ds_read2_b64 v[56:59], v49 offset0:136 offset1:140
	s_waitcnt lgkmcnt(0)
	v_mfma_f32_16x16x32_bf16 v[32:35], v[56:59], v[32:35], v[40:43]
	s_nop 3
	ds_read2_b64 v[40:43], v49 offset0:144 offset1:148
	s_waitcnt lgkmcnt(0)
	v_mfma_f32_16x16x32_bf16 v[24:27], v[40:43], v[24:27], v[32:35]
	s_nop 2
	ds_read2_b64 v[32:35], v49 offset0:152 offset1:156
	s_waitcnt lgkmcnt(0)
	v_mfma_f32_16x16x32_bf16 v[16:19], v[32:35], v[16:19], v[24:27]
	s_nop 2
	ds_read2_b64 v[24:27], v49 offset0:160 offset1:164
	v_mfma_f32_16x16x32_bf16 v[36:39], v[56:59], v[36:39], v[44:47]
	v_mfma_f32_16x16x32_bf16 v[28:31], v[40:43], v[28:31], v[36:39]
	s_waitcnt lgkmcnt(0)
	v_mfma_f32_16x16x32_bf16 v[8:11], v[24:27], v[8:11], v[16:19]
	s_nop 2
	ds_read2_b64 v[16:19], v49 offset0:168 offset1:172
	v_mfma_f32_16x16x32_bf16 v[20:23], v[32:35], v[20:23], v[28:31]
	v_mfma_f32_16x16x32_bf16 v[12:15], v[24:27], v[12:15], v[20:23]
	s_waitcnt lgkmcnt(0)
	v_mfma_f32_16x16x32_bf16 v[0:3], v[16:19], v[0:3], v[8:11]
	v_mfma_f32_16x16x32_bf16 v[4:7], v[16:19], v[4:7], v[12:15]
	s_nop 6
	v_mul_f32_e64 v2, v48, v2
	v_mul_f32_e64 v3, v48, v3
	v_pk_mul_f32 v[0:1], v[48:49], v[0:1] op_sel_hi:[0,1]
	v_pk_mul_f32 v[6:7], v[50:51], v[6:7] op_sel_hi:[0,1]
	v_pk_mul_f32 v[4:5], v[50:51], v[4:5] op_sel_hi:[0,1]
	v_cvt_pk_bf16_f32 v0, v0, v1
	v_cvt_pk_bf16_f32 v1, v2, v3
	v_cvt_pk_bf16_f32 v2, v4, v5
	v_cvt_pk_bf16_f32 v3, v6, v7
	global_store_dwordx2 v[52:53], v[0:1], off offset:224
	global_store_dwordx2 v[54:55], v[2:3], off offset:224
	s_barrier
	s_cbranch_execnz .LBB0_504
	s_branch .LBB0_595
.LBB0_650:
	v_lshlrev_b32_e32 v0, 2, v32
	global_load_dword v0, v0, s[8:9]
	s_and_b64 vcc, exec, s[6:7]
	s_cbranch_vccnz .LBB0_515

; __global__ void __launch_bounds__(NTHR, 2) hybrid_fwd(Args args) {
	.amdhsa_kernel _Z10hybrid_fwd4Args
		.amdhsa_group_segment_fixed_size 0
		.amdhsa_private_segment_fixed_size 0
		.amdhsa_kernarg_size 512
		.amdhsa_user_sgpr_count 2
		.amdhsa_user_sgpr_dispatch_ptr 0
		.amdhsa_user_sgpr_queue_ptr 0
		.amdhsa_user_sgpr_kernarg_segment_ptr 1
		.amdhsa_user_sgpr_dispatch_id 0
		.amdhsa_user_sgpr_kernarg_preload_length 0
		.amdhsa_user_sgpr_kernarg_preload_offset 0
		.amdhsa_user_sgpr_private_segment_size 0
		.amdhsa_uses_dynamic_stack 0
		.amdhsa_enable_private_segment 0
		.amdhsa_system_sgpr_workgroup_id_x 1
		.amdhsa_system_sgpr_workgroup_id_y 0
		.amdhsa_system_sgpr_workgroup_id_z 0
		.amdhsa_system_sgpr_workgroup_info 0
		.amdhsa_system_vgpr_workitem_id 2
		.amdhsa_next_free_vgpr 237
		.amdhsa_next_free_sgpr 102
		.amdhsa_accum_offset 240
		.amdhsa_reserve_vcc 1
		.amdhsa_float_round_mode_32 0
		.amdhsa_float_round_mode_16_64 0
		.amdhsa_float_denorm_mode_32 3
		.amdhsa_float_denorm_mode_16_64 3
		.amdhsa_dx10_clamp 1
		.amdhsa_ieee_mode 1
		.amdhsa_fp16_overflow 0
		.amdhsa_tg_split 0
		.amdhsa_exception_fp_ieee_invalid_op 0
		.amdhsa_exception_fp_denorm_src 0
		.amdhsa_exception_fp_ieee_div_zero 0
		.amdhsa_exception_fp_ieee_overflow 0
		.amdhsa_exception_fp_ieee_underflow 0
		.amdhsa_exception_fp_ieee_inexact 0
		.amdhsa_exception_int_div_zero 0
	.end_amdhsa_kernel

; __global__ void __launch_bounds__(NTHR, 2) hybrid_fwd(Args args) {
amdhsa.kernels:
  - .agpr_count:     0
    .args:
      - .offset:         0
        .size:           256
        .value_kind:     by_value
      - .offset:         256
        .size:           4
        .value_kind:     hidden_block_count_x
      - .offset:         260
        .size:           4
        .value_kind:     hidden_block_count_y
      - .offset:         264
        .size:           4
        .value_kind:     hidden_block_count_z
      - .offset:         268
        .size:           2
        .value_kind:     hidden_group_size_x
      - .offset:         270
        .size:           2
        .value_kind:     hidden_group_size_y
      - .offset:         272
        .size:           2
        .value_kind:     hidden_group_size_z
      - .offset:         274
        .size:           2
        .value_kind:     hidden_remainder_x
      - .offset:         276
        .size:           2
        .value_kind:     hidden_remainder_y
      - .offset:         278
        .size:           2
        .value_kind:     hidden_remainder_z
      - .offset:         296
        .size:           8
        .value_kind:     hidden_global_offset_x
      - .offset:         304
        .size:           8
        .value_kind:     hidden_global_offset_y
      - .offset:         312
        .size:           8
        .value_kind:     hidden_global_offset_z
      - .offset:         320
        .size:           2
        .value_kind:     hidden_grid_dims
      - .offset:         344
        .size:           8
        .value_kind:     hidden_multigrid_sync_arg
      - .offset:         376
        .size:           4
        .value_kind:     hidden_dynamic_lds_size
    .group_segment_fixed_size: 0
    .kernarg_segment_align: 8
    .kernarg_segment_size: 512
    .language:       OpenCL C
    .language_version:
      - 2
      - 0
    .max_flat_workgroup_size: 512
    .name:           _Z10hybrid_fwd4Args
    .private_segment_fixed_size: 0
    .sgpr_count:     108
    .sgpr_spill_count: 59
    .symbol:         _Z10hybrid_fwd4Args.kd
    .uniform_work_group_size: 1
    .uses_dynamic_stack: false
    .vgpr_count:     237
    .vgpr_spill_count: 0
    .wavefront_size: 64
